# FoX: V-tile DMA issued in softmax half, K/bias in MFMA half, first LDS reads of next MFMA half prefetched across barrier; write-through sc1 stores in phases 1-2 to shorten the seam L2 writeback
# speedup vs baseline: 1.0727x; 1.0116x over previous
.LBB0_127:
	s_or_b64 exec, exec, s[12:13]
	ds_write2_b32 v84, v48, v49 offset1:1
	ds_write2_b32 v84, v50, v51 offset0:2 offset1:3
	v_add_u32_e32 v48, 0x420, v84
	ds_write2_b32 v48, v32, v33 offset1:1
	v_add_u32_e32 v32, 0x428, v84
	ds_write2_b32 v32, v34, v35 offset1:1
	v_add_u32_e32 v32, 0x840, v84
	ds_write2_b32 v32, v52, v53 offset1:1
	v_add_u32_e32 v32, 0x848, v84
	ds_write2_b32 v32, v54, v55 offset1:1
	v_add_u32_e32 v32, 0xc60, v84
	ds_write2_b32 v32, v36, v37 offset1:1
	v_add_u32_e32 v32, 0xc68, v84
	ds_write2_b32 v32, v38, v39 offset1:1
	v_add_u32_e32 v32, 0x1080, v84
	ds_write2_b32 v32, v56, v57 offset1:1
	v_add_u32_e32 v32, 0x1088, v84
	ds_write2_b32 v32, v58, v59 offset1:1
	v_add_u32_e32 v32, 0x14a0, v84
	ds_write2_b32 v32, v40, v41 offset1:1
	v_add_u32_e32 v32, 0x14a8, v84
	ds_write2_b32 v32, v42, v43 offset1:1
	v_add_u32_e32 v32, 0x18c0, v84
	ds_write2_b32 v32, v60, v61 offset1:1
	v_add_u32_e32 v32, 0x18c8, v84
	ds_write2_b32 v32, v62, v63 offset1:1
	v_add_u32_e32 v32, 0x1ce0, v84
	ds_write2_b32 v32, v44, v45 offset1:1
	v_add_u32_e32 v32, 0x1ce8, v84
	ds_write2_b32 v32, v46, v47 offset1:1
	s_waitcnt lgkmcnt(0)
	s_and_b64 s[0:1], exec, vcc
	v_add_u32_e32 v34, v70, v79
	s_or_b64 s[10:11], s[0:1], s[10:11]
	v_cmp_ne_u32_e32 vcc, 0, v65
	v_ashrrev_i32_e32 v65, 31, v64
	v_ashrrev_i32_e32 v33, 31, v34
	s_and_saveexec_b64 s[0:1], vcc
	s_xor_b64 s[0:1], exec, s[0:1]
	s_cbranch_execz .LBB0_129
	ds_read2_b32 v[36:37], v83 offset1:33
	ds_read2_b32 v[40:41], v83 offset0:66 offset1:99
	ds_read2_b32 v[42:43], v83 offset0:132 offset1:165
	v_mov_b32_e32 v38, v69
	v_mov_b32_e32 v39, v69
	s_waitcnt lgkmcnt(2)
	v_mul_f32_e32 v32, 0x42800000, v36
	v_mul_f32_e32 v35, 0x42800000, v37
	ds_read2_b32 v[36:37], v83 offset0:198 offset1:231
	v_cvt_pk_fp8_f32 v38, v32, v35
	s_waitcnt lgkmcnt(2)
	v_mul_f32_e32 v32, 0x42800000, v40
	v_mul_f32_e32 v35, 0x42800000, v41
	s_waitcnt lgkmcnt(1)
	v_mul_f32_e32 v40, 0x42800000, v42
	v_mul_f32_e32 v41, 0x42800000, v43
	v_cvt_pk_fp8_f32 v39, v40, v41
	v_cvt_pk_fp8_f32 v38, v32, v35 op_sel:[0,0,1]
	s_waitcnt lgkmcnt(0)
	v_mul_f32_e32 v32, 0x42800000, v36
	v_mul_f32_e32 v35, 0x42800000, v37
	v_cvt_pk_fp8_f32 v39, v32, v35 op_sel:[0,0,1]
	v_mad_u64_u32 v[34:35], s[12:13], v34, v78, v[66:67]
	v_mov_b32_e32 v32, v35
	v_mad_u64_u32 v[32:33], s[12:13], v33, v78, v[32:33]
	v_mov_b32_e32 v35, v32
	v_lshl_add_u64 v[32:33], v[34:35], 0, v[64:65]
	v_lshl_add_u64 v[32:33], v[32:33], 0, v[72:73]
	global_store_dwordx2 v[32:33], v[38:39], off sc1
.LBB0_129:
	s_or_saveexec_b64 s[0:1], s[0:1]
	v_lshlrev_b32_e32 v32, 1, v72
	s_xor_b64 exec, exec, s[0:1]
	s_cbranch_execz .LBB0_131
	ds_read2_b32 v[36:37], v83 offset1:33
	ds_read2_b32 v[38:39], v83 offset0:66 offset1:99
	ds_read2_b32 v[42:43], v83 offset0:198 offset1:231
	s_waitcnt lgkmcnt(2)
	v_bfe_u32 v35, v36, 16, 1
	v_bfe_u32 v40, v37, 16, 1
	v_add3_u32 v35, v36, v35, s63
	s_waitcnt lgkmcnt(1)
	v_bfe_u32 v41, v38, 16, 1
	v_add3_u32 v36, v37, v40, s63
	v_lshrrev_b32_e32 v35, 16, v35
	v_and_or_b32 v36, v36, s64, v35
	v_add3_u32 v35, v38, v41, s63
	ds_read2_b32 v[40:41], v83 offset0:132 offset1:165
	v_bfe_u32 v37, v39, 16, 1
	v_lshrrev_b32_e32 v35, 16, v35
	v_add3_u32 v37, v39, v37, s63
	v_and_or_b32 v37, v37, s64, v35
	s_waitcnt lgkmcnt(0)
	v_bfe_u32 v35, v40, 16, 1
	v_add3_u32 v35, v40, v35, s63
	v_bfe_u32 v38, v41, 16, 1
	v_lshrrev_b32_e32 v35, 16, v35
	v_add3_u32 v38, v41, v38, s63
	v_and_or_b32 v38, v38, s64, v35
	v_bfe_u32 v35, v42, 16, 1
	v_add3_u32 v35, v42, v35, s63
	v_bfe_u32 v39, v43, 16, 1
	v_lshrrev_b32_e32 v35, 16, v35
	v_add3_u32 v39, v43, v39, s63
	v_and_or_b32 v39, v39, s64, v35
	v_mad_u64_u32 v[34:35], s[12:13], v34, v78, 0
	v_mov_b32_e32 v40, v35
	v_mad_u64_u32 v[40:41], s[12:13], v33, v78, v[40:41]
	v_mov_b32_e32 v35, v40
	v_lshl_add_u64 v[34:35], v[34:35], 1, v[66:67]
	v_lshl_add_u64 v[34:35], v[64:65], 1, v[34:35]
	v_mov_b32_e32 v33, v69
	v_lshl_add_u64 v[34:35], v[34:35], 0, v[32:33]
	global_store_dwordx4 v[34:35], v[36:39], off sc1
.LBB0_131:
	s_or_b64 exec, exec, s[0:1]
	v_add_u32_e32 v34, v70, v80
	v_ashrrev_i32_e32 v33, 31, v34
	s_and_saveexec_b64 s[0:1], vcc
	s_xor_b64 s[0:1], exec, s[0:1]
	s_cbranch_execz .LBB0_133
	ds_read2_b32 v[36:37], v83 offset0:8 offset1:41
	ds_read2_b32 v[40:41], v83 offset0:74 offset1:107
	ds_read2_b32 v[42:43], v83 offset0:140 offset1:173
	v_mov_b32_e32 v38, v69
	v_mov_b32_e32 v39, v69
	s_waitcnt lgkmcnt(2)
	v_mul_f32_e32 v35, 0x42800000, v36
	v_mul_f32_e32 v36, 0x42800000, v37
	v_cvt_pk_fp8_f32 v38, v35, v36
	ds_read2_b32 v[36:37], v83 offset0:206 offset1:239
	s_waitcnt lgkmcnt(2)
	v_mul_f32_e32 v35, 0x42800000, v40
	v_mul_f32_e32 v40, 0x42800000, v41
	s_waitcnt lgkmcnt(1)
	v_mul_f32_e32 v41, 0x42800000, v42
	v_mul_f32_e32 v42, 0x42800000, v43
	v_cvt_pk_fp8_f32 v39, v41, v42
	v_cvt_pk_fp8_f32 v38, v35, v40 op_sel:[0,0,1]
	s_waitcnt lgkmcnt(0)
	v_mul_f32_e32 v35, 0x42800000, v36
	v_mul_f32_e32 v36, 0x42800000, v37
	v_cvt_pk_fp8_f32 v39, v35, v36 op_sel:[0,0,1]
	v_mad_u64_u32 v[34:35], s[12:13], v34, v78, v[66:67]
	v_mov_b32_e32 v36, v35
	v_mad_u64_u32 v[36:37], s[12:13], v33, v78, v[36:37]
	v_mov_b32_e32 v35, v36
	v_lshl_add_u64 v[34:35], v[34:35], 0, v[64:65]
	v_lshl_add_u64 v[34:35], v[34:35], 0, v[72:73]
	global_store_dwordx2 v[34:35], v[38:39], off sc1
.LBB0_133:
	s_andn2_saveexec_b64 s[0:1], s[0:1]
	s_cbranch_execz .LBB0_135
	ds_read2_b32 v[36:37], v83 offset0:8 offset1:41
	ds_read2_b32 v[38:39], v83 offset0:74 offset1:107
	ds_read2_b32 v[42:43], v83 offset0:206 offset1:239
	s_waitcnt lgkmcnt(2)
	v_bfe_u32 v35, v36, 16, 1
	v_bfe_u32 v40, v37, 16, 1
	v_add3_u32 v35, v36, v35, s63
	s_waitcnt lgkmcnt(1)
	v_bfe_u32 v41, v38, 16, 1
	v_add3_u32 v36, v37, v40, s63
	v_lshrrev_b32_e32 v35, 16, v35
	v_and_or_b32 v36, v36, s64, v35
	v_add3_u32 v35, v38, v41, s63
	ds_read2_b32 v[40:41], v83 offset0:140 offset1:173
	v_bfe_u32 v37, v39, 16, 1
	v_lshrrev_b32_e32 v35, 16, v35
	v_add3_u32 v37, v39, v37, s63
	v_and_or_b32 v37, v37, s64, v35
	s_waitcnt lgkmcnt(0)
	v_bfe_u32 v35, v40, 16, 1
	v_add3_u32 v35, v40, v35, s63
	v_bfe_u32 v38, v41, 16, 1
	v_lshrrev_b32_e32 v35, 16, v35
	v_add3_u32 v38, v41, v38, s63
	v_and_or_b32 v38, v38, s64, v35
	v_bfe_u32 v35, v42, 16, 1
	v_add3_u32 v35, v42, v35, s63
	v_bfe_u32 v39, v43, 16, 1
	v_lshrrev_b32_e32 v35, 16, v35
	v_add3_u32 v39, v43, v39, s63
	v_and_or_b32 v39, v39, s64, v35
	v_mad_u64_u32 v[34:35], s[12:13], v34, v78, 0
	v_mov_b32_e32 v40, v35
	v_mad_u64_u32 v[40:41], s[12:13], v33, v78, v[40:41]
	v_mov_b32_e32 v35, v40
	v_lshl_add_u64 v[34:35], v[34:35], 1, v[66:67]
	v_lshl_add_u64 v[34:35], v[64:65], 1, v[34:35]
	v_mov_b32_e32 v33, v69
	v_lshl_add_u64 v[34:35], v[34:35], 0, v[32:33]
	global_store_dwordx4 v[34:35], v[36:39], off sc1
.LBB0_135:
	s_or_b64 exec, exec, s[0:1]
	v_add_u32_e32 v34, v70, v81
	v_ashrrev_i32_e32 v33, 31, v34
	s_and_saveexec_b64 s[0:1], vcc
	s_xor_b64 s[0:1], exec, s[0:1]
	s_cbranch_execz .LBB0_137
	ds_read2_b32 v[36:37], v83 offset0:16 offset1:49
	ds_read2_b32 v[40:41], v83 offset0:82 offset1:115
	ds_read2_b32 v[42:43], v83 offset0:148 offset1:181
	v_mov_b32_e32 v38, v69
	v_mov_b32_e32 v39, v69
	s_waitcnt lgkmcnt(2)
	v_mul_f32_e32 v35, 0x42800000, v36
	v_mul_f32_e32 v36, 0x42800000, v37
	v_cvt_pk_fp8_f32 v38, v35, v36
	ds_read2_b32 v[36:37], v83 offset0:214 offset1:247
	s_waitcnt lgkmcnt(2)
	v_mul_f32_e32 v35, 0x42800000, v40
	v_mul_f32_e32 v40, 0x42800000, v41
	s_waitcnt lgkmcnt(1)
	v_mul_f32_e32 v41, 0x42800000, v42
	v_mul_f32_e32 v42, 0x42800000, v43
	v_cvt_pk_fp8_f32 v39, v41, v42
	v_cvt_pk_fp8_f32 v38, v35, v40 op_sel:[0,0,1]
	s_waitcnt lgkmcnt(0)
	v_mul_f32_e32 v35, 0x42800000, v36
	v_mul_f32_e32 v36, 0x42800000, v37
	v_cvt_pk_fp8_f32 v39, v35, v36 op_sel:[0,0,1]
	v_mad_u64_u32 v[34:35], s[12:13], v34, v78, v[66:67]
	v_mov_b32_e32 v36, v35
	v_mad_u64_u32 v[36:37], s[12:13], v33, v78, v[36:37]
	v_mov_b32_e32 v35, v36
	v_lshl_add_u64 v[34:35], v[34:35], 0, v[64:65]
	v_lshl_add_u64 v[34:35], v[34:35], 0, v[72:73]
	global_store_dwordx2 v[34:35], v[38:39], off sc1
.LBB0_137:
	s_andn2_saveexec_b64 s[0:1], s[0:1]
	s_cbranch_execz .LBB0_139
	ds_read2_b32 v[36:37], v83 offset0:16 offset1:49
	ds_read2_b32 v[38:39], v83 offset0:82 offset1:115
	ds_read2_b32 v[42:43], v83 offset0:214 offset1:247
	s_waitcnt lgkmcnt(2)
	v_bfe_u32 v35, v36, 16, 1
	v_bfe_u32 v40, v37, 16, 1
	v_add3_u32 v35, v36, v35, s63
	s_waitcnt lgkmcnt(1)
	v_bfe_u32 v41, v38, 16, 1
	v_add3_u32 v36, v37, v40, s63
	v_lshrrev_b32_e32 v35, 16, v35
	v_and_or_b32 v36, v36, s64, v35
	v_add3_u32 v35, v38, v41, s63
	ds_read2_b32 v[40:41], v83 offset0:148 offset1:181
	v_bfe_u32 v37, v39, 16, 1
	v_lshrrev_b32_e32 v35, 16, v35
	v_add3_u32 v37, v39, v37, s63
	v_and_or_b32 v37, v37, s64, v35
	s_waitcnt lgkmcnt(0)
	v_bfe_u32 v35, v40, 16, 1
	v_add3_u32 v35, v40, v35, s63
	v_bfe_u32 v38, v41, 16, 1
	v_lshrrev_b32_e32 v35, 16, v35
	v_add3_u32 v38, v41, v38, s63
	v_and_or_b32 v38, v38, s64, v35
	v_bfe_u32 v35, v42, 16, 1
	v_add3_u32 v35, v42, v35, s63
	v_bfe_u32 v39, v43, 16, 1
	v_lshrrev_b32_e32 v35, 16, v35
	v_add3_u32 v39, v43, v39, s63
	v_and_or_b32 v39, v39, s64, v35
	v_mad_u64_u32 v[34:35], s[12:13], v34, v78, 0
	v_mov_b32_e32 v40, v35
	v_mad_u64_u32 v[40:41], s[12:13], v33, v78, v[40:41]
	v_mov_b32_e32 v35, v40
	v_lshl_add_u64 v[34:35], v[34:35], 1, v[66:67]
	v_lshl_add_u64 v[34:35], v[64:65], 1, v[34:35]
	v_mov_b32_e32 v33, v69
	v_lshl_add_u64 v[34:35], v[34:35], 0, v[32:33]
	global_store_dwordx4 v[34:35], v[36:39], off sc1
.LBB0_139:
	s_or_b64 exec, exec, s[0:1]
	v_add_u32_e32 v34, v70, v82
	v_ashrrev_i32_e32 v33, 31, v34
	s_and_saveexec_b64 s[0:1], vcc
	s_xor_b64 s[0:1], exec, s[0:1]
	s_cbranch_execz .LBB0_141
	ds_read2_b32 v[36:37], v83 offset0:24 offset1:57
	ds_read2_b32 v[40:41], v83 offset0:90 offset1:123
	ds_read2_b32 v[42:43], v83 offset0:156 offset1:189
	v_mov_b32_e32 v38, v69
	v_mov_b32_e32 v39, v69
	s_waitcnt lgkmcnt(2)
	v_mul_f32_e32 v32, 0x42800000, v36
	v_mul_f32_e32 v35, 0x42800000, v37
	ds_read2_b32 v[36:37], v83 offset0:222 offset1:255
	v_cvt_pk_fp8_f32 v38, v32, v35
	s_waitcnt lgkmcnt(2)
	v_mul_f32_e32 v32, 0x42800000, v40
	v_mul_f32_e32 v35, 0x42800000, v41
	s_waitcnt lgkmcnt(1)
	v_mul_f32_e32 v40, 0x42800000, v42
	v_mul_f32_e32 v41, 0x42800000, v43
	v_cvt_pk_fp8_f32 v39, v40, v41
	v_cvt_pk_fp8_f32 v38, v32, v35 op_sel:[0,0,1]
	s_waitcnt lgkmcnt(0)
	v_mul_f32_e32 v32, 0x42800000, v36
	v_mul_f32_e32 v35, 0x42800000, v37
	v_cvt_pk_fp8_f32 v39, v32, v35 op_sel:[0,0,1]
	v_mad_u64_u32 v[34:35], s[12:13], v34, v78, v[66:67]
	v_mov_b32_e32 v32, v35
	v_mad_u64_u32 v[32:33], s[12:13], v33, v78, v[32:33]
	v_mov_b32_e32 v35, v32
	v_lshl_add_u64 v[32:33], v[34:35], 0, v[64:65]
	v_lshl_add_u64 v[32:33], v[32:33], 0, v[72:73]
	global_store_dwordx2 v[32:33], v[38:39], off sc1
.LBB0_141:
	s_andn2_saveexec_b64 s[0:1], s[0:1]
	s_cbranch_execz .LBB0_106
	ds_read2_b32 v[36:37], v83 offset0:24 offset1:57
	ds_read2_b32 v[38:39], v83 offset0:90 offset1:123
	ds_read2_b32 v[42:43], v83 offset0:222 offset1:255
	s_waitcnt lgkmcnt(2)
	v_bfe_u32 v35, v36, 16, 1
	v_bfe_u32 v40, v37, 16, 1
	v_add3_u32 v35, v36, v35, s63
	s_waitcnt lgkmcnt(1)
	v_bfe_u32 v41, v38, 16, 1
	v_add3_u32 v36, v37, v40, s63
	v_lshrrev_b32_e32 v35, 16, v35
	v_and_or_b32 v36, v36, s64, v35
	v_add3_u32 v35, v38, v41, s63
	ds_read2_b32 v[40:41], v83 offset0:156 offset1:189
	v_bfe_u32 v37, v39, 16, 1
	v_lshrrev_b32_e32 v35, 16, v35
	v_add3_u32 v37, v39, v37, s63
	v_and_or_b32 v37, v37, s64, v35
	s_waitcnt lgkmcnt(0)
	v_bfe_u32 v35, v40, 16, 1
	v_add3_u32 v35, v40, v35, s63
	v_bfe_u32 v38, v41, 16, 1
	v_lshrrev_b32_e32 v35, 16, v35
	v_add3_u32 v38, v41, v38, s63
	v_and_or_b32 v38, v38, s64, v35
	v_bfe_u32 v35, v42, 16, 1
	v_add3_u32 v35, v42, v35, s63
	v_bfe_u32 v39, v43, 16, 1
	v_lshrrev_b32_e32 v35, 16, v35
	v_add3_u32 v39, v43, v39, s63
	v_and_or_b32 v39, v39, s64, v35
	v_mad_u64_u32 v[34:35], s[12:13], v34, v78, 0
	v_mov_b32_e32 v40, v35
	v_mad_u64_u32 v[40:41], s[12:13], v33, v78, v[40:41]
	v_mov_b32_e32 v35, v40
	v_lshl_add_u64 v[34:35], v[34:35], 1, v[66:67]
	v_lshl_add_u64 v[34:35], v[64:65], 1, v[34:35]
	v_mov_b32_e32 v33, v69
	v_lshl_add_u64 v[32:33], v[34:35], 0, v[32:33]
	global_store_dwordx4 v[32:33], v[36:39], off sc1
	s_branch .LBB0_106

.LBB0_153:
	s_or_b64 exec, exec, s[22:23]
	v_add_f32_e32 v139, v92, v93
	v_add_f32_e32 v141, v94, v95
	v_add_f32_e32 v139, v139, v141
	v_add_f32_e32 v141, v88, v89
	v_add_f32_e32 v142, v90, v91
	v_add_f32_e32 v139, 0, v139
	v_add_f32_e32 v141, v141, v142
	v_add_f32_e32 v139, v139, v141
	v_add_f32_e32 v141, v84, v85
	v_add_f32_e32 v142, v86, v87
	v_add_f32_e32 v141, v141, v142
	v_add_f32_e32 v139, v139, v141
	v_add_f32_e32 v141, v80, v81
	v_add_f32_e32 v142, v82, v83
	v_add_f32_e32 v141, v141, v142
	v_add_f32_e32 v139, v139, v141
	v_add_f32_e32 v141, v76, v77
	v_add_f32_e32 v142, v78, v79
	v_add_f32_e32 v141, v141, v142
	v_add_f32_e32 v139, v139, v141
	v_add_f32_e32 v141, v72, v73
	v_add_f32_e32 v142, v74, v75
	v_add_f32_e32 v141, v141, v142
	v_add_f32_e32 v139, v139, v141
	v_add_f32_e32 v141, v68, v69
	v_add_f32_e32 v142, v70, v71
	v_add_f32_e32 v141, v141, v142
	v_add_f32_e32 v139, v139, v141
	v_add_f32_e32 v141, v64, v65
	v_add_f32_e32 v142, v66, v67
	v_add_f32_e32 v141, v141, v142
	v_add_f32_e32 v139, v139, v141
	s_nop 1
	v_add_f32_dpp v139, v139, v139 quad_perm:[1,0,3,2] row_mask:0xf bank_mask:0xf bound_ctrl:1
	s_nop 1
	v_add_f32_dpp v139, v139, v139 quad_perm:[2,3,0,1] row_mask:0xf bank_mask:0xf bound_ctrl:1
	s_nop 1
	v_add_f32_dpp v139, v139, v139 row_half_mirror row_mask:0xf bank_mask:0xf bound_ctrl:1
	s_nop 1
	v_add_f32_dpp v139, v139, v139 row_mirror row_mask:0xf bank_mask:0xf bound_ctrl:1
	s_nop 0
	v_readlane_b32 s24, v139, 16
	v_readlane_b32 s25, v139, 48
	v_readlane_b32 s22, v139, 0
	v_readlane_b32 s23, v139, 32
	v_mov_b32_e32 v142, s24
	v_mov_b32_e32 v143, s25
	v_pk_add_f32 v[142:143], s[22:23], v[142:143]
	s_nop 0
	v_add_f32_e32 v139, v142, v143
	v_fmamk_f32 v93, v139, 0xba000000, v93
	v_fmamk_f32 v89, v139, 0xba000000, v89
	v_fmamk_f32 v153, v139, 0xba000000, v95
	v_fmamk_f32 v152, v139, 0xba000000, v94
	v_fmac_f32_e32 v92, 0xba000000, v139
	v_fmamk_f32 v145, v139, 0xba000000, v91
	v_fmac_f32_e32 v88, 0xba000000, v139
	v_mov_b32_e32 v94, v93
	v_mov_b32_e32 v95, v89
	v_fmamk_f32 v144, v139, 0xba000000, v90
	v_mov_b32_e32 v90, v92
	v_mov_b32_e32 v91, v88
	v_pk_mul_f32 v[94:95], v[94:95], v[94:95]
	v_mov_b32_e32 v142, v153
	v_mov_b32_e32 v143, v145
	v_pk_fma_f32 v[90:91], v[90:91], v[90:91], v[94:95]
	v_mov_b32_e32 v94, v152
	v_mov_b32_e32 v95, v144
	v_pk_mul_f32 v[142:143], v[142:143], v[142:143]
	v_fmamk_f32 v87, v139, 0xba000000, v87
	v_pk_fma_f32 v[94:95], v[94:95], v[94:95], v[142:143]
	v_fmamk_f32 v143, v139, 0xba000000, v85
	v_pk_add_f32 v[90:91], v[90:91], v[94:95]
	v_fmamk_f32 v142, v139, 0xba000000, v84
	v_fmac_f32_e32 v86, 0xba000000, v139
	v_pk_add_f32 v[154:155], v[90:91], v[90:91] op_sel_hi:[0,1]
	v_pk_mul_f32 v[84:85], v[86:87], v[86:87]
	v_pk_mul_f32 v[90:91], v[142:143], v[142:143]
	v_fmac_f32_e32 v82, 0xba000000, v139
	v_pk_mov_b32 v[94:95], v[90:91], v[84:85] op_sel:[1,0]
	v_mov_b32_e32 v91, v85
	v_pk_add_f32 v[84:85], v[94:95], v[90:91]
	v_fmamk_f32 v94, v139, 0xba000000, v80
	v_fmamk_f32 v95, v139, 0xba000000, v81
	v_mul_f32_e32 v80, v94, v94
	v_pk_fma_f32 v[80:81], v[94:95], v[94:95], v[80:81] op_sel_hi:[1,1,0]
	v_fmamk_f32 v83, v139, 0xba000000, v83
	v_mul_f32_e32 v80, v82, v82
	v_pk_add_f32 v[84:85], v[84:85], v[84:85] op_sel_hi:[0,1]
	v_pk_fma_f32 v[156:157], v[82:83], v[82:83], v[80:81] op_sel_hi:[1,1,0]
	v_fmamk_f32 v91, v139, 0xba000000, v79
	v_fmamk_f32 v90, v139, 0xba000000, v78
	v_fmamk_f32 v77, v139, 0xba000000, v77
	v_fmac_f32_e32 v76, 0xba000000, v139
	v_mul_f32_e32 v80, v76, v76
	v_mul_f32_e32 v156, v77, v77
	v_mul_f32_e32 v84, v90, v90
	v_mul_f32_e32 v154, v91, v91
	v_pk_add_f32 v[78:79], v[80:81], v[156:157]
	v_pk_add_f32 v[80:81], v[84:85], v[154:155]
	v_fmamk_f32 v85, v139, 0xba000000, v73
	v_fmamk_f32 v84, v139, 0xba000000, v72
	v_fmamk_f32 v75, v139, 0xba000000, v75
	v_fmac_f32_e32 v74, 0xba000000, v139
	v_pk_add_f32 v[78:79], v[78:79], v[80:81]
	v_pk_mul_f32 v[72:73], v[74:75], v[74:75]
	v_pk_mul_f32 v[80:81], v[84:85], v[84:85]
	v_fmac_f32_e32 v70, 0xba000000, v139
	v_pk_mov_b32 v[154:155], v[80:81], v[72:73] op_sel:[1,0]
	v_mov_b32_e32 v81, v73
	v_pk_add_f32 v[72:73], v[154:155], v[80:81]
	v_fmamk_f32 v80, v139, 0xba000000, v68
	v_fmamk_f32 v81, v139, 0xba000000, v69
	v_mul_f32_e32 v68, v80, v80
	v_pk_fma_f32 v[68:69], v[80:81], v[80:81], v[68:69] op_sel_hi:[1,1,0]
	v_fmamk_f32 v71, v139, 0xba000000, v71
	v_mul_f32_e32 v68, v70, v70
	v_pk_add_f32 v[78:79], v[78:79], v[78:79] op_sel_hi:[0,1]
	v_pk_add_f32 v[72:73], v[72:73], v[72:73] op_sel_hi:[0,1]
	v_pk_fma_f32 v[154:155], v[70:71], v[70:71], v[68:69] op_sel_hi:[1,1,0]
	v_fmamk_f32 v67, v139, 0xba000000, v67
	v_fmamk_f32 v66, v139, 0xba000000, v66
	v_fmamk_f32 v65, v139, 0xba000000, v65
	v_fmac_f32_e32 v64, 0xba000000, v139
	v_mul_f32_e32 v68, v64, v64
	v_mul_f32_e32 v154, v65, v65
	v_mul_f32_e32 v72, v66, v66
	v_mul_f32_e32 v78, v67, v67
	v_pk_add_f32 v[68:69], v[68:69], v[154:155]
	v_pk_add_f32 v[72:73], v[72:73], v[78:79]
	v_lshl_add_u64 v[154:155], s[54:55], 0, v[100:101]
	v_pk_add_f32 v[68:69], v[68:69], v[72:73]
	s_nop 0
	v_add_f32_e32 v68, v68, v69
	s_nop 1
	v_add_f32_dpp v68, v68, v68 quad_perm:[1,0,3,2] row_mask:0xf bank_mask:0xf bound_ctrl:1
	s_nop 1
	v_add_f32_dpp v68, v68, v68 quad_perm:[2,3,0,1] row_mask:0xf bank_mask:0xf bound_ctrl:1
	s_nop 1
	v_add_f32_dpp v68, v68, v68 row_half_mirror row_mask:0xf bank_mask:0xf bound_ctrl:1
	s_nop 1
	v_add_f32_dpp v68, v68, v68 row_mirror row_mask:0xf bank_mask:0xf bound_ctrl:1
	s_nop 0
	v_readlane_b32 s24, v68, 16
	v_readlane_b32 s25, v68, 48
	v_readlane_b32 s22, v68, 0
	v_readlane_b32 s23, v68, 32
	v_mov_b32_e32 v68, s24
	v_mov_b32_e32 v69, s25
	v_pk_add_f32 v[68:69], s[22:23], v[68:69]
	s_mov_b32 s22, 0xf800000
	v_add_f32_e32 v68, v68, v69
	v_fmamk_f32 v68, v68, 0x3a000000, v97
	v_cmp_gt_f32_e32 vcc, s22, v68
	v_mul_f32_e32 v69, 0x4f800000, v68
	s_nop 0
	v_cndmask_b32_e32 v68, v68, v69, vcc
	v_sqrt_f32_e32 v69, v68
	s_nop 0
	v_add_u32_e32 v72, -1, v69
	v_fma_f32 v73, -v72, v69, v68
	v_cmp_ge_f32_e64 s[22:23], 0, v73
	v_add_u32_e32 v73, 1, v69
	s_nop 0
	v_cndmask_b32_e64 v72, v69, v72, s[22:23]
	v_fma_f32 v69, -v73, v69, v68
	v_cmp_lt_f32_e64 s[22:23], 0, v69
	s_nop 1
	v_cndmask_b32_e64 v69, v72, v73, s[22:23]
	v_mul_f32_e32 v72, 0x37800000, v69
	v_cndmask_b32_e32 v69, v69, v72, vcc
	v_cmp_class_f32_e32 vcc, v68, v148
	s_nop 1
	v_cndmask_b32_e32 v68, v69, v68, vcc
	v_div_scale_f32 v69, s[22:23], v68, v68, 1.0
	v_rcp_f32_e32 v72, v69
	s_brev_b32 s22, 32
	v_fma_f32 v73, -v69, v72, 1.0
	v_fmac_f32_e32 v72, v73, v72
	v_div_scale_f32 v73, vcc, 1.0, v68, 1.0
	v_mul_f32_e32 v78, v73, v72
	v_fma_f32 v79, -v69, v78, v73
	v_fmac_f32_e32 v78, v79, v72
	v_fma_f32 v69, -v69, v78, v73
	v_div_fmas_f32 v69, v69, v72, v78
	v_div_fixup_f32 v68, v69, v68, 1.0
	v_pk_mul_f32 v[78:79], v[92:93], v[68:69] op_sel_hi:[1,0]
	v_pk_mul_f32 v[92:93], v[152:153], v[68:69] op_sel_hi:[1,0]
	s_waitcnt vmcnt(7)
	v_pk_fma_f32 v[160:161], v[132:133], v[78:79], v[0:1]
	v_pk_fma_f32 v[92:93], v[130:131], v[92:93], v[2:3]
	v_and_b32_sdwa v139, v161, v150 dst_sel:DWORD dst_unused:UNUSED_PAD src0_sel:WORD_1 src1_sel:DWORD
	v_and_b32_sdwa v79, v93, v150 dst_sel:DWORD dst_unused:UNUSED_PAD src0_sel:WORD_1 src1_sel:DWORD
	v_and_b32_sdwa v69, v92, v150 dst_sel:DWORD dst_unused:UNUSED_PAD src0_sel:WORD_1 src1_sel:DWORD
	v_add3_u32 v79, v93, v79, s82
	v_add3_u32 v69, v92, v69, s82
	v_and_b32_e32 v79, 0xffff0000, v79
	v_or_b32_sdwa v153, v79, v69 dst_sel:DWORD dst_unused:UNUSED_PAD src0_sel:DWORD src1_sel:WORD_1
	v_mov_b32_e32 v69, 0
	v_cvt_pk_fp8_f32 v69, v160, v161
	v_and_b32_sdwa v78, v160, v150 dst_sel:DWORD dst_unused:UNUSED_PAD src0_sel:WORD_1 src1_sel:DWORD
	v_add3_u32 v139, v161, v139, s82
	v_lshl_add_u64 v[72:73], s[54:55], 0, v[98:99]
	v_add3_u32 v78, v160, v78, s82
	v_and_b32_e32 v139, 0xffff0000, v139
	v_or_b32_sdwa v152, v139, v78 dst_sel:DWORD dst_unused:UNUSED_PAD src0_sel:DWORD src1_sel:WORD_1
	v_add_co_u32_e32 v78, vcc, s22, v72
	v_cvt_pk_fp8_f32 v69, v92, v93 op_sel:[0,0,1]
	s_nop 0
	v_addc_co_u32_e32 v79, vcc, 0, v73, vcc
	s_mov_b32 s22, 0x12800000
	v_add_co_u32_e32 v72, vcc, s22, v154
	global_store_dwordx2 v[78:79], v[152:153], off sc1
	s_nop 0
	v_addc_co_u32_e32 v73, vcc, 0, v155, vcc
	global_store_dword v[72:73], v69, off
	ds_read_b128 v[152:155], v146
	ds_read_b128 v[156:159], v146 offset:32768
	v_pk_mul_f32 v[144:145], v[144:145], v[68:69] op_sel_hi:[1,0]
	v_pk_mul_f32 v[88:89], v[88:89], v[68:69] op_sel_hi:[1,0]
	s_waitcnt vmcnt(8)
	v_pk_fma_f32 v[144:145], v[106:107], v[144:145], v[6:7]
	s_waitcnt lgkmcnt(1)
	v_pk_fma_f32 v[162:163], v[152:153], v[160:161], 0 op_sel_hi:[1,0,0]
	v_pk_fma_f32 v[164:165], v[154:155], v[160:161], 0 op_sel_hi:[1,0,0]
	s_waitcnt lgkmcnt(0)
	v_pk_fma_f32 v[166:167], v[156:157], v[160:161], 0 op_sel_hi:[1,0,0]
	v_pk_fma_f32 v[170:171], v[158:159], v[160:161], 0 op_sel_hi:[1,0,0]
	ds_read_b128 v[152:155], v146 offset:8192
	ds_read_b128 v[156:159], v146 offset:40960
	v_and_b32_sdwa v141, v145, v150 dst_sel:DWORD dst_unused:UNUSED_PAD src0_sel:WORD_1 src1_sel:DWORD
	v_and_b32_sdwa v69, v144, v150 dst_sel:DWORD dst_unused:UNUSED_PAD src0_sel:WORD_1 src1_sel:DWORD
	v_add3_u32 v141, v145, v141, s82
	s_waitcnt lgkmcnt(1)
	v_pk_fma_f32 v[164:165], v[154:155], v[160:161], v[164:165] op_sel:[0,1,0]
	v_pk_fma_f32 v[162:163], v[152:153], v[160:161], v[162:163] op_sel:[0,1,0]
	s_waitcnt lgkmcnt(0)
	v_pk_fma_f32 v[170:171], v[158:159], v[160:161], v[170:171] op_sel:[0,1,0]
	v_pk_fma_f32 v[160:161], v[156:157], v[160:161], v[166:167] op_sel:[0,1,0]
	ds_read_b128 v[152:155], v146 offset:16384
	ds_read_b128 v[156:159], v146 offset:49152
	v_add3_u32 v69, v144, v69, s82
	v_and_b32_e32 v141, 0xffff0000, v141
	v_pk_fma_f32 v[88:89], v[108:109], v[88:89], v[4:5]
	s_waitcnt lgkmcnt(1)
	v_pk_fma_f32 v[162:163], v[152:153], v[92:93], v[162:163] op_sel_hi:[1,0,1]
	v_pk_fma_f32 v[164:165], v[154:155], v[92:93], v[164:165] op_sel_hi:[1,0,1]
	s_waitcnt lgkmcnt(0)
	v_pk_fma_f32 v[160:161], v[156:157], v[92:93], v[160:161] op_sel_hi:[1,0,1]
	v_pk_fma_f32 v[166:167], v[158:159], v[92:93], v[170:171] op_sel_hi:[1,0,1]
	ds_read_b128 v[152:155], v146 offset:24576
	ds_read_b128 v[156:159], v146 offset:57344
	v_and_b32_sdwa v139, v88, v150 dst_sel:DWORD dst_unused:UNUSED_PAD src0_sel:WORD_1 src1_sel:DWORD
	v_add3_u32 v139, v88, v139, s82
	s_waitcnt lgkmcnt(1)
	v_pk_fma_f32 v[162:163], v[152:153], v[92:93], v[162:163] op_sel:[0,1,0]
	v_or_b32_sdwa v153, v141, v69 dst_sel:DWORD dst_unused:UNUSED_PAD src0_sel:DWORD src1_sel:WORD_1
	v_mov_b32_e32 v69, 0
	v_cvt_pk_fp8_f32 v69, v88, v89
	v_and_b32_sdwa v152, v89, v150 dst_sel:DWORD dst_unused:UNUSED_PAD src0_sel:WORD_1 src1_sel:DWORD
	v_add3_u32 v152, v89, v152, s82
	v_and_b32_e32 v152, 0xffff0000, v152
	v_cvt_pk_fp8_f32 v69, v144, v145 op_sel:[0,0,1]
	v_or_b32_sdwa v152, v152, v139 dst_sel:DWORD dst_unused:UNUSED_PAD src0_sel:DWORD src1_sel:WORD_1
	global_store_dwordx2 v[78:79], v[152:153], off offset:512 sc1
	v_pk_fma_f32 v[164:165], v[154:155], v[92:93], v[164:165] op_sel:[0,1,0]
	global_store_dword v[72:73], v69, off offset:256
	s_waitcnt lgkmcnt(0)
	v_pk_fma_f32 v[166:167], v[92:93], v[158:159], v[166:167] op_sel:[1,0,0]
	v_pk_fma_f32 v[92:93], v[92:93], v[156:157], v[160:161] op_sel:[1,0,0]
	ds_read_b128 v[152:155], v146 offset:1024
	ds_read_b128 v[156:159], v146 offset:33792
	v_pk_mul_f32 v[86:87], v[86:87], v[68:69] op_sel_hi:[1,0]
	s_waitcnt lgkmcnt(1)
	v_pk_fma_f32 v[160:161], v[88:89], v[152:153], v[162:163] op_sel_hi:[0,1,1]
	v_pk_fma_f32 v[162:163], v[88:89], v[154:155], v[164:165] op_sel_hi:[0,1,1]
	s_waitcnt lgkmcnt(0)
	v_pk_fma_f32 v[92:93], v[88:89], v[156:157], v[92:93] op_sel_hi:[0,1,1]
	v_pk_fma_f32 v[164:165], v[88:89], v[158:159], v[166:167] op_sel_hi:[0,1,1]
	ds_read_b128 v[152:155], v146 offset:9216
	ds_read_b128 v[156:159], v146 offset:41984
	s_waitcnt lgkmcnt(1)
	v_pk_fma_f32 v[162:163], v[88:89], v[154:155], v[162:163] op_sel:[1,0,0]
	v_pk_fma_f32 v[160:161], v[88:89], v[152:153], v[160:161] op_sel:[1,0,0]
	s_waitcnt lgkmcnt(0)
	v_pk_fma_f32 v[164:165], v[88:89], v[158:159], v[164:165] op_sel:[1,0,0]
	v_pk_fma_f32 v[88:89], v[88:89], v[156:157], v[92:93] op_sel:[1,0,0]
	ds_read_b128 v[152:155], v146 offset:17408
	ds_read_b128 v[156:159], v146 offset:50176
	s_waitcnt lgkmcnt(1)
	v_pk_fma_f32 v[92:93], v[144:145], v[152:153], v[160:161] op_sel_hi:[0,1,1]
	v_pk_fma_f32 v[160:161], v[144:145], v[154:155], v[162:163] op_sel_hi:[0,1,1]
	s_waitcnt lgkmcnt(0)
	v_pk_fma_f32 v[88:89], v[144:145], v[156:157], v[88:89] op_sel_hi:[0,1,1]
	v_pk_fma_f32 v[162:163], v[144:145], v[158:159], v[164:165] op_sel_hi:[0,1,1]
	ds_read_b128 v[152:155], v146 offset:25600
	ds_read_b128 v[156:159], v146 offset:58368
	s_waitcnt lgkmcnt(1)
	v_pk_fma_f32 v[92:93], v[144:145], v[152:153], v[92:93] op_sel:[1,0,0]
	s_waitcnt lgkmcnt(0)
	v_pk_fma_f32 v[152:153], v[144:145], v[158:159], v[162:163] op_sel:[1,0,0]
	s_waitcnt vmcnt(9)
	v_pk_fma_f32 v[158:159], v[110:111], v[86:87], v[10:11]
	v_pk_fma_f32 v[156:157], v[144:145], v[156:157], v[88:89] op_sel:[1,0,0]
	v_and_b32_sdwa v87, v159, v150 dst_sel:DWORD dst_unused:UNUSED_PAD src0_sel:WORD_1 src1_sel:DWORD
	v_pk_mul_f32 v[88:89], v[142:143], v[68:69] op_sel_hi:[1,0]
	v_and_b32_sdwa v69, v158, v150 dst_sel:DWORD dst_unused:UNUSED_PAD src0_sel:WORD_1 src1_sel:DWORD
	v_add3_u32 v87, v159, v87, s82
	v_add3_u32 v69, v158, v69, s82
	v_and_b32_e32 v87, 0xffff0000, v87
	v_pk_fma_f32 v[154:155], v[144:145], v[154:155], v[160:161] op_sel:[1,0,0]
	v_pk_fma_f32 v[160:161], v[112:113], v[88:89], v[8:9]
	v_or_b32_sdwa v87, v87, v69 dst_sel:DWORD dst_unused:UNUSED_PAD src0_sel:DWORD src1_sel:WORD_1
	v_mov_b32_e32 v69, 0
	v_cvt_pk_fp8_f32 v69, v160, v161
	v_and_b32_sdwa v88, v161, v150 dst_sel:DWORD dst_unused:UNUSED_PAD src0_sel:WORD_1 src1_sel:DWORD
	v_and_b32_sdwa v86, v160, v150 dst_sel:DWORD dst_unused:UNUSED_PAD src0_sel:WORD_1 src1_sel:DWORD
	v_add3_u32 v88, v161, v88, s82
	v_cvt_pk_fp8_f32 v69, v158, v159 op_sel:[0,0,1]
	v_add3_u32 v86, v160, v86, s82
	v_and_b32_e32 v88, 0xffff0000, v88
	v_or_b32_sdwa v86, v88, v86 dst_sel:DWORD dst_unused:UNUSED_PAD src0_sel:DWORD src1_sel:WORD_1
	global_store_dwordx2 v[78:79], v[86:87], off offset:1024 sc1
	global_store_dword v[72:73], v69, off offset:512
	ds_read_b128 v[86:89], v146 offset:2048
	ds_read_b128 v[142:145], v146 offset:34816
	v_pk_mul_f32 v[82:83], v[82:83], v[68:69] op_sel_hi:[1,0]
	s_waitcnt lgkmcnt(1)
	v_pk_fma_f32 v[92:93], v[160:161], v[86:87], v[92:93] op_sel_hi:[0,1,1]
	v_pk_fma_f32 v[154:155], v[160:161], v[88:89], v[154:155] op_sel_hi:[0,1,1]
	s_waitcnt lgkmcnt(0)
	v_pk_fma_f32 v[156:157], v[160:161], v[142:143], v[156:157] op_sel_hi:[0,1,1]
	v_pk_fma_f32 v[152:153], v[160:161], v[144:145], v[152:153] op_sel_hi:[0,1,1]
	ds_read_b128 v[86:89], v146 offset:10240
	ds_read_b128 v[142:145], v146 offset:43008
	s_waitcnt vmcnt(10)
	v_pk_fma_f32 v[82:83], v[134:135], v[82:83], v[14:15]
	s_waitcnt lgkmcnt(1)
	v_pk_fma_f32 v[154:155], v[160:161], v[88:89], v[154:155] op_sel:[1,0,0]
	v_pk_fma_f32 v[92:93], v[160:161], v[86:87], v[92:93] op_sel:[1,0,0]
	s_waitcnt lgkmcnt(0)
	v_pk_fma_f32 v[152:153], v[160:161], v[144:145], v[152:153] op_sel:[1,0,0]
	v_pk_fma_f32 v[156:157], v[160:161], v[142:143], v[156:157] op_sel:[1,0,0]
	ds_read_b128 v[86:89], v146 offset:18432
	ds_read_b128 v[142:145], v146 offset:51200
	s_waitcnt lgkmcnt(1)
	v_pk_fma_f32 v[92:93], v[158:159], v[86:87], v[92:93] op_sel_hi:[0,1,1]
	v_pk_fma_f32 v[154:155], v[158:159], v[88:89], v[154:155] op_sel_hi:[0,1,1]
	s_waitcnt lgkmcnt(0)
	v_pk_fma_f32 v[156:157], v[158:159], v[142:143], v[156:157] op_sel_hi:[0,1,1]
	v_pk_fma_f32 v[152:153], v[158:159], v[144:145], v[152:153] op_sel_hi:[0,1,1]
	ds_read_b128 v[86:89], v146 offset:26624
	ds_read_b128 v[142:145], v146 offset:59392
	s_waitcnt lgkmcnt(1)
	v_pk_fma_f32 v[160:161], v[158:159], v[86:87], v[92:93] op_sel:[1,0,0]
	v_pk_mul_f32 v[86:87], v[94:95], v[68:69] op_sel_hi:[1,0]
	s_waitcnt lgkmcnt(0)
	v_pk_fma_f32 v[144:145], v[158:159], v[144:145], v[152:153] op_sel:[1,0,0]
	v_pk_fma_f32 v[152:153], v[136:137], v[86:87], v[12:13]
	v_and_b32_sdwa v87, v83, v150 dst_sel:DWORD dst_unused:UNUSED_PAD src0_sel:WORD_1 src1_sel:DWORD
	v_and_b32_sdwa v69, v82, v150 dst_sel:DWORD dst_unused:UNUSED_PAD src0_sel:WORD_1 src1_sel:DWORD
	v_add3_u32 v87, v83, v87, s82
	v_add3_u32 v69, v82, v69, s82
	v_and_b32_e32 v87, 0xffff0000, v87
	v_or_b32_sdwa v87, v87, v69 dst_sel:DWORD dst_unused:UNUSED_PAD src0_sel:DWORD src1_sel:WORD_1
	v_mov_b32_e32 v69, 0
	v_cvt_pk_fp8_f32 v69, v152, v153
	v_pk_fma_f32 v[154:155], v[158:159], v[88:89], v[154:155] op_sel:[1,0,0]
	v_and_b32_sdwa v88, v153, v150 dst_sel:DWORD dst_unused:UNUSED_PAD src0_sel:WORD_1 src1_sel:DWORD
	v_and_b32_sdwa v86, v152, v150 dst_sel:DWORD dst_unused:UNUSED_PAD src0_sel:WORD_1 src1_sel:DWORD
	v_cvt_pk_fp8_f32 v69, v82, v83 op_sel:[0,0,1]
	v_add3_u32 v88, v153, v88, s82
	v_add3_u32 v86, v152, v86, s82
	v_and_b32_e32 v88, 0xffff0000, v88
	v_or_b32_sdwa v86, v88, v86 dst_sel:DWORD dst_unused:UNUSED_PAD src0_sel:DWORD src1_sel:WORD_1
	global_store_dwordx2 v[78:79], v[86:87], off offset:1536 sc1
	global_store_dword v[72:73], v69, off offset:768
	ds_read_b128 v[86:89], v146 offset:3072
	ds_read_b128 v[92:95], v146 offset:35840
	v_pk_fma_f32 v[142:143], v[158:159], v[142:143], v[156:157] op_sel:[1,0,0]
	v_pk_mul_f32 v[76:77], v[76:77], v[68:69] op_sel_hi:[1,0]
	s_waitcnt lgkmcnt(1)
	v_pk_fma_f32 v[156:157], v[152:153], v[86:87], v[160:161] op_sel_hi:[0,1,1]
	v_pk_fma_f32 v[154:155], v[152:153], v[88:89], v[154:155] op_sel_hi:[0,1,1]
	s_waitcnt lgkmcnt(0)
	v_pk_fma_f32 v[142:143], v[152:153], v[92:93], v[142:143] op_sel_hi:[0,1,1]
	v_pk_fma_f32 v[144:145], v[152:153], v[94:95], v[144:145] op_sel_hi:[0,1,1]
	ds_read_b128 v[86:89], v146 offset:11264
	ds_read_b128 v[92:95], v146 offset:44032
	s_waitcnt vmcnt(11)
	v_pk_fma_f32 v[76:77], v[116:117], v[76:77], v[16:17]
	s_waitcnt lgkmcnt(1)
	v_pk_fma_f32 v[154:155], v[152:153], v[88:89], v[154:155] op_sel:[1,0,0]
	v_pk_fma_f32 v[156:157], v[152:153], v[86:87], v[156:157] op_sel:[1,0,0]
	s_waitcnt lgkmcnt(0)
	v_pk_fma_f32 v[144:145], v[152:153], v[94:95], v[144:145] op_sel:[1,0,0]
	v_pk_fma_f32 v[142:143], v[152:153], v[92:93], v[142:143] op_sel:[1,0,0]
	ds_read_b128 v[86:89], v146 offset:19456
	ds_read_b128 v[92:95], v146 offset:52224
	s_waitcnt lgkmcnt(1)
	v_pk_fma_f32 v[152:153], v[82:83], v[86:87], v[156:157] op_sel_hi:[0,1,1]
	v_pk_fma_f32 v[154:155], v[82:83], v[88:89], v[154:155] op_sel_hi:[0,1,1]
	s_waitcnt lgkmcnt(0)
	v_pk_fma_f32 v[142:143], v[82:83], v[92:93], v[142:143] op_sel_hi:[0,1,1]
	v_pk_fma_f32 v[144:145], v[82:83], v[94:95], v[144:145] op_sel_hi:[0,1,1]
	ds_read_b128 v[86:89], v146 offset:27648
	ds_read_b128 v[92:95], v146 offset:60416
	s_waitcnt lgkmcnt(1)
	v_pk_fma_f32 v[152:153], v[82:83], v[86:87], v[152:153] op_sel:[1,0,0]
	v_pk_mul_f32 v[86:87], v[90:91], v[68:69] op_sel_hi:[1,0]
	v_pk_fma_f32 v[154:155], v[82:83], v[88:89], v[154:155] op_sel:[1,0,0]
	s_waitcnt lgkmcnt(0)
	v_pk_fma_f32 v[94:95], v[82:83], v[94:95], v[144:145] op_sel:[1,0,0]
	v_pk_fma_f32 v[82:83], v[82:83], v[92:93], v[142:143] op_sel:[1,0,0]
	v_pk_fma_f32 v[142:143], v[114:115], v[86:87], v[18:19]
	v_and_b32_sdwa v88, v77, v150 dst_sel:DWORD dst_unused:UNUSED_PAD src0_sel:WORD_1 src1_sel:DWORD
	v_and_b32_sdwa v87, v143, v150 dst_sel:DWORD dst_unused:UNUSED_PAD src0_sel:WORD_1 src1_sel:DWORD
	v_and_b32_sdwa v69, v142, v150 dst_sel:DWORD dst_unused:UNUSED_PAD src0_sel:WORD_1 src1_sel:DWORD
	v_add3_u32 v87, v143, v87, s82
	v_add3_u32 v69, v142, v69, s82
	v_and_b32_e32 v87, 0xffff0000, v87
	v_or_b32_sdwa v87, v87, v69 dst_sel:DWORD dst_unused:UNUSED_PAD src0_sel:DWORD src1_sel:WORD_1
	v_mov_b32_e32 v69, 0
	v_cvt_pk_fp8_f32 v69, v76, v77
	v_and_b32_sdwa v86, v76, v150 dst_sel:DWORD dst_unused:UNUSED_PAD src0_sel:WORD_1 src1_sel:DWORD
	v_add3_u32 v88, v77, v88, s82
	v_add3_u32 v86, v76, v86, s82
	v_cvt_pk_fp8_f32 v69, v142, v143 op_sel:[0,0,1]
	v_and_b32_e32 v88, 0xffff0000, v88
	v_or_b32_sdwa v86, v88, v86 dst_sel:DWORD dst_unused:UNUSED_PAD src0_sel:DWORD src1_sel:WORD_1
	global_store_dwordx2 v[78:79], v[86:87], off offset:2048 sc1
	global_store_dword v[72:73], v69, off offset:1024
	ds_read_b128 v[86:89], v146 offset:4096
	ds_read_b128 v[90:93], v146 offset:36864
	v_pk_mul_f32 v[74:75], v[74:75], v[68:69] op_sel_hi:[1,0]
	s_waitcnt lgkmcnt(1)
	v_pk_fma_f32 v[144:145], v[76:77], v[86:87], v[152:153] op_sel_hi:[0,1,1]
	v_pk_fma_f32 v[152:153], v[76:77], v[88:89], v[154:155] op_sel_hi:[0,1,1]
	s_waitcnt lgkmcnt(0)
	v_pk_fma_f32 v[82:83], v[76:77], v[90:91], v[82:83] op_sel_hi:[0,1,1]
	v_pk_fma_f32 v[94:95], v[76:77], v[92:93], v[94:95] op_sel_hi:[0,1,1]
	ds_read_b128 v[86:89], v146 offset:12288
	ds_read_b128 v[90:93], v146 offset:45056
	s_waitcnt lgkmcnt(1)
	v_pk_fma_f32 v[152:153], v[76:77], v[88:89], v[152:153] op_sel:[1,0,0]
	v_pk_fma_f32 v[144:145], v[76:77], v[86:87], v[144:145] op_sel:[1,0,0]
	s_waitcnt lgkmcnt(0)
	v_pk_fma_f32 v[94:95], v[76:77], v[92:93], v[94:95] op_sel:[1,0,0]
	v_pk_fma_f32 v[76:77], v[76:77], v[90:91], v[82:83] op_sel:[1,0,0]
	ds_read_b128 v[86:89], v146 offset:20480
	ds_read_b128 v[90:93], v146 offset:53248
	s_waitcnt lgkmcnt(1)
	v_pk_fma_f32 v[82:83], v[142:143], v[86:87], v[144:145] op_sel_hi:[0,1,1]
	v_pk_fma_f32 v[144:145], v[142:143], v[88:89], v[152:153] op_sel_hi:[0,1,1]
	s_waitcnt lgkmcnt(0)
	v_pk_fma_f32 v[76:77], v[142:143], v[90:91], v[76:77] op_sel_hi:[0,1,1]
	v_pk_fma_f32 v[94:95], v[142:143], v[92:93], v[94:95] op_sel_hi:[0,1,1]
	ds_read_b128 v[86:89], v146 offset:28672
	ds_read_b128 v[90:93], v146 offset:61440
	s_waitcnt lgkmcnt(1)
	v_pk_fma_f32 v[88:89], v[142:143], v[88:89], v[144:145] op_sel:[1,0,0]
	s_waitcnt lgkmcnt(0)
	v_pk_fma_f32 v[92:93], v[142:143], v[92:93], v[94:95] op_sel:[1,0,0]
	s_waitcnt vmcnt(12)
	v_pk_fma_f32 v[94:95], v[118:119], v[74:75], v[22:23]
	v_pk_fma_f32 v[90:91], v[142:143], v[90:91], v[76:77] op_sel:[1,0,0]
	v_and_b32_sdwa v75, v95, v150 dst_sel:DWORD dst_unused:UNUSED_PAD src0_sel:WORD_1 src1_sel:DWORD
	v_pk_mul_f32 v[76:77], v[84:85], v[68:69] op_sel_hi:[1,0]
	v_and_b32_sdwa v69, v94, v150 dst_sel:DWORD dst_unused:UNUSED_PAD src0_sel:WORD_1 src1_sel:DWORD
	v_add3_u32 v75, v95, v75, s82
	v_add3_u32 v69, v94, v69, s82
	v_and_b32_e32 v75, 0xffff0000, v75
	v_pk_fma_f32 v[86:87], v[142:143], v[86:87], v[82:83] op_sel:[1,0,0]
	v_pk_fma_f32 v[142:143], v[120:121], v[76:77], v[20:21]
	v_or_b32_sdwa v75, v75, v69 dst_sel:DWORD dst_unused:UNUSED_PAD src0_sel:DWORD src1_sel:WORD_1
	v_mov_b32_e32 v69, 0
	v_cvt_pk_fp8_f32 v69, v142, v143
	v_and_b32_sdwa v76, v143, v150 dst_sel:DWORD dst_unused:UNUSED_PAD src0_sel:WORD_1 src1_sel:DWORD
	v_and_b32_sdwa v74, v142, v150 dst_sel:DWORD dst_unused:UNUSED_PAD src0_sel:WORD_1 src1_sel:DWORD
	v_add3_u32 v76, v143, v76, s82
	v_cvt_pk_fp8_f32 v69, v94, v95 op_sel:[0,0,1]
	v_add3_u32 v74, v142, v74, s82
	v_and_b32_e32 v76, 0xffff0000, v76
	v_or_b32_sdwa v74, v76, v74 dst_sel:DWORD dst_unused:UNUSED_PAD src0_sel:DWORD src1_sel:WORD_1
	global_store_dwordx2 v[78:79], v[74:75], off offset:2560 sc1
	global_store_dword v[72:73], v69, off offset:1280
	ds_read_b128 v[74:77], v146 offset:5120
	ds_read_b128 v[82:85], v146 offset:37888
	v_pk_mul_f32 v[70:71], v[70:71], v[68:69] op_sel_hi:[1,0]
	s_waitcnt lgkmcnt(1)
	v_pk_fma_f32 v[86:87], v[142:143], v[74:75], v[86:87] op_sel_hi:[0,1,1]
	v_pk_fma_f32 v[88:89], v[142:143], v[76:77], v[88:89] op_sel_hi:[0,1,1]
	s_waitcnt lgkmcnt(0)
	v_pk_fma_f32 v[90:91], v[142:143], v[82:83], v[90:91] op_sel_hi:[0,1,1]
	v_pk_fma_f32 v[92:93], v[142:143], v[84:85], v[92:93] op_sel_hi:[0,1,1]
	ds_read_b128 v[74:77], v146 offset:13312
	ds_read_b128 v[82:85], v146 offset:46080
	s_waitcnt vmcnt(13)
	v_pk_fma_f32 v[70:71], v[122:123], v[70:71], v[26:27]
	s_waitcnt lgkmcnt(1)
	v_pk_fma_f32 v[88:89], v[142:143], v[76:77], v[88:89] op_sel:[1,0,0]
	v_pk_fma_f32 v[86:87], v[142:143], v[74:75], v[86:87] op_sel:[1,0,0]
	s_waitcnt lgkmcnt(0)
	v_pk_fma_f32 v[92:93], v[142:143], v[84:85], v[92:93] op_sel:[1,0,0]
	v_pk_fma_f32 v[90:91], v[142:143], v[82:83], v[90:91] op_sel:[1,0,0]
	ds_read_b128 v[74:77], v146 offset:21504
	ds_read_b128 v[82:85], v146 offset:54272
	s_waitcnt lgkmcnt(1)
	v_pk_fma_f32 v[86:87], v[94:95], v[74:75], v[86:87] op_sel_hi:[0,1,1]
	v_pk_fma_f32 v[88:89], v[94:95], v[76:77], v[88:89] op_sel_hi:[0,1,1]
	s_waitcnt lgkmcnt(0)
	v_pk_fma_f32 v[90:91], v[94:95], v[82:83], v[90:91] op_sel_hi:[0,1,1]
	v_pk_fma_f32 v[92:93], v[94:95], v[84:85], v[92:93] op_sel_hi:[0,1,1]
	ds_read_b128 v[74:77], v146 offset:29696
	ds_read_b128 v[82:85], v146 offset:62464
	s_waitcnt lgkmcnt(1)
	v_pk_fma_f32 v[86:87], v[94:95], v[74:75], v[86:87] op_sel:[1,0,0]
	v_pk_mul_f32 v[74:75], v[80:81], v[68:69] op_sel_hi:[1,0]
	s_waitcnt lgkmcnt(0)
	v_pk_fma_f32 v[84:85], v[94:95], v[84:85], v[92:93] op_sel:[1,0,0]
	v_pk_fma_f32 v[92:93], v[124:125], v[74:75], v[24:25]
	v_and_b32_sdwa v75, v71, v150 dst_sel:DWORD dst_unused:UNUSED_PAD src0_sel:WORD_1 src1_sel:DWORD
	v_and_b32_sdwa v69, v70, v150 dst_sel:DWORD dst_unused:UNUSED_PAD src0_sel:WORD_1 src1_sel:DWORD
	v_add3_u32 v75, v71, v75, s82
	v_add3_u32 v69, v70, v69, s82
	v_and_b32_e32 v75, 0xffff0000, v75
	v_or_b32_sdwa v75, v75, v69 dst_sel:DWORD dst_unused:UNUSED_PAD src0_sel:DWORD src1_sel:WORD_1
	v_mov_b32_e32 v69, 0
	v_cvt_pk_fp8_f32 v69, v92, v93
	v_pk_fma_f32 v[88:89], v[94:95], v[76:77], v[88:89] op_sel:[1,0,0]
	v_and_b32_sdwa v76, v93, v150 dst_sel:DWORD dst_unused:UNUSED_PAD src0_sel:WORD_1 src1_sel:DWORD
	v_and_b32_sdwa v74, v92, v150 dst_sel:DWORD dst_unused:UNUSED_PAD src0_sel:WORD_1 src1_sel:DWORD
	v_cvt_pk_fp8_f32 v69, v70, v71 op_sel:[0,0,1]
	v_add3_u32 v76, v93, v76, s82
	v_add3_u32 v74, v92, v74, s82
	v_and_b32_e32 v76, 0xffff0000, v76
	v_or_b32_sdwa v74, v76, v74 dst_sel:DWORD dst_unused:UNUSED_PAD src0_sel:DWORD src1_sel:WORD_1
	global_store_dwordx2 v[78:79], v[74:75], off offset:3072 sc1
	global_store_dword v[72:73], v69, off offset:1536
	v_pk_fma_f32 v[90:91], v[94:95], v[82:83], v[90:91] op_sel:[1,0,0]
	ds_read_b128 v[74:77], v146 offset:6144
	ds_read_b128 v[80:83], v146 offset:38912
	v_pk_mul_f32 v[64:65], v[64:65], v[68:69] op_sel_hi:[1,0]
	v_pk_mul_f32 v[66:67], v[66:67], v[68:69] op_sel_hi:[1,0]
	s_waitcnt lgkmcnt(1)
	v_pk_fma_f32 v[86:87], v[92:93], v[74:75], v[86:87] op_sel_hi:[0,1,1]
	v_pk_fma_f32 v[88:89], v[92:93], v[76:77], v[88:89] op_sel_hi:[0,1,1]
	s_waitcnt lgkmcnt(0)
	v_pk_fma_f32 v[90:91], v[92:93], v[80:81], v[90:91] op_sel_hi:[0,1,1]
	v_pk_fma_f32 v[84:85], v[92:93], v[82:83], v[84:85] op_sel_hi:[0,1,1]
	ds_read_b128 v[74:77], v146 offset:14336
	ds_read_b128 v[80:83], v146 offset:47104
	s_waitcnt lgkmcnt(1)
	v_pk_fma_f32 v[88:89], v[92:93], v[76:77], v[88:89] op_sel:[1,0,0]
	v_pk_fma_f32 v[86:87], v[92:93], v[74:75], v[86:87] op_sel:[1,0,0]
	s_waitcnt lgkmcnt(0)
	v_pk_fma_f32 v[84:85], v[92:93], v[82:83], v[84:85] op_sel:[1,0,0]
	v_pk_fma_f32 v[90:91], v[92:93], v[80:81], v[90:91] op_sel:[1,0,0]
	ds_read_b128 v[74:77], v146 offset:22528
	ds_read_b128 v[80:83], v146 offset:55296
	s_waitcnt lgkmcnt(1)
	v_pk_fma_f32 v[86:87], v[70:71], v[74:75], v[86:87] op_sel_hi:[0,1,1]
	v_pk_fma_f32 v[88:89], v[70:71], v[76:77], v[88:89] op_sel_hi:[0,1,1]
	s_waitcnt lgkmcnt(0)
	v_pk_fma_f32 v[90:91], v[70:71], v[80:81], v[90:91] op_sel_hi:[0,1,1]
	v_pk_fma_f32 v[84:85], v[70:71], v[82:83], v[84:85] op_sel_hi:[0,1,1]
	ds_read_b128 v[74:77], v146 offset:30720
	ds_read_b128 v[80:83], v146 offset:63488
	s_waitcnt lgkmcnt(1)
	v_pk_fma_f32 v[74:75], v[70:71], v[74:75], v[86:87] op_sel:[1,0,0]
	s_waitcnt vmcnt(14)
	v_pk_fma_f32 v[86:87], v[128:129], v[64:65], v[28:29]
	s_waitcnt lgkmcnt(0)
	v_pk_fma_f32 v[82:83], v[70:71], v[82:83], v[84:85] op_sel:[1,0,0]
	v_pk_fma_f32 v[84:85], v[126:127], v[66:67], v[30:31]
	v_and_b32_sdwa v65, v86, v150 dst_sel:DWORD dst_unused:UNUSED_PAD src0_sel:WORD_1 src1_sel:DWORD
	v_add3_u32 v66, v86, v65, s82
	v_and_b32_sdwa v65, v85, v150 dst_sel:DWORD dst_unused:UNUSED_PAD src0_sel:WORD_1 src1_sel:DWORD
	v_and_b32_sdwa v67, v87, v150 dst_sel:DWORD dst_unused:UNUSED_PAD src0_sel:WORD_1 src1_sel:DWORD
	v_and_b32_sdwa v64, v84, v150 dst_sel:DWORD dst_unused:UNUSED_PAD src0_sel:WORD_1 src1_sel:DWORD
	v_add3_u32 v65, v85, v65, s82
	v_add3_u32 v67, v87, v67, s82
	v_add3_u32 v64, v84, v64, s82
	v_and_b32_e32 v65, 0xffff0000, v65
	v_and_b32_e32 v67, 0xffff0000, v67
	v_or_b32_sdwa v65, v65, v64 dst_sel:DWORD dst_unused:UNUSED_PAD src0_sel:DWORD src1_sel:WORD_1
	v_or_b32_sdwa v64, v67, v66 dst_sel:DWORD dst_unused:UNUSED_PAD src0_sel:DWORD src1_sel:WORD_1
	global_store_dwordx2 v[78:79], v[64:65], off offset:3584 sc1
	v_mov_b32_e32 v64, 0
	v_cvt_pk_fp8_f32 v64, v86, v87
	v_pk_fma_f32 v[76:77], v[70:71], v[76:77], v[88:89] op_sel:[1,0,0]
	v_pk_fma_f32 v[80:81], v[70:71], v[80:81], v[90:91] op_sel:[1,0,0]
	v_cvt_pk_fp8_f32 v64, v84, v85 op_sel:[0,0,1]
	global_store_dword v[72:73], v64, off offset:1792
	ds_read_b128 v[64:67], v146 offset:7168
	ds_read_b128 v[68:71], v146 offset:39936
	s_waitcnt lgkmcnt(1)
	v_pk_fma_f32 v[72:73], v[86:87], v[64:65], v[74:75] op_sel_hi:[0,1,1]
	v_pk_fma_f32 v[74:75], v[86:87], v[66:67], v[76:77] op_sel_hi:[0,1,1]
	s_waitcnt lgkmcnt(0)
	v_pk_fma_f32 v[76:77], v[86:87], v[68:69], v[80:81] op_sel_hi:[0,1,1]
	v_pk_fma_f32 v[78:79], v[86:87], v[70:71], v[82:83] op_sel_hi:[0,1,1]
	ds_read_b128 v[64:67], v146 offset:15360
	ds_read_b128 v[68:71], v146 offset:48128
	s_waitcnt lgkmcnt(1)
	v_pk_fma_f32 v[74:75], v[86:87], v[66:67], v[74:75] op_sel:[1,0,0]
	v_pk_fma_f32 v[72:73], v[86:87], v[64:65], v[72:73] op_sel:[1,0,0]
	s_waitcnt lgkmcnt(0)
	v_pk_fma_f32 v[78:79], v[86:87], v[70:71], v[78:79] op_sel:[1,0,0]
	v_pk_fma_f32 v[76:77], v[86:87], v[68:69], v[76:77] op_sel:[1,0,0]
	ds_read_b128 v[64:67], v146 offset:23552
	ds_read_b128 v[68:71], v146 offset:56320
	s_waitcnt lgkmcnt(1)
	v_pk_fma_f32 v[72:73], v[84:85], v[64:65], v[72:73] op_sel_hi:[0,1,1]
	v_pk_fma_f32 v[74:75], v[84:85], v[66:67], v[74:75] op_sel_hi:[0,1,1]
	s_waitcnt lgkmcnt(0)
	v_pk_fma_f32 v[76:77], v[84:85], v[68:69], v[76:77] op_sel_hi:[0,1,1]
	v_pk_fma_f32 v[78:79], v[84:85], v[70:71], v[78:79] op_sel_hi:[0,1,1]
	ds_read_b128 v[64:67], v146 offset:31744
	ds_read_b128 v[68:71], v146 offset:64512
	s_waitcnt lgkmcnt(1)
	v_pk_fma_f32 v[64:65], v[84:85], v[64:65], v[72:73] op_sel:[1,0,0]
	s_nop 1
	v_add_f32_dpp v64, v64, v64 quad_perm:[1,0,3,2] row_mask:0xf bank_mask:0xf bound_ctrl:1
	v_pk_fma_f32 v[66:67], v[84:85], v[66:67], v[74:75] op_sel:[1,0,0]
	s_waitcnt lgkmcnt(0)
	v_pk_fma_f32 v[68:69], v[84:85], v[68:69], v[76:77] op_sel:[1,0,0]
	v_add_f32_dpp v64, v64, v64 quad_perm:[2,3,0,1] row_mask:0xf bank_mask:0xf bound_ctrl:1
	v_pk_fma_f32 v[70:71], v[84:85], v[70:71], v[78:79] op_sel:[1,0,0]
	s_nop 0
	v_add_f32_dpp v64, v64, v64 row_half_mirror row_mask:0xf bank_mask:0xf bound_ctrl:1
	s_nop 1
	v_add_f32_dpp v64, v64, v64 row_mirror row_mask:0xf bank_mask:0xf bound_ctrl:1
	s_nop 0
	v_readlane_b32 s66, v64, 0
	v_readlane_b32 s39, v64, 16
	v_readlane_b32 s67, v64, 32
	v_readlane_b32 s86, v64, 48
	v_add_f32_dpp v64, v65, v65 quad_perm:[1,0,3,2] row_mask:0xf bank_mask:0xf bound_ctrl:1
	s_nop 1
	v_add_f32_dpp v64, v64, v64 quad_perm:[2,3,0,1] row_mask:0xf bank_mask:0xf bound_ctrl:1
	s_nop 1
	v_add_f32_dpp v64, v64, v64 row_half_mirror row_mask:0xf bank_mask:0xf bound_ctrl:1
	s_nop 1
	v_add_f32_dpp v64, v64, v64 row_mirror row_mask:0xf bank_mask:0xf bound_ctrl:1
	s_nop 0
	v_readlane_b32 s68, v64, 0
	v_readlane_b32 s87, v64, 16
	v_readlane_b32 s69, v64, 32
	v_readlane_b32 s88, v64, 48
	v_add_f32_dpp v64, v66, v66 quad_perm:[1,0,3,2] row_mask:0xf bank_mask:0xf bound_ctrl:1
	s_nop 1
	v_add_f32_dpp v64, v64, v64 quad_perm:[2,3,0,1] row_mask:0xf bank_mask:0xf bound_ctrl:1
	s_nop 1
	v_add_f32_dpp v64, v64, v64 row_half_mirror row_mask:0xf bank_mask:0xf bound_ctrl:1
	s_nop 1
	v_add_f32_dpp v64, v64, v64 row_mirror row_mask:0xf bank_mask:0xf bound_ctrl:1
	s_nop 0
	v_readlane_b32 s70, v64, 0
	v_readlane_b32 s89, v64, 16
	v_readlane_b32 s71, v64, 32
	v_readlane_b32 s90, v64, 48
	v_add_f32_dpp v64, v67, v67 quad_perm:[1,0,3,2] row_mask:0xf bank_mask:0xf bound_ctrl:1
	s_nop 1
	v_add_f32_dpp v64, v64, v64 quad_perm:[2,3,0,1] row_mask:0xf bank_mask:0xf bound_ctrl:1
	s_nop 1
	v_add_f32_dpp v64, v64, v64 row_half_mirror row_mask:0xf bank_mask:0xf bound_ctrl:1
	s_nop 1
	v_add_f32_dpp v64, v64, v64 row_mirror row_mask:0xf bank_mask:0xf bound_ctrl:1
	s_nop 0
	v_readlane_b32 s72, v64, 0
	v_readlane_b32 s91, v64, 16
	v_readlane_b32 s73, v64, 32
	v_readlane_b32 s92, v64, 48
	v_add_f32_dpp v64, v68, v68 quad_perm:[1,0,3,2] row_mask:0xf bank_mask:0xf bound_ctrl:1
	s_nop 1
	v_add_f32_dpp v64, v64, v64 quad_perm:[2,3,0,1] row_mask:0xf bank_mask:0xf bound_ctrl:1
	s_nop 1
	v_add_f32_dpp v64, v64, v64 row_half_mirror row_mask:0xf bank_mask:0xf bound_ctrl:1
	s_nop 1
	v_add_f32_dpp v64, v64, v64 row_mirror row_mask:0xf bank_mask:0xf bound_ctrl:1
	s_nop 0
	v_readlane_b32 s74, v64, 0
	v_readlane_b32 s93, v64, 16
	v_readlane_b32 s75, v64, 32
	v_readlane_b32 s94, v64, 48
	v_add_f32_dpp v64, v69, v69 quad_perm:[1,0,3,2] row_mask:0xf bank_mask:0xf bound_ctrl:1
	s_nop 1
	v_add_f32_dpp v64, v64, v64 quad_perm:[2,3,0,1] row_mask:0xf bank_mask:0xf bound_ctrl:1
	s_nop 1
	v_add_f32_dpp v64, v64, v64 row_half_mirror row_mask:0xf bank_mask:0xf bound_ctrl:1
	s_nop 1
	v_add_f32_dpp v64, v64, v64 row_mirror row_mask:0xf bank_mask:0xf bound_ctrl:1
	s_nop 0
	v_readlane_b32 s76, v64, 0
	v_readlane_b32 s95, v64, 16
	v_readlane_b32 s77, v64, 32
	v_readlane_b32 s96, v64, 48
	v_add_f32_dpp v64, v70, v70 quad_perm:[1,0,3,2] row_mask:0xf bank_mask:0xf bound_ctrl:1
	s_nop 1
	v_add_f32_dpp v64, v64, v64 quad_perm:[2,3,0,1] row_mask:0xf bank_mask:0xf bound_ctrl:1
	s_nop 1
	v_add_f32_dpp v64, v64, v64 row_half_mirror row_mask:0xf bank_mask:0xf bound_ctrl:1
	s_nop 1
	v_add_f32_dpp v64, v64, v64 row_mirror row_mask:0xf bank_mask:0xf bound_ctrl:1
	s_nop 0
	v_readlane_b32 s78, v64, 0
	v_readlane_b32 s97, v64, 16
	v_readlane_b32 s79, v64, 32
	v_readlane_b32 vcc_lo, v64, 48
	v_add_f32_dpp v64, v71, v71 quad_perm:[1,0,3,2] row_mask:0xf bank_mask:0xf bound_ctrl:1
	s_nop 1
	v_add_f32_dpp v64, v64, v64 quad_perm:[2,3,0,1] row_mask:0xf bank_mask:0xf bound_ctrl:1
	s_nop 1
	v_add_f32_dpp v64, v64, v64 row_half_mirror row_mask:0xf bank_mask:0xf bound_ctrl:1
	s_nop 1
	v_add_f32_dpp v64, v64, v64 row_mirror row_mask:0xf bank_mask:0xf bound_ctrl:1
	s_nop 0
	v_readlane_b32 s80, v64, 0
	v_readlane_b32 vcc_hi, v64, 16
	v_readlane_b32 s81, v64, 32
	v_readlane_b32 s33, v64, 48
	s_and_saveexec_b64 s[22:23], s[0:1]
	s_cbranch_execz .LBB0_150
	v_mov_b32_e32 v64, vcc_hi
	v_mov_b32_e32 v65, s33
	v_pk_add_f32 v[64:65], s[80:81], v[64:65]
	s_mov_b32 s24, 0xb2a5705f
	v_add_f32_e32 v66, v64, v65
	v_mov_b32_e32 v64, s39
	v_mov_b32_e32 v65, s86
	v_pk_add_f32 v[64:65], s[66:67], v[64:65]
	s_nop 0
	v_add_f32_e32 v67, v64, v65
	v_mov_b32_e32 v64, s87
	v_mov_b32_e32 v65, s88
	v_pk_add_f32 v[64:65], s[68:69], v[64:65]
	s_nop 0
	v_add_f32_e32 v68, v64, v65
	v_mov_b32_e32 v64, s89
	v_mov_b32_e32 v65, s90
	v_pk_add_f32 v[64:65], s[70:71], v[64:65]
	s_nop 0
	v_add_f32_e32 v69, v64, v65
	v_mov_b32_e32 v64, s91
	v_mov_b32_e32 v65, s92
	v_pk_add_f32 v[64:65], s[72:73], v[64:65]
	s_nop 0
	v_add_f32_e32 v70, v64, v65
	v_mov_b32_e32 v64, s93
	v_mov_b32_e32 v65, s94
	v_pk_add_f32 v[64:65], s[74:75], v[64:65]
	s_nop 0
	v_add_f32_e32 v71, v64, v65
	v_mov_b32_e32 v64, s95
	v_mov_b32_e32 v65, s96
	v_pk_add_f32 v[64:65], s[76:77], v[64:65]
	s_nop 0
	v_add_f32_e32 v72, v64, v65
	v_mov_b32_e32 v64, s97
	v_mov_b32_e32 v65, vcc_lo
	v_pk_add_f32 v[64:65], s[78:79], v[64:65]
	s_nop 0
	v_add_f32_e32 v64, v64, v65
	v_cndmask_b32_e64 v65, v67, v68, s[4:5]
	v_cndmask_b32_e64 v65, v65, v69, s[6:7]
	v_cndmask_b32_e64 v65, v65, v70, s[8:9]
	v_cndmask_b32_e64 v65, v65, v71, s[10:11]
	v_cndmask_b32_e64 v65, v65, v72, s[12:13]
	v_cndmask_b32_e64 v64, v65, v64, s[14:15]
	global_load_dword v65, v[104:105], off
	v_cndmask_b32_e64 v64, v64, v66, s[16:17]
	s_waitcnt vmcnt(0)
	v_add_f32_e32 v65, v64, v65
	v_mul_f32_e64 v66, |v65|, s83
	v_fma_f32 v67, |v65|, s83, -v66
	v_rndne_f32_e32 v68, v66
	v_fma_f32 v67, |v65|, s24, v67
	v_sub_f32_e32 v66, v66, v68
	v_add_f32_e32 v66, v66, v67
	v_exp_f32_e32 v66, v66
	v_cvt_i32_f32_e32 v67, v68
	s_mov_b32 s24, 0x42ce8ed0
	v_cmp_ngt_f32_e64 vcc, |v65|, s24
	s_mov_b32 s24, 0xc2b17218
	v_ldexp_f32 v66, v66, v67
	v_cndmask_b32_e32 v66, 0, v66, vcc
	v_cmp_nlt_f32_e64 vcc, |v65|, s24
	v_min_f32_e32 v64, 0, v65
	s_mov_b32 s24, 0x3f2aaaab
	v_cndmask_b32_e32 v65, v151, v66, vcc
	v_add_f32_e32 v68, 1.0, v65
	v_add_f32_e32 v66, -1.0, v68
	v_sub_f32_e32 v67, v66, v68
	v_add_f32_e32 v67, 1.0, v67
	v_sub_f32_e32 v66, v65, v66
	v_add_f32_e32 v69, v66, v67
	v_frexp_mant_f32_e32 v66, v68
	v_cmp_gt_f32_e32 vcc, s24, v66
	v_cvt_f64_f32_e32 v[66:67], v68
	v_frexp_exp_i32_f64_e32 v66, v[66:67]
	v_subbrev_co_u32_e32 v74, vcc, 0, v66, vcc
	v_sub_u32_e32 v66, 0, v74
	v_ldexp_f32 v67, v68, v66
	v_add_f32_e32 v68, -1.0, v67
	v_add_f32_e32 v70, 1.0, v67
	v_ldexp_f32 v66, v69, v66
	v_add_f32_e32 v69, 1.0, v68
	v_add_f32_e32 v71, -1.0, v70
	v_sub_f32_e32 v69, v67, v69
	v_sub_f32_e32 v67, v67, v71
	v_add_f32_e32 v69, v66, v69
	v_add_f32_e32 v66, v66, v67
	v_add_f32_e32 v75, v70, v66
	v_rcp_f32_e32 v77, v75
	v_sub_f32_e32 v67, v70, v75
	v_add_f32_e32 v76, v66, v67
	v_add_f32_e32 v67, v68, v69
	v_mul_f32_e32 v79, v67, v77
	v_sub_f32_e32 v66, v68, v67
	v_mul_f32_e32 v68, v75, v79
	v_fma_f32 v70, v79, v75, -v68
	v_fmac_f32_e32 v70, v79, v76
	v_add_f32_e32 v78, v69, v66
	v_add_f32_e32 v66, v68, v70
	v_sub_f32_e32 v69, v67, v66
	v_pk_add_f32 v[72:73], v[66:67], v[68:69] neg_lo:[0,1] neg_hi:[0,1]
	v_mov_b32_e32 v71, v66
	v_pk_add_f32 v[66:67], v[72:73], v[70:71] neg_lo:[0,1] neg_hi:[0,1]
	s_mov_b32 s24, 0x7f800000
	v_add_f32_e32 v67, v78, v67
	v_add_f32_e32 v66, v66, v67
	v_add_f32_e32 v67, v69, v66
	v_mul_f32_e32 v78, v77, v67
	v_mul_f32_e32 v68, v75, v78
	v_fma_f32 v70, v78, v75, -v68
	v_fmac_f32_e32 v70, v78, v76
	v_sub_f32_e32 v69, v69, v67
	v_add_f32_e32 v75, v66, v69
	v_add_f32_e32 v66, v68, v70
	v_sub_f32_e32 v69, v67, v66
	v_pk_add_f32 v[72:73], v[66:67], v[68:69] neg_lo:[0,1] neg_hi:[0,1]
	v_mov_b32_e32 v71, v66
	v_pk_add_f32 v[66:67], v[72:73], v[70:71] neg_lo:[0,1] neg_hi:[0,1]
	v_cmp_neq_f32_e32 vcc, s24, v65
	v_add_f32_e32 v67, v75, v67
	v_add_f32_e32 v66, v66, v67
	v_add_f32_e32 v67, v79, v78
	v_add_f32_e32 v66, v69, v66
	v_sub_f32_e32 v68, v67, v79
	v_mul_f32_e32 v66, v77, v66
	v_sub_f32_e32 v68, v78, v68
	v_add_f32_e32 v68, v68, v66
	v_add_f32_e32 v70, v67, v68
	v_mul_f32_e32 v71, v70, v70
	v_fmamk_f32 v66, v71, 0x3e9b6dac, v149
	v_fmaak_f32 v139, v71, v66, 0x3f2aaada
	v_cvt_f32_i32_e32 v66, v74
	v_sub_f32_e32 v67, v70, v67
	v_sub_f32_e32 v67, v68, v67
	v_ldexp_f32 v72, v67, 1
	v_mul_f32_e32 v67, v70, v71
	v_ldexp_f32 v69, v70, 1
	v_pk_mul_f32 v[70:71], v[66:67], v[138:139]
	s_nop 0
	v_fma_f32 v68, v66, s84, -v70
	v_fmac_f32_e32 v68, 0xb102e308, v66
	v_pk_add_f32 v[66:67], v[70:71], v[68:69]
	s_nop 0
	v_sub_f32_e32 v69, v67, v69
	v_sub_f32_e32 v69, v71, v69
	v_add_f32_e32 v73, v72, v69
	v_mov_b32_e32 v72, v70
	v_pk_add_f32 v[70:71], v[66:67], v[70:71] neg_lo:[0,1] neg_hi:[0,1]
	v_pk_add_f32 v[74:75], v[66:67], v[72:73]
	v_mov_b32_e32 v69, v66
	v_mov_b32_e32 v71, v75
	v_pk_add_f32 v[76:77], v[68:69], v[70:71] neg_lo:[0,1] neg_hi:[0,1]
	v_pk_add_f32 v[68:69], v[68:69], v[70:71]
	v_mov_b32_e32 v72, v73
	v_pk_add_f32 v[70:71], v[68:69], v[66:67] op_sel:[1,0] op_sel_hi:[0,1] neg_lo:[0,1] neg_hi:[0,1]
	v_pk_add_f32 v[78:79], v[74:75], v[70:71] op_sel_hi:[1,0] neg_lo:[0,1] neg_hi:[0,1]
	v_mov_b32_e32 v74, v75
	v_mov_b32_e32 v75, v69
	v_pk_mov_b32 v[70:71], v[66:67], v[70:71] op_sel:[1,0]
	v_mov_b32_e32 v73, v66
	v_pk_add_f32 v[70:71], v[74:75], v[70:71] neg_lo:[0,1] neg_hi:[0,1]
	v_mov_b32_e32 v78, v76
	v_pk_add_f32 v[66:67], v[72:73], v[70:71] neg_lo:[0,1] neg_hi:[0,1]
	v_mov_b32_e32 v77, v69
	v_pk_add_f32 v[70:71], v[78:79], v[66:67]
	s_nop 0
	v_pk_add_f32 v[72:73], v[70:71], v[70:71] op_sel:[0,1] op_sel_hi:[1,0]
	s_nop 0
	v_pk_add_f32 v[68:69], v[68:69], v[72:73] op_sel:[1,0] op_sel_hi:[0,1]
	v_mov_b32_e32 v71, v68
	v_pk_add_f32 v[74:75], v[70:71], v[76:77] neg_lo:[0,1] neg_hi:[0,1]
	v_mov_b32_e32 v67, v72
	v_sub_f32_e32 v69, v70, v74
	v_pk_add_f32 v[66:67], v[66:67], v[74:75] neg_lo:[0,1] neg_hi:[0,1]
	v_sub_f32_e32 v69, v76, v69
	v_add_f32_e32 v66, v66, v69
	v_add_f32_e32 v66, v66, v67
	v_add_f32_e32 v66, v68, v66
	v_cndmask_b32_e32 v66, v151, v66, vcc
	v_cmp_lt_f32_e64 vcc, |v65|, s85
	s_nop 1
	v_cndmask_b32_e32 v65, v66, v65, vcc
	v_sub_f32_e32 v66, v64, v65
	v_add_u32_e32 v64, v147, v96
	v_ashrrev_i32_e32 v65, 31, v64
	v_lshl_add_u64 v[64:65], v[64:65], 2, s[42:43]
	global_store_dword v[64:65], v66, off
	s_branch .LBB0_150

.LBB0_221:
	s_or_b64 exec, exec, s[4:5]
	s_lshl_b64 s[0:1], s[0:1], 13
	s_lshl_b64 s[0:1], s[0:1], 2
	s_add_u32 s0, s54, s0
	s_addc_u32 s1, s55, s1
	v_lshlrev_b32_e32 v18, 2, v10
	v_mov_b32_e32 v19, 0
	v_lshl_add_u64 v[20:21], s[0:1], 0, v[18:19]
	s_mov_b64 s[0:1], 0x50000
	v_mov_b32_e32 v24, v11
	v_lshl_add_u64 v[22:23], v[20:21], 0, s[0:1]
	v_pk_add_f32 v[0:1], v[0:1], v[24:25] op_sel_hi:[1,0]
	v_pk_add_f32 v[16:17], v[16:17], v[24:25] op_sel_hi:[1,0]
	s_mov_b32 s0, 0xbfb8aa3b
	v_pk_mul_f32 v[18:19], v[16:17], s[0:1] op_sel_hi:[1,0]
	v_pk_mul_f32 v[16:17], v[0:1], s[0:1] op_sel_hi:[1,0]
	s_mov_b32 s1, 0x50000
	v_add_co_u32_e32 v0, vcc, s1, v20
	v_pk_add_f32 v[12:13], v[12:13], v[24:25] op_sel_hi:[1,0]
	s_nop 0
	v_addc_co_u32_e32 v1, vcc, 0, v21, vcc
	global_store_dwordx4 v[0:1], v[16:19], off sc1
	v_pk_add_f32 v[0:1], v[14:15], v[24:25] op_sel_hi:[1,0]
	v_pk_mul_f32 v[14:15], v[12:13], s[0:1] op_sel_hi:[1,0]
	v_pk_mul_f32 v[12:13], v[0:1], s[0:1] op_sel_hi:[1,0]
	v_pk_add_f32 v[0:1], v[8:9], v[24:25] op_sel_hi:[1,0]
	v_pk_add_f32 v[6:7], v[6:7], v[24:25] op_sel_hi:[1,0]
	v_pk_add_f32 v[2:3], v[2:3], v[24:25] op_sel_hi:[1,0]
	v_pk_mul_f32 v[8:9], v[6:7], s[0:1] op_sel_hi:[1,0]
	v_pk_mul_f32 v[6:7], v[0:1], s[0:1] op_sel_hi:[1,0]
	v_pk_add_f32 v[0:1], v[4:5], v[24:25] op_sel_hi:[1,0]
	v_pk_mul_f32 v[2:3], v[2:3], s[0:1] op_sel_hi:[1,0]
	v_pk_mul_f32 v[0:1], v[0:1], s[0:1] op_sel_hi:[1,0]
	global_store_dwordx4 v[22:23], v[12:15], off offset:16 sc1
	global_store_dwordx4 v[22:23], v[6:9], off offset:32 sc1
	global_store_dwordx4 v[22:23], v[0:3], off offset:48 sc1
	s_barrier
	s_branch .LBB0_224

.LBB0_253:
	v_lshl_or_b32 v120, s4, 8, v167
	v_add_u32_e32 v177, s5, v120
	s_lshl_b32 s4, -1, s6
	s_xor_b64 s[24:25], s[66:67], -1
	s_not_b32 s15, s4
	v_ashrrev_i32_e32 v120, s6, v177
	s_and_b64 s[4:5], s[46:47], exec
	v_ashrrev_i32_e32 v121, 31, v120
	s_cselect_b32 s15, -1, s15
	s_lshl_b64 s[4:5], s[64:65], 1
	v_lshlrev_b64 v[120:121], 13, v[120:121]
	v_lshl_add_u32 v178, s42, 8, v164
	s_add_u32 s42, s74, s4
	v_cndmask_b32_e64 v120, v120, 0, s[46:47]
	v_cndmask_b32_e64 v121, v121, 0, s[46:47]
	s_addc_u32 s43, s75, s5
	v_mul_lo_u32 v123, v121, s62
	v_mul_lo_u32 v124, v120, s63
	v_mad_u64_u32 v[120:121], s[4:5], v120, s62, 0
	v_and_b32_e32 v122, s15, v177
	v_add3_u32 v121, v121, v124, v123
	v_lshl_add_u64 v[120:121], v[120:121], 1, s[42:43]
	v_ashrrev_i32_e32 v123, 31, v122
	v_ashrrev_i32_e32 v124, 31, v178
	v_lshl_add_u64 v[154:155], v[122:123], 1, v[120:121]
	v_cvt_pk_bf16_f32 v120, v128, v129
	v_cvt_pk_bf16_f32 v121, v130, v131
	v_mul_lo_u32 v130, s62, v124
	v_mul_lo_u32 v124, s63, v178
	v_mad_u64_u32 v[128:129], s[4:5], s62, v178, 0
	v_add3_u32 v129, v129, v130, v124
	v_lshl_add_u64 v[124:125], v[128:129], 1, v[154:155]
	v_cvt_pk_bf16_f32 v122, v132, v133
	v_cvt_pk_bf16_f32 v123, v134, v135
	global_store_dwordx4 v[124:125], v[120:123], off sc1
	s_andn2_b64 vcc, exec, s[24:25]
	s_mov_b64 s[64:65], -1
	v_cndmask_b32_e64 v120, 0, 1, s[24:25]
	v_cmp_ne_u32_e64 s[4:5], 1, v120
	s_cbranch_vccnz .LBB0_255
	v_mul_f32_e32 v120, 0xbfb8aa3b, v116
	v_exp_f32_e32 v120, v120
	v_mul_f32_e32 v121, 0xbfb8aa3b, v112
	v_exp_f32_e32 v121, v121
	s_mov_b64 s[64:65], 0
	v_add_f32_e32 v120, 1.0, v120
	v_rcp_f32_e32 v124, v120
	v_add_f32_e32 v121, 1.0, v121
	v_rcp_f32_e32 v125, v121
	v_mov_b64_e32 v[122:123], v[118:119]
	v_mov_b64_e32 v[120:121], v[116:117]
	v_mul_f32_e32 v120, v116, v124
	v_cndmask_b32_e64 v120, v124, v120, s[40:41]
	v_mul_f32_e32 v124, 0xbfb8aa3b, v117
	v_exp_f32_e32 v131, v124
	v_mul_f32_e32 v124, 0xbfb8aa3b, v113
	v_mul_f32_e32 v121, v112, v125
	v_exp_f32_e32 v132, v124
	v_cndmask_b32_e64 v121, v125, v121, s[40:41]
	v_mov_b64_e32 v[126:127], v[114:115]
	v_mov_b64_e32 v[124:125], v[112:113]
	v_add_f32_e32 v124, 1.0, v131
	v_cndmask_b32_e64 v122, v122, v118, s[38:39]
	v_rcp_f32_e32 v125, v124
	v_add_f32_e32 v124, 1.0, v132
	v_mul_f32_e32 v132, 0xbfb8aa3b, v122
	v_exp_f32_e32 v132, v132
	v_cndmask_b32_e64 v126, v126, v114, s[38:39]
	v_rcp_f32_e32 v131, v124
	v_mul_f32_e32 v133, 0xbfb8aa3b, v126
	v_add_f32_e32 v132, 1.0, v132
	v_rcp_f32_e32 v132, v132
	v_exp_f32_e32 v133, v133
	v_mov_b32_e32 v124, v121
	v_mul_f32_e32 v121, v117, v125
	v_cndmask_b32_e64 v121, v125, v121, s[40:41]
	v_mul_f32_e32 v125, v113, v131
	v_mul_f32_e32 v122, v122, v132
	v_cndmask_b32_e64 v123, v123, v119, s[38:39]
	v_cndmask_b32_e64 v127, v127, v115, s[38:39]
	v_cndmask_b32_e64 v125, v131, v125, s[40:41]
	v_add_f32_e32 v131, 1.0, v133
	v_cndmask_b32_e64 v122, v132, v122, s[40:41]
	v_mul_f32_e32 v132, 0xbfb8aa3b, v123
	v_mul_f32_e32 v133, 0xbfb8aa3b, v127
	v_exp_f32_e32 v132, v132
	v_exp_f32_e32 v133, v133
	v_rcp_f32_e32 v131, v131
	v_add_f32_e32 v132, 1.0, v132
	v_add_f32_e32 v133, 1.0, v133
	v_rcp_f32_e32 v132, v132
	v_rcp_f32_e32 v133, v133
	v_mul_f32_e32 v126, v126, v131
	v_cndmask_b32_e64 v126, v131, v126, s[40:41]
	v_mul_f32_e32 v123, v123, v132
	v_mul_f32_e32 v127, v127, v133
	v_cndmask_b32_e64 v123, v132, v123, s[40:41]
	v_cndmask_b32_e64 v127, v133, v127, s[40:41]

.LBB0_257:
	v_or_b32_e32 v116, 16, v178
	v_cvt_pk_bf16_f32 v112, v120, v121
	v_mul_lo_u32 v117, s63, v116
	v_mad_u64_u32 v[120:121], s[24:25], s62, v116, 0
	v_add3_u32 v121, v121, v130, v117
	v_cvt_pk_bf16_f32 v113, v122, v123
	v_cvt_pk_bf16_f32 v114, v124, v125
	v_cvt_pk_bf16_f32 v115, v126, v127
	v_lshl_add_u64 v[116:117], v[120:121], 1, v[154:155]
	s_and_b64 vcc, exec, s[4:5]
	s_mov_b64 s[64:65], -1
	global_store_dwordx4 v[116:117], v[112:115], off sc1
	s_cbranch_vccnz .LBB0_259
	s_nop 0
	v_mul_f32_e32 v112, 0xbfb8aa3b, v108
	v_exp_f32_e32 v112, v112
	v_mul_f32_e32 v113, 0xbfb8aa3b, v104
	v_exp_f32_e32 v113, v113
	s_mov_b64 s[64:65], 0
	v_add_f32_e32 v112, 1.0, v112
	v_rcp_f32_e32 v116, v112
	v_add_f32_e32 v113, 1.0, v113
	v_rcp_f32_e32 v117, v113
	v_mov_b64_e32 v[114:115], v[110:111]
	v_mov_b64_e32 v[112:113], v[108:109]
	v_mul_f32_e32 v112, v108, v116
	v_cndmask_b32_e64 v112, v116, v112, s[40:41]
	v_mul_f32_e32 v116, 0xbfb8aa3b, v109
	v_exp_f32_e32 v122, v116
	v_mul_f32_e32 v116, 0xbfb8aa3b, v105
	v_mul_f32_e32 v113, v104, v117
	v_exp_f32_e32 v123, v116
	v_cndmask_b32_e64 v113, v117, v113, s[40:41]
	v_mov_b64_e32 v[118:119], v[106:107]
	v_mov_b64_e32 v[116:117], v[104:105]
	v_add_f32_e32 v116, 1.0, v122
	v_cndmask_b32_e64 v114, v114, v110, s[38:39]
	v_rcp_f32_e32 v117, v116
	v_add_f32_e32 v116, 1.0, v123
	v_mul_f32_e32 v123, 0xbfb8aa3b, v114
	v_exp_f32_e32 v123, v123
	v_cndmask_b32_e64 v118, v118, v106, s[38:39]
	v_rcp_f32_e32 v122, v116
	v_mul_f32_e32 v124, 0xbfb8aa3b, v118
	v_add_f32_e32 v123, 1.0, v123
	v_rcp_f32_e32 v123, v123
	v_exp_f32_e32 v124, v124
	v_mov_b32_e32 v116, v113
	v_mul_f32_e32 v113, v109, v117
	v_cndmask_b32_e64 v113, v117, v113, s[40:41]
	v_mul_f32_e32 v117, v105, v122
	v_mul_f32_e32 v114, v114, v123
	v_cndmask_b32_e64 v115, v115, v111, s[38:39]
	v_cndmask_b32_e64 v119, v119, v107, s[38:39]
	v_cndmask_b32_e64 v117, v122, v117, s[40:41]
	v_add_f32_e32 v122, 1.0, v124
	v_cndmask_b32_e64 v114, v123, v114, s[40:41]
	v_mul_f32_e32 v123, 0xbfb8aa3b, v115
	v_mul_f32_e32 v124, 0xbfb8aa3b, v119
	v_exp_f32_e32 v123, v123
	v_exp_f32_e32 v124, v124
	v_rcp_f32_e32 v122, v122
	v_add_f32_e32 v123, 1.0, v123
	v_add_f32_e32 v124, 1.0, v124
	v_rcp_f32_e32 v123, v123
	v_rcp_f32_e32 v124, v124
	v_mul_f32_e32 v118, v118, v122
	v_cndmask_b32_e64 v118, v122, v118, s[40:41]
	v_mul_f32_e32 v115, v115, v123
	v_mul_f32_e32 v119, v119, v124
	v_cndmask_b32_e64 v115, v123, v115, s[40:41]
	v_cndmask_b32_e64 v119, v124, v119, s[40:41]

.LBB0_261:
	v_or_b32_e32 v108, 32, v178
	v_cvt_pk_bf16_f32 v104, v112, v113
	v_mul_lo_u32 v109, s63, v108
	v_mad_u64_u32 v[112:113], s[24:25], s62, v108, 0
	v_add3_u32 v113, v113, v130, v109
	v_cvt_pk_bf16_f32 v105, v114, v115
	v_cvt_pk_bf16_f32 v106, v116, v117
	v_cvt_pk_bf16_f32 v107, v118, v119
	v_lshl_add_u64 v[108:109], v[112:113], 1, v[154:155]
	s_and_b64 vcc, exec, s[4:5]
	s_mov_b64 s[64:65], -1
	global_store_dwordx4 v[108:109], v[104:107], off sc1
	s_cbranch_vccnz .LBB0_263
	s_nop 0
	v_mul_f32_e32 v104, 0xbfb8aa3b, v100
	v_exp_f32_e32 v104, v104
	v_mul_f32_e32 v105, 0xbfb8aa3b, v96
	v_exp_f32_e32 v105, v105
	s_mov_b64 s[64:65], 0
	v_add_f32_e32 v104, 1.0, v104
	v_rcp_f32_e32 v108, v104
	v_add_f32_e32 v105, 1.0, v105
	v_rcp_f32_e32 v109, v105
	v_mov_b64_e32 v[106:107], v[102:103]
	v_mov_b64_e32 v[104:105], v[100:101]
	v_mul_f32_e32 v104, v100, v108
	v_cndmask_b32_e64 v104, v108, v104, s[40:41]
	v_mul_f32_e32 v108, 0xbfb8aa3b, v101
	v_exp_f32_e32 v114, v108
	v_mul_f32_e32 v108, 0xbfb8aa3b, v97
	v_mul_f32_e32 v105, v96, v109
	v_exp_f32_e32 v115, v108
	v_cndmask_b32_e64 v105, v109, v105, s[40:41]
	v_mov_b64_e32 v[110:111], v[98:99]
	v_mov_b64_e32 v[108:109], v[96:97]
	v_add_f32_e32 v108, 1.0, v114
	v_cndmask_b32_e64 v106, v106, v102, s[38:39]
	v_rcp_f32_e32 v109, v108
	v_add_f32_e32 v108, 1.0, v115
	v_mul_f32_e32 v115, 0xbfb8aa3b, v106
	v_exp_f32_e32 v115, v115
	v_cndmask_b32_e64 v110, v110, v98, s[38:39]
	v_rcp_f32_e32 v114, v108
	v_mul_f32_e32 v116, 0xbfb8aa3b, v110
	v_add_f32_e32 v115, 1.0, v115
	v_rcp_f32_e32 v115, v115
	v_exp_f32_e32 v116, v116
	v_mov_b32_e32 v108, v105
	v_mul_f32_e32 v105, v101, v109
	v_cndmask_b32_e64 v105, v109, v105, s[40:41]
	v_mul_f32_e32 v109, v97, v114
	v_mul_f32_e32 v106, v106, v115
	v_cndmask_b32_e64 v107, v107, v103, s[38:39]
	v_cndmask_b32_e64 v111, v111, v99, s[38:39]
	v_cndmask_b32_e64 v109, v114, v109, s[40:41]
	v_add_f32_e32 v114, 1.0, v116
	v_cndmask_b32_e64 v106, v115, v106, s[40:41]
	v_mul_f32_e32 v115, 0xbfb8aa3b, v107
	v_mul_f32_e32 v116, 0xbfb8aa3b, v111
	v_exp_f32_e32 v115, v115
	v_exp_f32_e32 v116, v116
	v_rcp_f32_e32 v114, v114
	v_add_f32_e32 v115, 1.0, v115
	v_add_f32_e32 v116, 1.0, v116
	v_rcp_f32_e32 v115, v115
	v_rcp_f32_e32 v116, v116
	v_mul_f32_e32 v110, v110, v114
	v_cndmask_b32_e64 v110, v114, v110, s[40:41]
	v_mul_f32_e32 v107, v107, v115
	v_mul_f32_e32 v111, v111, v116
	v_cndmask_b32_e64 v107, v115, v107, s[40:41]
	v_cndmask_b32_e64 v111, v116, v111, s[40:41]

.LBB0_265:
	v_or_b32_e32 v100, 48, v178
	v_cvt_pk_bf16_f32 v96, v104, v105
	v_mul_lo_u32 v101, s63, v100
	v_mad_u64_u32 v[104:105], s[24:25], s62, v100, 0
	v_add3_u32 v105, v105, v130, v101
	v_cvt_pk_bf16_f32 v97, v106, v107
	v_cvt_pk_bf16_f32 v98, v108, v109
	v_cvt_pk_bf16_f32 v99, v110, v111
	v_lshl_add_u64 v[100:101], v[104:105], 1, v[154:155]
	s_and_b64 vcc, exec, s[4:5]
	s_mov_b64 s[64:65], -1
	global_store_dwordx4 v[100:101], v[96:99], off sc1
	s_cbranch_vccnz .LBB0_267
	s_nop 0
	v_mul_f32_e32 v96, 0xbfb8aa3b, v92
	v_exp_f32_e32 v96, v96
	v_mul_f32_e32 v97, 0xbfb8aa3b, v88
	v_exp_f32_e32 v97, v97
	s_mov_b64 s[64:65], 0
	v_add_f32_e32 v96, 1.0, v96
	v_rcp_f32_e32 v100, v96
	v_add_f32_e32 v97, 1.0, v97
	v_rcp_f32_e32 v101, v97
	v_mov_b64_e32 v[98:99], v[94:95]
	v_mov_b64_e32 v[96:97], v[92:93]
	v_mul_f32_e32 v96, v92, v100
	v_cndmask_b32_e64 v96, v100, v96, s[40:41]
	v_mul_f32_e32 v100, 0xbfb8aa3b, v93
	v_exp_f32_e32 v106, v100
	v_mul_f32_e32 v100, 0xbfb8aa3b, v89
	v_mul_f32_e32 v97, v88, v101
	v_exp_f32_e32 v107, v100
	v_cndmask_b32_e64 v97, v101, v97, s[40:41]
	v_mov_b64_e32 v[102:103], v[90:91]
	v_mov_b64_e32 v[100:101], v[88:89]
	v_add_f32_e32 v100, 1.0, v106
	v_cndmask_b32_e64 v98, v98, v94, s[38:39]
	v_rcp_f32_e32 v101, v100
	v_add_f32_e32 v100, 1.0, v107
	v_mul_f32_e32 v107, 0xbfb8aa3b, v98
	v_exp_f32_e32 v107, v107
	v_cndmask_b32_e64 v102, v102, v90, s[38:39]
	v_rcp_f32_e32 v106, v100
	v_mul_f32_e32 v108, 0xbfb8aa3b, v102
	v_add_f32_e32 v107, 1.0, v107
	v_rcp_f32_e32 v107, v107
	v_exp_f32_e32 v108, v108
	v_mov_b32_e32 v100, v97
	v_mul_f32_e32 v97, v93, v101
	v_cndmask_b32_e64 v97, v101, v97, s[40:41]
	v_mul_f32_e32 v101, v89, v106
	v_mul_f32_e32 v98, v98, v107
	v_cndmask_b32_e64 v99, v99, v95, s[38:39]
	v_cndmask_b32_e64 v103, v103, v91, s[38:39]
	v_cndmask_b32_e64 v101, v106, v101, s[40:41]
	v_add_f32_e32 v106, 1.0, v108
	v_cndmask_b32_e64 v98, v107, v98, s[40:41]
	v_mul_f32_e32 v107, 0xbfb8aa3b, v99
	v_mul_f32_e32 v108, 0xbfb8aa3b, v103
	v_exp_f32_e32 v107, v107
	v_exp_f32_e32 v108, v108
	v_rcp_f32_e32 v106, v106
	v_add_f32_e32 v107, 1.0, v107
	v_add_f32_e32 v108, 1.0, v108
	v_rcp_f32_e32 v107, v107
	v_rcp_f32_e32 v108, v108
	v_mul_f32_e32 v102, v102, v106
	v_cndmask_b32_e64 v102, v106, v102, s[40:41]
	v_mul_f32_e32 v99, v99, v107
	v_mul_f32_e32 v103, v103, v108
	v_cndmask_b32_e64 v99, v107, v99, s[40:41]
	v_cndmask_b32_e64 v103, v108, v103, s[40:41]

.LBB0_269:
	v_add_u32_e32 v92, 0x80, v178
	v_ashrrev_i32_e32 v93, 31, v92
	v_cvt_pk_bf16_f32 v88, v96, v97
	v_mul_lo_u32 v93, s62, v93
	v_mul_lo_u32 v94, s63, v92
	v_mad_u64_u32 v[96:97], s[24:25], s62, v92, 0
	v_add3_u32 v97, v97, v93, v94
	v_cvt_pk_bf16_f32 v89, v98, v99
	v_cvt_pk_bf16_f32 v90, v100, v101
	v_cvt_pk_bf16_f32 v91, v102, v103
	v_lshl_add_u64 v[92:93], v[96:97], 1, v[154:155]
	s_and_b64 vcc, exec, s[4:5]
	s_mov_b64 s[64:65], -1
	global_store_dwordx4 v[92:93], v[88:91], off sc1
	s_cbranch_vccnz .LBB0_271
	s_nop 0
	v_mul_f32_e32 v88, 0xbfb8aa3b, v84
	v_exp_f32_e32 v88, v88
	v_mul_f32_e32 v89, 0xbfb8aa3b, v80
	v_exp_f32_e32 v89, v89
	s_mov_b64 s[64:65], 0
	v_add_f32_e32 v88, 1.0, v88
	v_rcp_f32_e32 v92, v88
	v_add_f32_e32 v89, 1.0, v89
	v_rcp_f32_e32 v93, v89
	v_mov_b64_e32 v[90:91], v[86:87]
	v_mov_b64_e32 v[88:89], v[84:85]
	v_mul_f32_e32 v88, v84, v92
	v_cndmask_b32_e64 v88, v92, v88, s[40:41]
	v_mul_f32_e32 v92, 0xbfb8aa3b, v85
	v_exp_f32_e32 v98, v92
	v_mul_f32_e32 v92, 0xbfb8aa3b, v81
	v_mul_f32_e32 v89, v80, v93
	v_exp_f32_e32 v99, v92
	v_cndmask_b32_e64 v89, v93, v89, s[40:41]
	v_mov_b64_e32 v[94:95], v[82:83]
	v_mov_b64_e32 v[92:93], v[80:81]
	v_add_f32_e32 v92, 1.0, v98
	v_cndmask_b32_e64 v90, v90, v86, s[38:39]
	v_rcp_f32_e32 v93, v92
	v_add_f32_e32 v92, 1.0, v99
	v_mul_f32_e32 v99, 0xbfb8aa3b, v90
	v_exp_f32_e32 v99, v99
	v_cndmask_b32_e64 v94, v94, v82, s[38:39]
	v_rcp_f32_e32 v98, v92
	v_mul_f32_e32 v100, 0xbfb8aa3b, v94
	v_add_f32_e32 v99, 1.0, v99
	v_rcp_f32_e32 v99, v99
	v_exp_f32_e32 v100, v100
	v_mov_b32_e32 v92, v89
	v_mul_f32_e32 v89, v85, v93
	v_cndmask_b32_e64 v89, v93, v89, s[40:41]
	v_mul_f32_e32 v93, v81, v98
	v_mul_f32_e32 v90, v90, v99
	v_cndmask_b32_e64 v91, v91, v87, s[38:39]
	v_cndmask_b32_e64 v95, v95, v83, s[38:39]
	v_cndmask_b32_e64 v93, v98, v93, s[40:41]
	v_add_f32_e32 v98, 1.0, v100
	v_cndmask_b32_e64 v90, v99, v90, s[40:41]
	v_mul_f32_e32 v99, 0xbfb8aa3b, v91
	v_mul_f32_e32 v100, 0xbfb8aa3b, v95
	v_exp_f32_e32 v99, v99
	v_exp_f32_e32 v100, v100
	v_rcp_f32_e32 v98, v98
	v_add_f32_e32 v99, 1.0, v99
	v_add_f32_e32 v100, 1.0, v100
	v_rcp_f32_e32 v99, v99
	v_rcp_f32_e32 v100, v100
	v_mul_f32_e32 v94, v94, v98
	v_cndmask_b32_e64 v94, v98, v94, s[40:41]
	v_mul_f32_e32 v91, v91, v99
	v_mul_f32_e32 v95, v95, v100
	v_cndmask_b32_e64 v91, v99, v91, s[40:41]
	v_cndmask_b32_e64 v95, v100, v95, s[40:41]

.LBB0_273:
	v_add_u32_e32 v84, 0x90, v178
	v_ashrrev_i32_e32 v85, 31, v84
	v_cvt_pk_bf16_f32 v80, v88, v89
	v_mul_lo_u32 v85, s62, v85
	v_mul_lo_u32 v86, s63, v84
	v_mad_u64_u32 v[88:89], s[24:25], s62, v84, 0
	v_add3_u32 v89, v89, v85, v86
	v_cvt_pk_bf16_f32 v81, v90, v91
	v_cvt_pk_bf16_f32 v82, v92, v93
	v_cvt_pk_bf16_f32 v83, v94, v95
	v_lshl_add_u64 v[84:85], v[88:89], 1, v[154:155]
	s_and_b64 vcc, exec, s[4:5]
	s_mov_b64 s[64:65], -1
	global_store_dwordx4 v[84:85], v[80:83], off sc1
	s_cbranch_vccnz .LBB0_275
	s_nop 0
	v_mul_f32_e32 v80, 0xbfb8aa3b, v76
	v_exp_f32_e32 v80, v80
	v_mul_f32_e32 v81, 0xbfb8aa3b, v72
	v_exp_f32_e32 v81, v81
	s_mov_b64 s[64:65], 0
	v_add_f32_e32 v80, 1.0, v80
	v_rcp_f32_e32 v84, v80
	v_add_f32_e32 v81, 1.0, v81
	v_rcp_f32_e32 v85, v81
	v_mov_b64_e32 v[82:83], v[78:79]
	v_mov_b64_e32 v[80:81], v[76:77]
	v_mul_f32_e32 v80, v76, v84
	v_cndmask_b32_e64 v80, v84, v80, s[40:41]
	v_mul_f32_e32 v84, 0xbfb8aa3b, v77
	v_exp_f32_e32 v90, v84
	v_mul_f32_e32 v84, 0xbfb8aa3b, v73
	v_mul_f32_e32 v81, v72, v85
	v_exp_f32_e32 v91, v84
	v_cndmask_b32_e64 v81, v85, v81, s[40:41]
	v_mov_b64_e32 v[86:87], v[74:75]
	v_mov_b64_e32 v[84:85], v[72:73]
	v_add_f32_e32 v84, 1.0, v90
	v_cndmask_b32_e64 v82, v82, v78, s[38:39]
	v_rcp_f32_e32 v85, v84
	v_add_f32_e32 v84, 1.0, v91
	v_mul_f32_e32 v91, 0xbfb8aa3b, v82
	v_exp_f32_e32 v91, v91
	v_cndmask_b32_e64 v86, v86, v74, s[38:39]
	v_rcp_f32_e32 v90, v84
	v_mul_f32_e32 v92, 0xbfb8aa3b, v86
	v_add_f32_e32 v91, 1.0, v91
	v_rcp_f32_e32 v91, v91
	v_exp_f32_e32 v92, v92
	v_mov_b32_e32 v84, v81
	v_mul_f32_e32 v81, v77, v85
	v_cndmask_b32_e64 v81, v85, v81, s[40:41]
	v_mul_f32_e32 v85, v73, v90
	v_mul_f32_e32 v82, v82, v91
	v_cndmask_b32_e64 v83, v83, v79, s[38:39]
	v_cndmask_b32_e64 v87, v87, v75, s[38:39]
	v_cndmask_b32_e64 v85, v90, v85, s[40:41]
	v_add_f32_e32 v90, 1.0, v92
	v_cndmask_b32_e64 v82, v91, v82, s[40:41]
	v_mul_f32_e32 v91, 0xbfb8aa3b, v83
	v_mul_f32_e32 v92, 0xbfb8aa3b, v87
	v_exp_f32_e32 v91, v91
	v_exp_f32_e32 v92, v92
	v_rcp_f32_e32 v90, v90
	v_add_f32_e32 v91, 1.0, v91
	v_add_f32_e32 v92, 1.0, v92
	v_rcp_f32_e32 v91, v91
	v_rcp_f32_e32 v92, v92
	v_mul_f32_e32 v86, v86, v90
	v_cndmask_b32_e64 v86, v90, v86, s[40:41]
	v_mul_f32_e32 v83, v83, v91
	v_mul_f32_e32 v87, v87, v92
	v_cndmask_b32_e64 v83, v91, v83, s[40:41]
	v_cndmask_b32_e64 v87, v92, v87, s[40:41]

.LBB0_277:
	v_add_u32_e32 v76, 0xa0, v178
	v_ashrrev_i32_e32 v77, 31, v76
	v_cvt_pk_bf16_f32 v72, v80, v81
	v_mul_lo_u32 v77, s62, v77
	v_mul_lo_u32 v78, s63, v76
	v_mad_u64_u32 v[80:81], s[24:25], s62, v76, 0
	v_add3_u32 v81, v81, v77, v78
	v_cvt_pk_bf16_f32 v73, v82, v83
	v_cvt_pk_bf16_f32 v74, v84, v85
	v_cvt_pk_bf16_f32 v75, v86, v87
	v_lshl_add_u64 v[76:77], v[80:81], 1, v[154:155]
	s_and_b64 vcc, exec, s[4:5]
	s_mov_b64 s[64:65], -1
	global_store_dwordx4 v[76:77], v[72:75], off sc1
	s_cbranch_vccnz .LBB0_279
	s_nop 0
	v_mul_f32_e32 v72, 0xbfb8aa3b, v68
	v_exp_f32_e32 v72, v72
	v_mul_f32_e32 v73, 0xbfb8aa3b, v64
	v_exp_f32_e32 v73, v73
	s_mov_b64 s[64:65], 0
	v_add_f32_e32 v72, 1.0, v72
	v_rcp_f32_e32 v76, v72
	v_add_f32_e32 v73, 1.0, v73
	v_rcp_f32_e32 v77, v73
	v_mov_b64_e32 v[74:75], v[70:71]
	v_mov_b64_e32 v[72:73], v[68:69]
	v_mul_f32_e32 v72, v68, v76
	v_cndmask_b32_e64 v72, v76, v72, s[40:41]
	v_mul_f32_e32 v76, 0xbfb8aa3b, v69
	v_exp_f32_e32 v82, v76
	v_mul_f32_e32 v76, 0xbfb8aa3b, v65
	v_mul_f32_e32 v73, v64, v77
	v_exp_f32_e32 v83, v76
	v_cndmask_b32_e64 v73, v77, v73, s[40:41]
	v_mov_b64_e32 v[78:79], v[66:67]
	v_mov_b64_e32 v[76:77], v[64:65]
	v_add_f32_e32 v76, 1.0, v82
	v_cndmask_b32_e64 v74, v74, v70, s[38:39]
	v_rcp_f32_e32 v77, v76
	v_add_f32_e32 v76, 1.0, v83
	v_mul_f32_e32 v83, 0xbfb8aa3b, v74
	v_exp_f32_e32 v83, v83
	v_cndmask_b32_e64 v78, v78, v66, s[38:39]
	v_rcp_f32_e32 v82, v76
	v_mul_f32_e32 v84, 0xbfb8aa3b, v78
	v_add_f32_e32 v83, 1.0, v83
	v_rcp_f32_e32 v83, v83
	v_exp_f32_e32 v84, v84
	v_mov_b32_e32 v76, v73
	v_mul_f32_e32 v73, v69, v77
	v_cndmask_b32_e64 v73, v77, v73, s[40:41]
	v_mul_f32_e32 v77, v65, v82
	v_mul_f32_e32 v74, v74, v83
	v_cndmask_b32_e64 v75, v75, v71, s[38:39]
	v_cndmask_b32_e64 v79, v79, v67, s[38:39]
	v_cndmask_b32_e64 v77, v82, v77, s[40:41]
	v_add_f32_e32 v82, 1.0, v84
	v_cndmask_b32_e64 v74, v83, v74, s[40:41]
	v_mul_f32_e32 v83, 0xbfb8aa3b, v75
	v_mul_f32_e32 v84, 0xbfb8aa3b, v79
	v_exp_f32_e32 v83, v83
	v_exp_f32_e32 v84, v84
	v_rcp_f32_e32 v82, v82
	v_add_f32_e32 v83, 1.0, v83
	v_add_f32_e32 v84, 1.0, v84
	v_rcp_f32_e32 v83, v83
	v_rcp_f32_e32 v84, v84
	v_mul_f32_e32 v78, v78, v82
	v_cndmask_b32_e64 v78, v82, v78, s[40:41]
	v_mul_f32_e32 v75, v75, v83
	v_mul_f32_e32 v79, v79, v84
	v_cndmask_b32_e64 v75, v83, v75, s[40:41]
	v_cndmask_b32_e64 v79, v84, v79, s[40:41]

.LBB0_281:
	v_add_u32_e32 v68, 0xb0, v178
	v_ashrrev_i32_e32 v69, 31, v68
	v_cvt_pk_bf16_f32 v64, v72, v73
	v_mul_lo_u32 v69, s62, v69
	v_mul_lo_u32 v70, s63, v68
	v_mad_u64_u32 v[72:73], s[24:25], s62, v68, 0
	v_add3_u32 v73, v73, v69, v70
	v_cvt_pk_bf16_f32 v65, v74, v75
	v_cvt_pk_bf16_f32 v66, v76, v77
	v_cvt_pk_bf16_f32 v67, v78, v79
	v_lshl_add_u64 v[68:69], v[72:73], 1, v[154:155]
	s_and_b64 vcc, exec, s[4:5]
	s_mov_b64 s[64:65], -1
	global_store_dwordx4 v[68:69], v[64:67], off sc1
	s_cbranch_vccnz .LBB0_283
	s_nop 0
	v_mul_f32_e32 v64, 0xbfb8aa3b, v60
	v_exp_f32_e32 v64, v64
	v_mul_f32_e32 v65, 0xbfb8aa3b, v56
	v_exp_f32_e32 v65, v65
	s_mov_b64 s[64:65], 0
	v_add_f32_e32 v64, 1.0, v64
	v_rcp_f32_e32 v68, v64
	v_add_f32_e32 v65, 1.0, v65
	v_rcp_f32_e32 v69, v65
	v_mov_b64_e32 v[66:67], v[62:63]
	v_mov_b64_e32 v[64:65], v[60:61]
	v_mul_f32_e32 v64, v60, v68
	v_cndmask_b32_e64 v64, v68, v64, s[40:41]
	v_mul_f32_e32 v68, 0xbfb8aa3b, v61
	v_exp_f32_e32 v74, v68
	v_mul_f32_e32 v68, 0xbfb8aa3b, v57
	v_mul_f32_e32 v65, v56, v69
	v_exp_f32_e32 v75, v68
	v_cndmask_b32_e64 v65, v69, v65, s[40:41]
	v_mov_b64_e32 v[70:71], v[58:59]
	v_mov_b64_e32 v[68:69], v[56:57]
	v_add_f32_e32 v68, 1.0, v74
	v_cndmask_b32_e64 v66, v66, v62, s[38:39]
	v_rcp_f32_e32 v69, v68
	v_add_f32_e32 v68, 1.0, v75
	v_mul_f32_e32 v75, 0xbfb8aa3b, v66
	v_exp_f32_e32 v75, v75
	v_cndmask_b32_e64 v70, v70, v58, s[38:39]
	v_rcp_f32_e32 v74, v68
	v_mul_f32_e32 v76, 0xbfb8aa3b, v70
	v_add_f32_e32 v75, 1.0, v75
	v_rcp_f32_e32 v75, v75
	v_exp_f32_e32 v76, v76
	v_mov_b32_e32 v68, v65
	v_mul_f32_e32 v65, v61, v69
	v_cndmask_b32_e64 v65, v69, v65, s[40:41]
	v_mul_f32_e32 v69, v57, v74
	v_mul_f32_e32 v66, v66, v75
	v_cndmask_b32_e64 v67, v67, v63, s[38:39]
	v_cndmask_b32_e64 v71, v71, v59, s[38:39]
	v_cndmask_b32_e64 v69, v74, v69, s[40:41]
	v_add_f32_e32 v74, 1.0, v76
	v_cndmask_b32_e64 v66, v75, v66, s[40:41]
	v_mul_f32_e32 v75, 0xbfb8aa3b, v67
	v_mul_f32_e32 v76, 0xbfb8aa3b, v71
	v_exp_f32_e32 v75, v75
	v_exp_f32_e32 v76, v76
	v_rcp_f32_e32 v74, v74
	v_add_f32_e32 v75, 1.0, v75
	v_add_f32_e32 v76, 1.0, v76
	v_rcp_f32_e32 v75, v75
	v_rcp_f32_e32 v76, v76
	v_mul_f32_e32 v70, v70, v74
	v_cndmask_b32_e64 v70, v74, v70, s[40:41]
	v_mul_f32_e32 v67, v67, v75
	v_mul_f32_e32 v71, v71, v76
	v_cndmask_b32_e64 v67, v75, v67, s[40:41]
	v_cndmask_b32_e64 v71, v76, v71, s[40:41]

.LBB0_285:
	v_add_u32_e32 v57, 0x80, v177
	v_ashrrev_i32_e32 v56, s6, v57
	v_and_b32_e32 v58, s15, v57
	v_ashrrev_i32_e32 v57, 31, v56
	v_lshlrev_b64 v[56:57], 13, v[56:57]
	v_cndmask_b32_e64 v56, v56, 0, s[46:47]
	v_cndmask_b32_e64 v57, v57, 0, s[46:47]
	v_mul_lo_u32 v59, v57, s62
	v_mul_lo_u32 v60, v56, s63
	v_mad_u64_u32 v[56:57], s[24:25], v56, s62, 0
	v_add3_u32 v57, v57, v60, v59
	v_lshl_add_u64 v[56:57], v[56:57], 1, s[42:43]
	v_ashrrev_i32_e32 v59, 31, v58
	v_lshl_add_u64 v[74:75], v[58:59], 1, v[56:57]
	v_cvt_pk_bf16_f32 v56, v64, v65
	v_cvt_pk_bf16_f32 v57, v66, v67
	v_cvt_pk_bf16_f32 v58, v68, v69
	v_cvt_pk_bf16_f32 v59, v70, v71
	v_lshl_add_u64 v[60:61], v[128:129], 1, v[74:75]
	s_and_b64 vcc, exec, s[4:5]
	s_mov_b64 s[42:43], -1
	global_store_dwordx4 v[60:61], v[56:59], off sc1
	s_cbranch_vccnz .LBB0_287
	s_nop 0
	v_mul_f32_e32 v56, 0xbfb8aa3b, v52
	v_exp_f32_e32 v56, v56
	v_mul_f32_e32 v57, 0xbfb8aa3b, v48
	v_exp_f32_e32 v57, v57
	s_mov_b64 s[42:43], 0
	v_add_f32_e32 v56, 1.0, v56
	v_rcp_f32_e32 v60, v56
	v_add_f32_e32 v57, 1.0, v57
	v_rcp_f32_e32 v61, v57
	v_mov_b64_e32 v[58:59], v[54:55]
	v_mov_b64_e32 v[56:57], v[52:53]
	v_mul_f32_e32 v56, v52, v60
	v_cndmask_b32_e64 v56, v60, v56, s[40:41]
	v_mul_f32_e32 v60, 0xbfb8aa3b, v53
	v_exp_f32_e32 v64, v60
	v_mul_f32_e32 v60, 0xbfb8aa3b, v49
	v_mul_f32_e32 v57, v48, v61
	v_exp_f32_e32 v65, v60
	v_cndmask_b32_e64 v57, v61, v57, s[40:41]
	v_mov_b64_e32 v[62:63], v[50:51]
	v_mov_b64_e32 v[60:61], v[48:49]
	v_add_f32_e32 v60, 1.0, v64
	v_cndmask_b32_e64 v58, v58, v54, s[38:39]
	v_rcp_f32_e32 v61, v60
	v_add_f32_e32 v60, 1.0, v65
	v_mul_f32_e32 v65, 0xbfb8aa3b, v58
	v_exp_f32_e32 v65, v65
	v_cndmask_b32_e64 v62, v62, v50, s[38:39]
	v_rcp_f32_e32 v64, v60
	v_mul_f32_e32 v66, 0xbfb8aa3b, v62
	v_add_f32_e32 v65, 1.0, v65
	v_rcp_f32_e32 v65, v65
	v_exp_f32_e32 v66, v66
	v_mov_b32_e32 v60, v57
	v_mul_f32_e32 v57, v53, v61
	v_cndmask_b32_e64 v57, v61, v57, s[40:41]
	v_mul_f32_e32 v61, v49, v64
	v_mul_f32_e32 v58, v58, v65
	v_cndmask_b32_e64 v59, v59, v55, s[38:39]
	v_cndmask_b32_e64 v63, v63, v51, s[38:39]
	v_cndmask_b32_e64 v61, v64, v61, s[40:41]
	v_add_f32_e32 v64, 1.0, v66
	v_cndmask_b32_e64 v58, v65, v58, s[40:41]
	v_mul_f32_e32 v65, 0xbfb8aa3b, v59
	v_mul_f32_e32 v66, 0xbfb8aa3b, v63
	v_exp_f32_e32 v65, v65
	v_exp_f32_e32 v66, v66
	v_rcp_f32_e32 v64, v64
	v_add_f32_e32 v65, 1.0, v65
	v_add_f32_e32 v66, 1.0, v66
	v_rcp_f32_e32 v65, v65
	v_rcp_f32_e32 v66, v66
	v_mul_f32_e32 v62, v62, v64
	v_cndmask_b32_e64 v62, v64, v62, s[40:41]
	v_mul_f32_e32 v59, v59, v65
	v_mul_f32_e32 v63, v63, v66
	v_cndmask_b32_e64 v59, v65, v59, s[40:41]
	v_cndmask_b32_e64 v63, v66, v63, s[40:41]

.LBB0_289:
	v_cvt_pk_bf16_f32 v48, v56, v57
	v_cvt_pk_bf16_f32 v49, v58, v59
	s_nop 0
	v_cvt_pk_bf16_f32 v50, v60, v61
	v_cvt_pk_bf16_f32 v51, v62, v63
	v_lshl_add_u64 v[52:53], v[120:121], 1, v[74:75]
	s_and_b64 vcc, exec, s[4:5]
	s_mov_b64 s[42:43], -1
	global_store_dwordx4 v[52:53], v[48:51], off sc1
	s_cbranch_vccnz .LBB0_291
	s_nop 0
	v_mul_f32_e32 v48, 0xbfb8aa3b, v44
	v_exp_f32_e32 v48, v48
	v_mul_f32_e32 v49, 0xbfb8aa3b, v40
	v_exp_f32_e32 v49, v49
	s_mov_b64 s[42:43], 0
	v_add_f32_e32 v48, 1.0, v48
	v_rcp_f32_e32 v52, v48
	v_add_f32_e32 v49, 1.0, v49
	v_rcp_f32_e32 v53, v49
	v_mov_b64_e32 v[50:51], v[46:47]
	v_mov_b64_e32 v[48:49], v[44:45]
	v_mul_f32_e32 v48, v44, v52
	v_cndmask_b32_e64 v48, v52, v48, s[40:41]
	v_mul_f32_e32 v52, 0xbfb8aa3b, v45
	v_exp_f32_e32 v56, v52
	v_mul_f32_e32 v52, 0xbfb8aa3b, v41
	v_mul_f32_e32 v49, v40, v53
	v_exp_f32_e32 v57, v52
	v_cndmask_b32_e64 v49, v53, v49, s[40:41]
	v_mov_b64_e32 v[54:55], v[42:43]
	v_mov_b64_e32 v[52:53], v[40:41]
	v_add_f32_e32 v52, 1.0, v56
	v_cndmask_b32_e64 v50, v50, v46, s[38:39]
	v_rcp_f32_e32 v53, v52
	v_add_f32_e32 v52, 1.0, v57
	v_mul_f32_e32 v57, 0xbfb8aa3b, v50
	v_exp_f32_e32 v57, v57
	v_cndmask_b32_e64 v54, v54, v42, s[38:39]
	v_rcp_f32_e32 v56, v52
	v_mul_f32_e32 v58, 0xbfb8aa3b, v54
	v_add_f32_e32 v57, 1.0, v57
	v_rcp_f32_e32 v57, v57
	v_exp_f32_e32 v58, v58
	v_mov_b32_e32 v52, v49
	v_mul_f32_e32 v49, v45, v53
	v_cndmask_b32_e64 v49, v53, v49, s[40:41]
	v_mul_f32_e32 v53, v41, v56
	v_mul_f32_e32 v50, v50, v57
	v_cndmask_b32_e64 v51, v51, v47, s[38:39]
	v_cndmask_b32_e64 v55, v55, v43, s[38:39]
	v_cndmask_b32_e64 v53, v56, v53, s[40:41]
	v_add_f32_e32 v56, 1.0, v58
	v_cndmask_b32_e64 v50, v57, v50, s[40:41]
	v_mul_f32_e32 v57, 0xbfb8aa3b, v51
	v_mul_f32_e32 v58, 0xbfb8aa3b, v55
	v_exp_f32_e32 v57, v57
	v_exp_f32_e32 v58, v58
	v_rcp_f32_e32 v56, v56
	v_add_f32_e32 v57, 1.0, v57
	v_add_f32_e32 v58, 1.0, v58
	v_rcp_f32_e32 v57, v57
	v_rcp_f32_e32 v58, v58
	v_mul_f32_e32 v54, v54, v56
	v_cndmask_b32_e64 v54, v56, v54, s[40:41]
	v_mul_f32_e32 v51, v51, v57
	v_mul_f32_e32 v55, v55, v58
	v_cndmask_b32_e64 v51, v57, v51, s[40:41]
	v_cndmask_b32_e64 v55, v58, v55, s[40:41]

.LBB0_293:
	v_cvt_pk_bf16_f32 v40, v48, v49
	v_cvt_pk_bf16_f32 v41, v50, v51
	s_nop 0
	v_cvt_pk_bf16_f32 v42, v52, v53
	v_cvt_pk_bf16_f32 v43, v54, v55
	v_lshl_add_u64 v[44:45], v[112:113], 1, v[74:75]
	s_and_b64 vcc, exec, s[4:5]
	s_mov_b64 s[42:43], -1
	global_store_dwordx4 v[44:45], v[40:43], off sc1
	s_cbranch_vccnz .LBB0_295
	s_nop 0
	v_mul_f32_e32 v40, 0xbfb8aa3b, v36
	v_exp_f32_e32 v40, v40
	v_mul_f32_e32 v41, 0xbfb8aa3b, v32
	v_exp_f32_e32 v41, v41
	s_mov_b64 s[42:43], 0
	v_add_f32_e32 v40, 1.0, v40
	v_rcp_f32_e32 v44, v40
	v_add_f32_e32 v41, 1.0, v41
	v_rcp_f32_e32 v45, v41
	v_mov_b64_e32 v[42:43], v[38:39]
	v_mov_b64_e32 v[40:41], v[36:37]
	v_mul_f32_e32 v40, v36, v44
	v_cndmask_b32_e64 v40, v44, v40, s[40:41]
	v_mul_f32_e32 v44, 0xbfb8aa3b, v37
	v_exp_f32_e32 v48, v44
	v_mul_f32_e32 v44, 0xbfb8aa3b, v33
	v_mul_f32_e32 v41, v32, v45
	v_exp_f32_e32 v49, v44
	v_cndmask_b32_e64 v41, v45, v41, s[40:41]
	v_mov_b64_e32 v[46:47], v[34:35]
	v_mov_b64_e32 v[44:45], v[32:33]
	v_add_f32_e32 v44, 1.0, v48
	v_cndmask_b32_e64 v42, v42, v38, s[38:39]
	v_rcp_f32_e32 v45, v44
	v_add_f32_e32 v44, 1.0, v49
	v_mul_f32_e32 v49, 0xbfb8aa3b, v42
	v_exp_f32_e32 v49, v49
	v_cndmask_b32_e64 v46, v46, v34, s[38:39]
	v_rcp_f32_e32 v48, v44
	v_mul_f32_e32 v50, 0xbfb8aa3b, v46
	v_add_f32_e32 v49, 1.0, v49
	v_rcp_f32_e32 v49, v49
	v_exp_f32_e32 v50, v50
	v_mov_b32_e32 v44, v41
	v_mul_f32_e32 v41, v37, v45
	v_cndmask_b32_e64 v41, v45, v41, s[40:41]
	v_mul_f32_e32 v45, v33, v48
	v_mul_f32_e32 v42, v42, v49
	v_cndmask_b32_e64 v43, v43, v39, s[38:39]
	v_cndmask_b32_e64 v47, v47, v35, s[38:39]
	v_cndmask_b32_e64 v45, v48, v45, s[40:41]
	v_add_f32_e32 v48, 1.0, v50
	v_cndmask_b32_e64 v42, v49, v42, s[40:41]
	v_mul_f32_e32 v49, 0xbfb8aa3b, v43
	v_mul_f32_e32 v50, 0xbfb8aa3b, v47
	v_exp_f32_e32 v49, v49
	v_exp_f32_e32 v50, v50
	v_rcp_f32_e32 v48, v48
	v_add_f32_e32 v49, 1.0, v49
	v_add_f32_e32 v50, 1.0, v50
	v_rcp_f32_e32 v49, v49
	v_rcp_f32_e32 v50, v50
	v_mul_f32_e32 v46, v46, v48
	v_cndmask_b32_e64 v46, v48, v46, s[40:41]
	v_mul_f32_e32 v43, v43, v49
	v_mul_f32_e32 v47, v47, v50
	v_cndmask_b32_e64 v43, v49, v43, s[40:41]
	v_cndmask_b32_e64 v47, v50, v47, s[40:41]

.LBB0_297:
	v_cvt_pk_bf16_f32 v32, v40, v41
	v_cvt_pk_bf16_f32 v33, v42, v43
	s_nop 0
	v_cvt_pk_bf16_f32 v34, v44, v45
	v_cvt_pk_bf16_f32 v35, v46, v47
	v_lshl_add_u64 v[36:37], v[104:105], 1, v[74:75]
	s_and_b64 vcc, exec, s[4:5]
	s_mov_b64 s[42:43], -1
	global_store_dwordx4 v[36:37], v[32:35], off sc1
	s_cbranch_vccnz .LBB0_299
	s_nop 0
	v_mul_f32_e32 v32, 0xbfb8aa3b, v28
	v_exp_f32_e32 v32, v32
	v_mul_f32_e32 v33, 0xbfb8aa3b, v24
	v_exp_f32_e32 v33, v33
	s_mov_b64 s[42:43], 0
	v_add_f32_e32 v32, 1.0, v32
	v_rcp_f32_e32 v36, v32
	v_add_f32_e32 v33, 1.0, v33
	v_rcp_f32_e32 v37, v33
	v_mov_b64_e32 v[34:35], v[30:31]
	v_mov_b64_e32 v[32:33], v[28:29]
	v_mul_f32_e32 v32, v28, v36
	v_cndmask_b32_e64 v32, v36, v32, s[40:41]
	v_mul_f32_e32 v36, 0xbfb8aa3b, v29
	v_exp_f32_e32 v40, v36
	v_mul_f32_e32 v36, 0xbfb8aa3b, v25
	v_mul_f32_e32 v33, v24, v37
	v_exp_f32_e32 v41, v36
	v_cndmask_b32_e64 v33, v37, v33, s[40:41]
	v_mov_b64_e32 v[38:39], v[26:27]
	v_mov_b64_e32 v[36:37], v[24:25]
	v_add_f32_e32 v36, 1.0, v40
	v_cndmask_b32_e64 v34, v34, v30, s[38:39]
	v_rcp_f32_e32 v37, v36
	v_add_f32_e32 v36, 1.0, v41
	v_mul_f32_e32 v41, 0xbfb8aa3b, v34
	v_exp_f32_e32 v41, v41
	v_cndmask_b32_e64 v38, v38, v26, s[38:39]
	v_rcp_f32_e32 v40, v36
	v_mul_f32_e32 v42, 0xbfb8aa3b, v38
	v_add_f32_e32 v41, 1.0, v41
	v_rcp_f32_e32 v41, v41
	v_exp_f32_e32 v42, v42
	v_mov_b32_e32 v36, v33
	v_mul_f32_e32 v33, v29, v37
	v_cndmask_b32_e64 v33, v37, v33, s[40:41]
	v_mul_f32_e32 v37, v25, v40
	v_mul_f32_e32 v34, v34, v41
	v_cndmask_b32_e64 v35, v35, v31, s[38:39]
	v_cndmask_b32_e64 v39, v39, v27, s[38:39]
	v_cndmask_b32_e64 v37, v40, v37, s[40:41]
	v_add_f32_e32 v40, 1.0, v42
	v_cndmask_b32_e64 v34, v41, v34, s[40:41]
	v_mul_f32_e32 v41, 0xbfb8aa3b, v35
	v_mul_f32_e32 v42, 0xbfb8aa3b, v39
	v_exp_f32_e32 v41, v41
	v_exp_f32_e32 v42, v42
	v_rcp_f32_e32 v40, v40
	v_add_f32_e32 v41, 1.0, v41
	v_add_f32_e32 v42, 1.0, v42
	v_rcp_f32_e32 v41, v41
	v_rcp_f32_e32 v42, v42
	v_mul_f32_e32 v38, v38, v40
	v_cndmask_b32_e64 v38, v40, v38, s[40:41]
	v_mul_f32_e32 v35, v35, v41
	v_mul_f32_e32 v39, v39, v42
	v_cndmask_b32_e64 v35, v41, v35, s[40:41]
	v_cndmask_b32_e64 v39, v42, v39, s[40:41]

.LBB0_301:
	v_cvt_pk_bf16_f32 v24, v32, v33
	v_cvt_pk_bf16_f32 v25, v34, v35
	s_nop 0
	v_cvt_pk_bf16_f32 v26, v36, v37
	v_cvt_pk_bf16_f32 v27, v38, v39
	v_lshl_add_u64 v[28:29], v[96:97], 1, v[74:75]
	s_and_b64 vcc, exec, s[4:5]
	s_mov_b64 s[42:43], -1
	global_store_dwordx4 v[28:29], v[24:27], off sc1
	s_cbranch_vccnz .LBB0_303
	s_nop 0
	v_mul_f32_e32 v24, 0xbfb8aa3b, v20
	v_exp_f32_e32 v24, v24
	v_mul_f32_e32 v25, 0xbfb8aa3b, v16
	v_exp_f32_e32 v25, v25
	s_mov_b64 s[42:43], 0
	v_add_f32_e32 v24, 1.0, v24
	v_rcp_f32_e32 v28, v24
	v_add_f32_e32 v25, 1.0, v25
	v_rcp_f32_e32 v29, v25
	v_mov_b64_e32 v[26:27], v[22:23]
	v_mov_b64_e32 v[24:25], v[20:21]
	v_mul_f32_e32 v24, v20, v28
	v_cndmask_b32_e64 v24, v28, v24, s[40:41]
	v_mul_f32_e32 v28, 0xbfb8aa3b, v21
	v_exp_f32_e32 v32, v28
	v_mul_f32_e32 v28, 0xbfb8aa3b, v17
	v_mul_f32_e32 v25, v16, v29
	v_exp_f32_e32 v33, v28
	v_cndmask_b32_e64 v25, v29, v25, s[40:41]
	v_mov_b64_e32 v[30:31], v[18:19]
	v_mov_b64_e32 v[28:29], v[16:17]
	v_add_f32_e32 v28, 1.0, v32
	v_cndmask_b32_e64 v26, v26, v22, s[38:39]
	v_rcp_f32_e32 v29, v28
	v_add_f32_e32 v28, 1.0, v33
	v_mul_f32_e32 v33, 0xbfb8aa3b, v26
	v_exp_f32_e32 v33, v33
	v_cndmask_b32_e64 v30, v30, v18, s[38:39]
	v_rcp_f32_e32 v32, v28
	v_mul_f32_e32 v34, 0xbfb8aa3b, v30
	v_add_f32_e32 v33, 1.0, v33
	v_rcp_f32_e32 v33, v33
	v_exp_f32_e32 v34, v34
	v_mov_b32_e32 v28, v25
	v_mul_f32_e32 v25, v21, v29
	v_cndmask_b32_e64 v25, v29, v25, s[40:41]
	v_mul_f32_e32 v29, v17, v32
	v_mul_f32_e32 v26, v26, v33
	v_cndmask_b32_e64 v27, v27, v23, s[38:39]
	v_cndmask_b32_e64 v31, v31, v19, s[38:39]
	v_cndmask_b32_e64 v29, v32, v29, s[40:41]
	v_add_f32_e32 v32, 1.0, v34
	v_cndmask_b32_e64 v26, v33, v26, s[40:41]
	v_mul_f32_e32 v33, 0xbfb8aa3b, v27
	v_mul_f32_e32 v34, 0xbfb8aa3b, v31
	v_exp_f32_e32 v33, v33
	v_exp_f32_e32 v34, v34
	v_rcp_f32_e32 v32, v32
	v_add_f32_e32 v33, 1.0, v33
	v_add_f32_e32 v34, 1.0, v34
	v_rcp_f32_e32 v33, v33
	v_rcp_f32_e32 v34, v34
	v_mul_f32_e32 v30, v30, v32
	v_cndmask_b32_e64 v30, v32, v30, s[40:41]
	v_mul_f32_e32 v27, v27, v33
	v_mul_f32_e32 v31, v31, v34
	v_cndmask_b32_e64 v27, v33, v27, s[40:41]
	v_cndmask_b32_e64 v31, v34, v31, s[40:41]

.LBB0_305:
	v_cvt_pk_bf16_f32 v16, v24, v25
	v_cvt_pk_bf16_f32 v17, v26, v27
	s_nop 0
	v_cvt_pk_bf16_f32 v18, v28, v29
	v_cvt_pk_bf16_f32 v19, v30, v31
	v_lshl_add_u64 v[20:21], v[88:89], 1, v[74:75]
	s_and_b64 vcc, exec, s[4:5]
	s_mov_b64 s[42:43], -1
	global_store_dwordx4 v[20:21], v[16:19], off sc1
	s_cbranch_vccnz .LBB0_307
	s_nop 0
	v_mul_f32_e32 v16, 0xbfb8aa3b, v12
	v_exp_f32_e32 v16, v16
	v_mul_f32_e32 v17, 0xbfb8aa3b, v8
	v_exp_f32_e32 v17, v17
	s_mov_b64 s[42:43], 0
	v_add_f32_e32 v16, 1.0, v16
	v_rcp_f32_e32 v20, v16
	v_add_f32_e32 v17, 1.0, v17
	v_rcp_f32_e32 v21, v17
	v_mov_b64_e32 v[18:19], v[14:15]
	v_mov_b64_e32 v[16:17], v[12:13]
	v_mul_f32_e32 v16, v12, v20
	v_cndmask_b32_e64 v16, v20, v16, s[40:41]
	v_mul_f32_e32 v20, 0xbfb8aa3b, v13
	v_exp_f32_e32 v24, v20
	v_mul_f32_e32 v20, 0xbfb8aa3b, v9
	v_mul_f32_e32 v17, v8, v21
	v_exp_f32_e32 v25, v20
	v_cndmask_b32_e64 v17, v21, v17, s[40:41]
	v_mov_b64_e32 v[22:23], v[10:11]
	v_mov_b64_e32 v[20:21], v[8:9]
	v_add_f32_e32 v20, 1.0, v24
	v_cndmask_b32_e64 v18, v18, v14, s[38:39]
	v_rcp_f32_e32 v21, v20
	v_add_f32_e32 v20, 1.0, v25
	v_mul_f32_e32 v25, 0xbfb8aa3b, v18
	v_exp_f32_e32 v25, v25
	v_cndmask_b32_e64 v22, v22, v10, s[38:39]
	v_rcp_f32_e32 v24, v20
	v_mul_f32_e32 v26, 0xbfb8aa3b, v22
	v_add_f32_e32 v25, 1.0, v25
	v_rcp_f32_e32 v25, v25
	v_exp_f32_e32 v26, v26
	v_mov_b32_e32 v20, v17
	v_mul_f32_e32 v17, v13, v21
	v_cndmask_b32_e64 v17, v21, v17, s[40:41]
	v_mul_f32_e32 v21, v9, v24
	v_mul_f32_e32 v18, v18, v25
	v_cndmask_b32_e64 v19, v19, v15, s[38:39]
	v_cndmask_b32_e64 v23, v23, v11, s[38:39]
	v_cndmask_b32_e64 v21, v24, v21, s[40:41]
	v_add_f32_e32 v24, 1.0, v26
	v_cndmask_b32_e64 v18, v25, v18, s[40:41]
	v_mul_f32_e32 v25, 0xbfb8aa3b, v19
	v_mul_f32_e32 v26, 0xbfb8aa3b, v23
	v_exp_f32_e32 v25, v25
	v_exp_f32_e32 v26, v26
	v_rcp_f32_e32 v24, v24
	v_add_f32_e32 v25, 1.0, v25
	v_add_f32_e32 v26, 1.0, v26
	v_rcp_f32_e32 v25, v25
	v_rcp_f32_e32 v26, v26
	v_mul_f32_e32 v22, v22, v24
	v_cndmask_b32_e64 v22, v24, v22, s[40:41]
	v_mul_f32_e32 v19, v19, v25
	v_mul_f32_e32 v23, v23, v26
	v_cndmask_b32_e64 v19, v25, v19, s[40:41]
	v_cndmask_b32_e64 v23, v26, v23, s[40:41]

.LBB0_309:
	v_cvt_pk_bf16_f32 v8, v16, v17
	v_cvt_pk_bf16_f32 v9, v18, v19
	s_nop 0
	v_cvt_pk_bf16_f32 v10, v20, v21
	v_cvt_pk_bf16_f32 v11, v22, v23
	v_lshl_add_u64 v[12:13], v[80:81], 1, v[74:75]
	s_and_b64 vcc, exec, s[4:5]
	s_mov_b64 s[4:5], -1
	global_store_dwordx4 v[12:13], v[8:11], off sc1
	s_cbranch_vccnz .LBB0_311
	s_nop 0
	v_mul_f32_e32 v8, 0xbfb8aa3b, v4
	v_exp_f32_e32 v8, v8
	v_mul_f32_e32 v9, 0xbfb8aa3b, v0
	v_exp_f32_e32 v9, v9
	s_mov_b64 s[4:5], 0
	v_add_f32_e32 v8, 1.0, v8
	v_rcp_f32_e32 v12, v8
	v_add_f32_e32 v9, 1.0, v9
	v_rcp_f32_e32 v13, v9
	v_mov_b64_e32 v[10:11], v[6:7]
	v_mov_b64_e32 v[8:9], v[4:5]
	v_mul_f32_e32 v8, v4, v12
	v_cndmask_b32_e64 v8, v12, v8, s[40:41]
	v_mul_f32_e32 v12, 0xbfb8aa3b, v5
	v_exp_f32_e32 v16, v12
	v_mul_f32_e32 v12, 0xbfb8aa3b, v1
	v_mul_f32_e32 v9, v0, v13
	v_exp_f32_e32 v17, v12
	v_cndmask_b32_e64 v9, v13, v9, s[40:41]
	v_mov_b64_e32 v[14:15], v[2:3]
	v_mov_b64_e32 v[12:13], v[0:1]
	v_add_f32_e32 v12, 1.0, v16
	v_cndmask_b32_e64 v10, v10, v6, s[38:39]
	v_rcp_f32_e32 v13, v12
	v_add_f32_e32 v12, 1.0, v17
	v_mul_f32_e32 v17, 0xbfb8aa3b, v10
	v_exp_f32_e32 v17, v17
	v_cndmask_b32_e64 v14, v14, v2, s[38:39]
	v_rcp_f32_e32 v16, v12
	v_mul_f32_e32 v18, 0xbfb8aa3b, v14
	v_add_f32_e32 v17, 1.0, v17
	v_rcp_f32_e32 v17, v17
	v_exp_f32_e32 v18, v18
	v_mov_b32_e32 v12, v9
	v_mul_f32_e32 v9, v5, v13
	v_cndmask_b32_e64 v9, v13, v9, s[40:41]
	v_mul_f32_e32 v13, v1, v16
	v_mul_f32_e32 v10, v10, v17
	v_cndmask_b32_e64 v11, v11, v7, s[38:39]
	v_cndmask_b32_e64 v15, v15, v3, s[38:39]
	v_cndmask_b32_e64 v13, v16, v13, s[40:41]
	v_add_f32_e32 v16, 1.0, v18
	v_cndmask_b32_e64 v10, v17, v10, s[40:41]
	v_mul_f32_e32 v17, 0xbfb8aa3b, v11
	v_mul_f32_e32 v18, 0xbfb8aa3b, v15
	v_exp_f32_e32 v17, v17
	v_exp_f32_e32 v18, v18
	v_rcp_f32_e32 v16, v16
	v_add_f32_e32 v17, 1.0, v17
	v_add_f32_e32 v18, 1.0, v18
	v_rcp_f32_e32 v17, v17
	v_rcp_f32_e32 v18, v18
	v_mul_f32_e32 v14, v14, v16
	v_cndmask_b32_e64 v14, v16, v14, s[40:41]
	v_mul_f32_e32 v11, v11, v17
	v_mul_f32_e32 v15, v15, v18
	v_cndmask_b32_e64 v11, v17, v11, s[40:41]
	v_cndmask_b32_e64 v15, v18, v15, s[40:41]

.LBB0_313:
	v_lshl_add_u64 v[4:5], v[72:73], 1, v[74:75]
	s_andn2_b64 vcc, exec, s[0:1]
	s_mov_b64 s[0:1], -1
	v_cvt_pk_bf16_f32 v0, v8, v9
	v_cvt_pk_bf16_f32 v1, v10, v11
	v_cvt_pk_bf16_f32 v2, v12, v13
	v_cvt_pk_bf16_f32 v3, v14, v15
	global_store_dwordx4 v[4:5], v[0:3], off sc1
	s_cbranch_vccnz .LBB0_231
	s_andn2_b64 vcc, exec, s[8:9]
	s_cbranch_vccnz .LBB0_230
	s_barrier
	s_branch .LBB0_230

.LBB0_361:
	s_lshl_b32 s0, s0, 8
	s_add_i32 s0, s0, s85
	v_add_u32_e32 v22, s0, v8
	v_lshl_or_b32 v8, s1, 8, v185
	v_add_u32_e32 v26, s23, v8
	s_lshl_b32 s0, -1, s8
	s_xor_b64 s[24:25], s[70:71], -1
	s_not_b32 s23, s0
	v_ashrrev_i32_e32 v8, s8, v26
	s_and_b64 s[0:1], s[62:63], exec
	v_ashrrev_i32_e32 v9, 31, v8
	s_cselect_b32 s23, -1, s23
	s_lshl_b64 s[0:1], s[68:69], 1
	v_lshlrev_b64 v[8:9], 13, v[8:9]
	s_add_u32 s68, s74, s0
	v_cndmask_b32_e64 v8, v8, 0, s[62:63]
	s_addc_u32 s69, s75, s1
	v_cndmask_b32_e64 v11, v9, 0, s[62:63]
	v_mad_u64_u32 v[8:9], s[0:1], v8, s66, 0
	v_and_b32_e32 v10, s23, v26
	v_mad_i32_i24 v9, v11, s66, v9
	v_lshl_add_u64 v[8:9], v[8:9], 1, s[68:69]
	v_ashrrev_i32_e32 v11, 31, v10
	v_lshl_add_u64 v[24:25], v[10:11], 1, v[8:9]
	v_mad_i64_i32 v[8:9], s[0:1], s66, v22, 0
	v_cvt_pk_bf16_f32 v0, v0, v1
	v_cvt_pk_bf16_f32 v1, v2, v3
	v_cvt_pk_bf16_f32 v2, v4, v5
	v_lshl_add_u64 v[4:5], v[8:9], 1, v[24:25]
	v_cvt_pk_bf16_f32 v3, v6, v7
	global_store_dwordx4 v[4:5], v[0:3], off sc1
	s_andn2_b64 vcc, exec, s[24:25]
	s_mov_b64 s[70:71], -1
	v_cndmask_b32_e64 v0, 0, 1, s[24:25]
	v_cmp_ne_u32_e64 s[0:1], 1, v0
	s_cbranch_vccnz .LBB0_363
	v_mul_f32_e32 v1, 0x3c800000, v144
	v_cndmask_b32_e64 v1, v144, v1, s[62:63]
	v_mul_f32_e32 v2, 0x3c800000, v149
	v_mul_f32_e32 v3, 0x3c800000, v145
	v_mul_f32_e32 v1, 0xbfb8aa3b, v1
	v_cndmask_b32_e64 v2, v149, v2, s[62:63]
	v_cndmask_b32_e64 v3, v145, v3, s[62:63]
	v_exp_f32_e32 v1, v1
	v_mul_f32_e32 v2, 0xbfb8aa3b, v2
	v_mul_f32_e32 v3, 0xbfb8aa3b, v3
	v_exp_f32_e32 v2, v2
	v_exp_f32_e32 v3, v3
	v_add_f32_e32 v1, 1.0, v1
	v_rcp_f32_e32 v4, v1
	v_add_f32_e32 v1, 1.0, v2
	v_add_f32_e32 v2, 1.0, v3
	v_mul_f32_e32 v3, 0x3c800000, v150
	v_mul_f32_e32 v5, 0x3c800000, v146
	v_cndmask_b32_e64 v3, v150, v3, s[62:63]
	v_cndmask_b32_e64 v5, v146, v5, s[62:63]
	v_mul_f32_e32 v3, 0xbfb8aa3b, v3
	v_mul_f32_e32 v5, 0xbfb8aa3b, v5
	v_exp_f32_e32 v3, v3
	v_exp_f32_e32 v6, v5
	v_rcp_f32_e32 v5, v2
	v_mul_f32_e32 v0, 0x3c800000, v148
	v_add_f32_e32 v2, 1.0, v3
	v_add_f32_e32 v3, 1.0, v6
	v_mul_f32_e32 v6, 0x3c800000, v151
	v_mul_f32_e32 v7, 0x3c800000, v147
	v_cndmask_b32_e64 v6, v151, v6, s[62:63]
	v_cndmask_b32_e64 v0, v148, v0, s[62:63]
	v_cndmask_b32_e64 v7, v147, v7, s[62:63]
	v_mul_f32_e32 v6, 0xbfb8aa3b, v6
	v_mul_f32_e32 v0, 0xbfb8aa3b, v0
	v_exp_f32_e32 v10, v6
	v_mul_f32_e32 v6, 0xbfb8aa3b, v7
	v_exp_f32_e32 v0, v0
	v_exp_f32_e32 v7, v6
	v_rcp_f32_e32 v6, v3
	v_add_f32_e32 v3, 1.0, v10
	v_add_f32_e32 v0, 1.0, v0
	v_add_f32_e32 v7, 1.0, v7
	v_rcp_f32_e32 v0, v0
	v_rcp_f32_e32 v1, v1
	v_rcp_f32_e32 v2, v2
	v_rcp_f32_e32 v3, v3
	v_rcp_f32_e32 v7, v7
	s_mov_b64 s[70:71], 0

.LBB0_365:
	v_cvt_pk_bf16_f32 v0, v0, v1
	v_cvt_pk_bf16_f32 v1, v2, v3
	s_nop 0
	v_cvt_pk_bf16_f32 v2, v4, v5
	v_add_u32_e32 v4, 16, v22
	v_mad_i64_i32 v[10:11], s[24:25], s66, v4, 0
	v_cvt_pk_bf16_f32 v3, v6, v7
	v_lshl_add_u64 v[4:5], v[10:11], 1, v[24:25]
	s_and_b64 vcc, exec, s[0:1]
	s_mov_b64 s[70:71], -1
	global_store_dwordx4 v[4:5], v[0:3], off sc1
	s_cbranch_vccnz .LBB0_367
	s_nop 0
	v_mul_f32_e32 v1, 0x3c800000, v136
	v_cndmask_b32_e64 v1, v136, v1, s[62:63]
	v_mul_f32_e32 v2, 0x3c800000, v141
	v_mul_f32_e32 v3, 0x3c800000, v137
	v_mul_f32_e32 v1, 0xbfb8aa3b, v1
	v_cndmask_b32_e64 v2, v141, v2, s[62:63]
	v_cndmask_b32_e64 v3, v137, v3, s[62:63]
	v_exp_f32_e32 v1, v1
	v_mul_f32_e32 v2, 0xbfb8aa3b, v2
	v_mul_f32_e32 v3, 0xbfb8aa3b, v3
	v_exp_f32_e32 v2, v2
	v_exp_f32_e32 v3, v3
	v_add_f32_e32 v1, 1.0, v1
	v_rcp_f32_e32 v4, v1
	v_add_f32_e32 v1, 1.0, v2
	v_add_f32_e32 v2, 1.0, v3
	v_mul_f32_e32 v3, 0x3c800000, v142
	v_mul_f32_e32 v5, 0x3c800000, v138
	v_cndmask_b32_e64 v3, v142, v3, s[62:63]
	v_cndmask_b32_e64 v5, v138, v5, s[62:63]
	v_mul_f32_e32 v3, 0xbfb8aa3b, v3
	v_mul_f32_e32 v5, 0xbfb8aa3b, v5
	v_exp_f32_e32 v3, v3
	v_exp_f32_e32 v6, v5
	v_rcp_f32_e32 v5, v2
	v_mul_f32_e32 v0, 0x3c800000, v140
	v_add_f32_e32 v2, 1.0, v3
	v_add_f32_e32 v3, 1.0, v6
	v_mul_f32_e32 v6, 0x3c800000, v143
	v_mul_f32_e32 v7, 0x3c800000, v139
	v_cndmask_b32_e64 v6, v143, v6, s[62:63]
	v_cndmask_b32_e64 v0, v140, v0, s[62:63]
	v_cndmask_b32_e64 v7, v139, v7, s[62:63]
	v_mul_f32_e32 v6, 0xbfb8aa3b, v6
	v_mul_f32_e32 v0, 0xbfb8aa3b, v0
	v_exp_f32_e32 v12, v6
	v_mul_f32_e32 v6, 0xbfb8aa3b, v7
	v_exp_f32_e32 v0, v0
	v_exp_f32_e32 v7, v6
	v_rcp_f32_e32 v6, v3
	v_add_f32_e32 v3, 1.0, v12
	v_add_f32_e32 v0, 1.0, v0
	v_add_f32_e32 v7, 1.0, v7
	v_rcp_f32_e32 v0, v0
	v_rcp_f32_e32 v1, v1
	v_rcp_f32_e32 v2, v2
	v_rcp_f32_e32 v3, v3
	v_rcp_f32_e32 v7, v7
	s_mov_b64 s[70:71], 0

.LBB0_369:
	v_cvt_pk_bf16_f32 v0, v0, v1
	v_cvt_pk_bf16_f32 v1, v2, v3
	s_nop 0
	v_cvt_pk_bf16_f32 v2, v4, v5
	v_add_u32_e32 v4, 32, v22
	v_mad_i64_i32 v[12:13], s[24:25], s66, v4, 0
	v_cvt_pk_bf16_f32 v3, v6, v7
	v_lshl_add_u64 v[4:5], v[12:13], 1, v[24:25]
	s_and_b64 vcc, exec, s[0:1]
	s_mov_b64 s[70:71], -1
	global_store_dwordx4 v[4:5], v[0:3], off sc1
	s_cbranch_vccnz .LBB0_371
	s_nop 0
	v_mul_f32_e32 v1, 0x3c800000, v128
	v_cndmask_b32_e64 v1, v128, v1, s[62:63]
	v_mul_f32_e32 v2, 0x3c800000, v133
	v_mul_f32_e32 v3, 0x3c800000, v129
	v_mul_f32_e32 v1, 0xbfb8aa3b, v1
	v_cndmask_b32_e64 v2, v133, v2, s[62:63]
	v_cndmask_b32_e64 v3, v129, v3, s[62:63]
	v_exp_f32_e32 v1, v1
	v_mul_f32_e32 v2, 0xbfb8aa3b, v2
	v_mul_f32_e32 v3, 0xbfb8aa3b, v3
	v_exp_f32_e32 v2, v2
	v_exp_f32_e32 v3, v3
	v_add_f32_e32 v1, 1.0, v1
	v_rcp_f32_e32 v4, v1
	v_add_f32_e32 v1, 1.0, v2
	v_add_f32_e32 v2, 1.0, v3
	v_mul_f32_e32 v3, 0x3c800000, v134
	v_mul_f32_e32 v5, 0x3c800000, v130
	v_cndmask_b32_e64 v3, v134, v3, s[62:63]
	v_cndmask_b32_e64 v5, v130, v5, s[62:63]
	v_mul_f32_e32 v3, 0xbfb8aa3b, v3
	v_mul_f32_e32 v5, 0xbfb8aa3b, v5
	v_exp_f32_e32 v3, v3
	v_exp_f32_e32 v6, v5
	v_rcp_f32_e32 v5, v2
	v_mul_f32_e32 v0, 0x3c800000, v132
	v_add_f32_e32 v2, 1.0, v3
	v_add_f32_e32 v3, 1.0, v6
	v_mul_f32_e32 v6, 0x3c800000, v135
	v_mul_f32_e32 v7, 0x3c800000, v131
	v_cndmask_b32_e64 v6, v135, v6, s[62:63]
	v_cndmask_b32_e64 v0, v132, v0, s[62:63]
	v_cndmask_b32_e64 v7, v131, v7, s[62:63]
	v_mul_f32_e32 v6, 0xbfb8aa3b, v6
	v_mul_f32_e32 v0, 0xbfb8aa3b, v0
	v_exp_f32_e32 v14, v6
	v_mul_f32_e32 v6, 0xbfb8aa3b, v7
	v_exp_f32_e32 v0, v0
	v_exp_f32_e32 v7, v6
	v_rcp_f32_e32 v6, v3
	v_add_f32_e32 v3, 1.0, v14
	v_add_f32_e32 v0, 1.0, v0
	v_add_f32_e32 v7, 1.0, v7
	v_rcp_f32_e32 v0, v0
	v_rcp_f32_e32 v1, v1
	v_rcp_f32_e32 v2, v2
	v_rcp_f32_e32 v3, v3
	v_rcp_f32_e32 v7, v7
	s_mov_b64 s[70:71], 0

.LBB0_373:
	v_cvt_pk_bf16_f32 v0, v0, v1
	v_cvt_pk_bf16_f32 v1, v2, v3
	s_nop 0
	v_cvt_pk_bf16_f32 v2, v4, v5
	v_add_u32_e32 v4, 48, v22
	v_mad_i64_i32 v[14:15], s[24:25], s66, v4, 0
	v_cvt_pk_bf16_f32 v3, v6, v7
	v_lshl_add_u64 v[4:5], v[14:15], 1, v[24:25]
	s_and_b64 vcc, exec, s[0:1]
	s_mov_b64 s[70:71], -1
	global_store_dwordx4 v[4:5], v[0:3], off sc1
	s_cbranch_vccnz .LBB0_375
	s_nop 0
	v_mul_f32_e32 v1, 0x3c800000, v120
	v_cndmask_b32_e64 v1, v120, v1, s[62:63]
	v_mul_f32_e32 v2, 0x3c800000, v125
	v_mul_f32_e32 v3, 0x3c800000, v121
	v_mul_f32_e32 v1, 0xbfb8aa3b, v1
	v_cndmask_b32_e64 v2, v125, v2, s[62:63]
	v_cndmask_b32_e64 v3, v121, v3, s[62:63]
	v_exp_f32_e32 v1, v1
	v_mul_f32_e32 v2, 0xbfb8aa3b, v2
	v_mul_f32_e32 v3, 0xbfb8aa3b, v3
	v_exp_f32_e32 v2, v2
	v_exp_f32_e32 v3, v3
	v_add_f32_e32 v1, 1.0, v1
	v_rcp_f32_e32 v4, v1
	v_add_f32_e32 v1, 1.0, v2
	v_add_f32_e32 v2, 1.0, v3
	v_mul_f32_e32 v3, 0x3c800000, v126
	v_mul_f32_e32 v5, 0x3c800000, v122
	v_cndmask_b32_e64 v3, v126, v3, s[62:63]
	v_cndmask_b32_e64 v5, v122, v5, s[62:63]
	v_mul_f32_e32 v3, 0xbfb8aa3b, v3
	v_mul_f32_e32 v5, 0xbfb8aa3b, v5
	v_exp_f32_e32 v3, v3
	v_exp_f32_e32 v6, v5
	v_rcp_f32_e32 v5, v2
	v_mul_f32_e32 v0, 0x3c800000, v124
	v_add_f32_e32 v2, 1.0, v3
	v_add_f32_e32 v3, 1.0, v6
	v_mul_f32_e32 v6, 0x3c800000, v127
	v_mul_f32_e32 v7, 0x3c800000, v123
	v_cndmask_b32_e64 v6, v127, v6, s[62:63]
	v_cndmask_b32_e64 v0, v124, v0, s[62:63]
	v_cndmask_b32_e64 v7, v123, v7, s[62:63]
	v_mul_f32_e32 v6, 0xbfb8aa3b, v6
	v_mul_f32_e32 v0, 0xbfb8aa3b, v0
	v_exp_f32_e32 v16, v6
	v_mul_f32_e32 v6, 0xbfb8aa3b, v7
	v_exp_f32_e32 v0, v0
	v_exp_f32_e32 v7, v6
	v_rcp_f32_e32 v6, v3
	v_add_f32_e32 v3, 1.0, v16
	v_add_f32_e32 v0, 1.0, v0
	v_add_f32_e32 v7, 1.0, v7
	v_rcp_f32_e32 v0, v0
	v_rcp_f32_e32 v1, v1
	v_rcp_f32_e32 v2, v2
	v_rcp_f32_e32 v3, v3
	v_rcp_f32_e32 v7, v7
	s_mov_b64 s[70:71], 0

.LBB0_377:
	v_add_u32_e32 v16, 0x80, v22
	v_mad_i64_i32 v[16:17], s[24:25], s66, v16, 0
	v_cvt_pk_bf16_f32 v0, v0, v1
	v_cvt_pk_bf16_f32 v1, v2, v3
	v_cvt_pk_bf16_f32 v2, v4, v5
	v_cvt_pk_bf16_f32 v3, v6, v7
	v_lshl_add_u64 v[4:5], v[16:17], 1, v[24:25]
	s_and_b64 vcc, exec, s[0:1]
	s_mov_b64 s[70:71], -1
	global_store_dwordx4 v[4:5], v[0:3], off sc1
	s_cbranch_vccnz .LBB0_379
	s_nop 0
	v_mul_f32_e32 v1, 0x3c800000, v112
	v_cndmask_b32_e64 v1, v112, v1, s[62:63]
	v_mul_f32_e32 v2, 0x3c800000, v117
	v_mul_f32_e32 v3, 0x3c800000, v113
	v_mul_f32_e32 v1, 0xbfb8aa3b, v1
	v_cndmask_b32_e64 v2, v117, v2, s[62:63]
	v_cndmask_b32_e64 v3, v113, v3, s[62:63]
	v_exp_f32_e32 v1, v1
	v_mul_f32_e32 v2, 0xbfb8aa3b, v2
	v_mul_f32_e32 v3, 0xbfb8aa3b, v3
	v_exp_f32_e32 v2, v2
	v_exp_f32_e32 v3, v3
	v_add_f32_e32 v1, 1.0, v1
	v_rcp_f32_e32 v4, v1
	v_add_f32_e32 v1, 1.0, v2
	v_add_f32_e32 v2, 1.0, v3
	v_mul_f32_e32 v3, 0x3c800000, v118
	v_mul_f32_e32 v5, 0x3c800000, v114
	v_cndmask_b32_e64 v3, v118, v3, s[62:63]
	v_cndmask_b32_e64 v5, v114, v5, s[62:63]
	v_mul_f32_e32 v3, 0xbfb8aa3b, v3
	v_mul_f32_e32 v5, 0xbfb8aa3b, v5
	v_exp_f32_e32 v3, v3
	v_exp_f32_e32 v6, v5
	v_rcp_f32_e32 v5, v2
	v_mul_f32_e32 v0, 0x3c800000, v116
	v_add_f32_e32 v2, 1.0, v3
	v_add_f32_e32 v3, 1.0, v6
	v_mul_f32_e32 v6, 0x3c800000, v119
	v_mul_f32_e32 v7, 0x3c800000, v115
	v_cndmask_b32_e64 v6, v119, v6, s[62:63]
	v_cndmask_b32_e64 v0, v116, v0, s[62:63]
	v_cndmask_b32_e64 v7, v115, v7, s[62:63]
	v_mul_f32_e32 v6, 0xbfb8aa3b, v6
	v_mul_f32_e32 v0, 0xbfb8aa3b, v0
	v_exp_f32_e32 v18, v6
	v_mul_f32_e32 v6, 0xbfb8aa3b, v7
	v_exp_f32_e32 v0, v0
	v_exp_f32_e32 v7, v6
	v_rcp_f32_e32 v6, v3
	v_add_f32_e32 v3, 1.0, v18
	v_add_f32_e32 v0, 1.0, v0
	v_add_f32_e32 v7, 1.0, v7
	v_rcp_f32_e32 v0, v0
	v_rcp_f32_e32 v1, v1
	v_rcp_f32_e32 v2, v2
	v_rcp_f32_e32 v3, v3
	v_rcp_f32_e32 v7, v7
	s_mov_b64 s[70:71], 0

.LBB0_381:
	v_cvt_pk_bf16_f32 v0, v0, v1
	v_cvt_pk_bf16_f32 v1, v2, v3
	s_nop 0
	v_cvt_pk_bf16_f32 v2, v4, v5
	v_add_u32_e32 v4, 0x90, v22
	v_mad_i64_i32 v[18:19], s[24:25], s66, v4, 0
	v_cvt_pk_bf16_f32 v3, v6, v7
	v_lshl_add_u64 v[4:5], v[18:19], 1, v[24:25]
	s_and_b64 vcc, exec, s[0:1]
	s_mov_b64 s[70:71], -1
	global_store_dwordx4 v[4:5], v[0:3], off sc1
	s_cbranch_vccnz .LBB0_383
	s_nop 0
	v_mul_f32_e32 v1, 0x3c800000, v104
	v_cndmask_b32_e64 v1, v104, v1, s[62:63]
	v_mul_f32_e32 v2, 0x3c800000, v109
	v_mul_f32_e32 v3, 0x3c800000, v105
	v_mul_f32_e32 v1, 0xbfb8aa3b, v1
	v_cndmask_b32_e64 v2, v109, v2, s[62:63]
	v_cndmask_b32_e64 v3, v105, v3, s[62:63]
	v_exp_f32_e32 v1, v1
	v_mul_f32_e32 v2, 0xbfb8aa3b, v2
	v_mul_f32_e32 v3, 0xbfb8aa3b, v3
	v_exp_f32_e32 v2, v2
	v_exp_f32_e32 v3, v3
	v_add_f32_e32 v1, 1.0, v1
	v_rcp_f32_e32 v4, v1
	v_add_f32_e32 v1, 1.0, v2
	v_add_f32_e32 v2, 1.0, v3
	v_mul_f32_e32 v3, 0x3c800000, v110
	v_mul_f32_e32 v5, 0x3c800000, v106
	v_cndmask_b32_e64 v3, v110, v3, s[62:63]
	v_cndmask_b32_e64 v5, v106, v5, s[62:63]
	v_mul_f32_e32 v3, 0xbfb8aa3b, v3
	v_mul_f32_e32 v5, 0xbfb8aa3b, v5
	v_exp_f32_e32 v3, v3
	v_exp_f32_e32 v6, v5
	v_rcp_f32_e32 v5, v2
	v_mul_f32_e32 v0, 0x3c800000, v108
	v_add_f32_e32 v2, 1.0, v3
	v_add_f32_e32 v3, 1.0, v6
	v_mul_f32_e32 v6, 0x3c800000, v111
	v_mul_f32_e32 v7, 0x3c800000, v107
	v_cndmask_b32_e64 v6, v111, v6, s[62:63]
	v_cndmask_b32_e64 v0, v108, v0, s[62:63]
	v_cndmask_b32_e64 v7, v107, v7, s[62:63]
	v_mul_f32_e32 v6, 0xbfb8aa3b, v6
	v_mul_f32_e32 v0, 0xbfb8aa3b, v0
	v_exp_f32_e32 v20, v6
	v_mul_f32_e32 v6, 0xbfb8aa3b, v7
	v_exp_f32_e32 v0, v0
	v_exp_f32_e32 v7, v6
	v_rcp_f32_e32 v6, v3
	v_add_f32_e32 v3, 1.0, v20
	v_add_f32_e32 v0, 1.0, v0
	v_add_f32_e32 v7, 1.0, v7
	v_rcp_f32_e32 v0, v0
	v_rcp_f32_e32 v1, v1
	v_rcp_f32_e32 v2, v2
	v_rcp_f32_e32 v3, v3
	v_rcp_f32_e32 v7, v7
	s_mov_b64 s[70:71], 0

.LBB0_385:
	v_cvt_pk_bf16_f32 v0, v0, v1
	v_cvt_pk_bf16_f32 v1, v2, v3
	s_nop 0
	v_cvt_pk_bf16_f32 v2, v4, v5
	v_add_u32_e32 v4, 0xa0, v22
	v_mad_i64_i32 v[20:21], s[24:25], s66, v4, 0
	v_cvt_pk_bf16_f32 v3, v6, v7
	v_lshl_add_u64 v[4:5], v[20:21], 1, v[24:25]
	s_and_b64 vcc, exec, s[0:1]
	s_mov_b64 s[70:71], -1
	global_store_dwordx4 v[4:5], v[0:3], off sc1
	s_cbranch_vccnz .LBB0_387
	s_nop 0
	v_mul_f32_e32 v1, 0x3c800000, v96
	v_cndmask_b32_e64 v1, v96, v1, s[62:63]
	v_mul_f32_e32 v2, 0x3c800000, v101
	v_mul_f32_e32 v3, 0x3c800000, v97
	v_mul_f32_e32 v1, 0xbfb8aa3b, v1
	v_cndmask_b32_e64 v2, v101, v2, s[62:63]
	v_cndmask_b32_e64 v3, v97, v3, s[62:63]
	v_exp_f32_e32 v1, v1
	v_mul_f32_e32 v2, 0xbfb8aa3b, v2
	v_mul_f32_e32 v3, 0xbfb8aa3b, v3
	v_exp_f32_e32 v2, v2
	v_exp_f32_e32 v3, v3
	v_add_f32_e32 v1, 1.0, v1
	v_rcp_f32_e32 v4, v1
	v_add_f32_e32 v1, 1.0, v2
	v_add_f32_e32 v2, 1.0, v3
	v_mul_f32_e32 v3, 0x3c800000, v102
	v_mul_f32_e32 v5, 0x3c800000, v98
	v_cndmask_b32_e64 v3, v102, v3, s[62:63]
	v_cndmask_b32_e64 v5, v98, v5, s[62:63]
	v_mul_f32_e32 v3, 0xbfb8aa3b, v3
	v_mul_f32_e32 v5, 0xbfb8aa3b, v5
	v_exp_f32_e32 v3, v3
	v_exp_f32_e32 v6, v5
	v_rcp_f32_e32 v5, v2
	v_mul_f32_e32 v0, 0x3c800000, v100
	v_add_f32_e32 v2, 1.0, v3
	v_add_f32_e32 v3, 1.0, v6
	v_mul_f32_e32 v6, 0x3c800000, v103
	v_mul_f32_e32 v7, 0x3c800000, v99
	v_cndmask_b32_e64 v6, v103, v6, s[62:63]
	v_cndmask_b32_e64 v0, v100, v0, s[62:63]
	v_cndmask_b32_e64 v7, v99, v7, s[62:63]
	v_mul_f32_e32 v6, 0xbfb8aa3b, v6
	v_mul_f32_e32 v0, 0xbfb8aa3b, v0
	v_exp_f32_e32 v23, v6
	v_mul_f32_e32 v6, 0xbfb8aa3b, v7
	v_exp_f32_e32 v0, v0
	v_exp_f32_e32 v7, v6
	v_rcp_f32_e32 v6, v3
	v_add_f32_e32 v3, 1.0, v23
	v_add_f32_e32 v0, 1.0, v0
	v_add_f32_e32 v7, 1.0, v7
	v_rcp_f32_e32 v0, v0
	v_rcp_f32_e32 v1, v1
	v_rcp_f32_e32 v2, v2
	v_rcp_f32_e32 v3, v3
	v_rcp_f32_e32 v7, v7
	s_mov_b64 s[70:71], 0

.LBB0_389:
	v_cvt_pk_bf16_f32 v0, v0, v1
	v_cvt_pk_bf16_f32 v1, v2, v3
	s_nop 0
	v_cvt_pk_bf16_f32 v2, v4, v5
	v_add_u32_e32 v4, 0xb0, v22
	v_mad_i64_i32 v[22:23], s[24:25], s66, v4, 0
	v_cvt_pk_bf16_f32 v3, v6, v7
	v_lshl_add_u64 v[4:5], v[22:23], 1, v[24:25]
	s_and_b64 vcc, exec, s[0:1]
	s_mov_b64 s[70:71], -1
	global_store_dwordx4 v[4:5], v[0:3], off sc1
	s_cbranch_vccnz .LBB0_391
	s_nop 0
	v_mul_f32_e32 v1, 0x3c800000, v88
	v_cndmask_b32_e64 v1, v88, v1, s[62:63]
	v_mul_f32_e32 v2, 0x3c800000, v93
	v_mul_f32_e32 v3, 0x3c800000, v89
	v_mul_f32_e32 v1, 0xbfb8aa3b, v1
	v_cndmask_b32_e64 v2, v93, v2, s[62:63]
	v_cndmask_b32_e64 v3, v89, v3, s[62:63]
	v_exp_f32_e32 v1, v1
	v_mul_f32_e32 v2, 0xbfb8aa3b, v2
	v_mul_f32_e32 v3, 0xbfb8aa3b, v3
	v_exp_f32_e32 v2, v2
	v_exp_f32_e32 v3, v3
	v_add_f32_e32 v1, 1.0, v1
	v_rcp_f32_e32 v4, v1
	v_add_f32_e32 v1, 1.0, v2
	v_add_f32_e32 v2, 1.0, v3
	v_mul_f32_e32 v3, 0x3c800000, v94
	v_mul_f32_e32 v5, 0x3c800000, v90
	v_cndmask_b32_e64 v3, v94, v3, s[62:63]
	v_cndmask_b32_e64 v5, v90, v5, s[62:63]
	v_mul_f32_e32 v3, 0xbfb8aa3b, v3
	v_mul_f32_e32 v5, 0xbfb8aa3b, v5
	v_exp_f32_e32 v3, v3
	v_exp_f32_e32 v6, v5
	v_rcp_f32_e32 v5, v2
	v_mul_f32_e32 v0, 0x3c800000, v92
	v_add_f32_e32 v2, 1.0, v3
	v_add_f32_e32 v3, 1.0, v6
	v_mul_f32_e32 v6, 0x3c800000, v95
	v_mul_f32_e32 v7, 0x3c800000, v91
	v_cndmask_b32_e64 v6, v95, v6, s[62:63]
	v_cndmask_b32_e64 v0, v92, v0, s[62:63]
	v_cndmask_b32_e64 v7, v91, v7, s[62:63]
	v_mul_f32_e32 v6, 0xbfb8aa3b, v6
	v_mul_f32_e32 v0, 0xbfb8aa3b, v0
	v_exp_f32_e32 v24, v6
	v_mul_f32_e32 v6, 0xbfb8aa3b, v7
	v_exp_f32_e32 v0, v0
	v_exp_f32_e32 v7, v6
	v_rcp_f32_e32 v6, v3
	v_add_f32_e32 v3, 1.0, v24
	v_add_f32_e32 v0, 1.0, v0
	v_add_f32_e32 v7, 1.0, v7
	v_rcp_f32_e32 v0, v0
	v_rcp_f32_e32 v1, v1
	v_rcp_f32_e32 v2, v2
	v_rcp_f32_e32 v3, v3
	v_rcp_f32_e32 v7, v7
	s_mov_b64 s[70:71], 0

.LBB0_393:
	v_add_u32_e32 v25, 0x80, v26
	v_ashrrev_i32_e32 v24, s8, v25
	v_and_b32_e32 v26, s23, v25
	v_ashrrev_i32_e32 v25, 31, v24
	v_lshlrev_b64 v[24:25], 13, v[24:25]
	v_cndmask_b32_e64 v24, v24, 0, s[62:63]
	v_cndmask_b32_e64 v27, v25, 0, s[62:63]
	v_mad_u64_u32 v[24:25], s[24:25], v24, s66, 0
	v_mad_i32_i24 v25, v27, s66, v25
	v_lshl_add_u64 v[24:25], v[24:25], 1, s[68:69]
	v_ashrrev_i32_e32 v27, 31, v26
	v_lshl_add_u64 v[24:25], v[26:27], 1, v[24:25]
	v_cvt_pk_bf16_f32 v0, v0, v1
	v_cvt_pk_bf16_f32 v1, v2, v3
	v_cvt_pk_bf16_f32 v2, v4, v5
	v_cvt_pk_bf16_f32 v3, v6, v7
	v_lshl_add_u64 v[4:5], v[8:9], 1, v[24:25]
	s_and_b64 vcc, exec, s[0:1]
	s_mov_b64 s[66:67], -1
	global_store_dwordx4 v[4:5], v[0:3], off sc1
	s_cbranch_vccnz .LBB0_395
	s_nop 0
	v_mul_f32_e32 v1, 0x3c800000, v80
	v_cndmask_b32_e64 v1, v80, v1, s[62:63]
	v_mul_f32_e32 v2, 0x3c800000, v85
	v_mul_f32_e32 v3, 0x3c800000, v81
	v_mul_f32_e32 v1, 0xbfb8aa3b, v1
	v_cndmask_b32_e64 v2, v85, v2, s[62:63]
	v_cndmask_b32_e64 v3, v81, v3, s[62:63]
	v_exp_f32_e32 v1, v1
	v_mul_f32_e32 v2, 0xbfb8aa3b, v2
	v_mul_f32_e32 v3, 0xbfb8aa3b, v3
	v_exp_f32_e32 v2, v2
	v_exp_f32_e32 v3, v3
	v_add_f32_e32 v1, 1.0, v1
	v_rcp_f32_e32 v4, v1
	v_add_f32_e32 v1, 1.0, v2
	v_add_f32_e32 v2, 1.0, v3
	v_mul_f32_e32 v3, 0x3c800000, v86
	v_mul_f32_e32 v5, 0x3c800000, v82
	v_cndmask_b32_e64 v3, v86, v3, s[62:63]
	v_cndmask_b32_e64 v5, v82, v5, s[62:63]
	v_mul_f32_e32 v3, 0xbfb8aa3b, v3
	v_mul_f32_e32 v5, 0xbfb8aa3b, v5
	v_exp_f32_e32 v3, v3
	v_exp_f32_e32 v6, v5
	v_rcp_f32_e32 v5, v2
	v_mul_f32_e32 v0, 0x3c800000, v84
	v_add_f32_e32 v2, 1.0, v3
	v_add_f32_e32 v3, 1.0, v6
	v_mul_f32_e32 v6, 0x3c800000, v87
	v_mul_f32_e32 v7, 0x3c800000, v83
	v_cndmask_b32_e64 v6, v87, v6, s[62:63]
	v_cndmask_b32_e64 v0, v84, v0, s[62:63]
	v_cndmask_b32_e64 v7, v83, v7, s[62:63]
	v_mul_f32_e32 v6, 0xbfb8aa3b, v6
	v_mul_f32_e32 v0, 0xbfb8aa3b, v0
	v_exp_f32_e32 v8, v6
	v_mul_f32_e32 v6, 0xbfb8aa3b, v7
	v_exp_f32_e32 v0, v0
	v_exp_f32_e32 v7, v6
	v_rcp_f32_e32 v6, v3
	v_add_f32_e32 v3, 1.0, v8
	v_add_f32_e32 v0, 1.0, v0
	v_add_f32_e32 v7, 1.0, v7
	v_rcp_f32_e32 v0, v0
	v_rcp_f32_e32 v1, v1
	v_rcp_f32_e32 v2, v2
	v_rcp_f32_e32 v3, v3
	v_rcp_f32_e32 v7, v7
	s_mov_b64 s[66:67], 0

.LBB0_397:
	v_cvt_pk_bf16_f32 v0, v0, v1
	v_cvt_pk_bf16_f32 v1, v2, v3
	s_nop 0
	v_cvt_pk_bf16_f32 v2, v4, v5
	v_cvt_pk_bf16_f32 v3, v6, v7
	v_lshl_add_u64 v[4:5], v[10:11], 1, v[24:25]
	s_and_b64 vcc, exec, s[0:1]
	s_mov_b64 s[66:67], -1
	global_store_dwordx4 v[4:5], v[0:3], off sc1
	s_cbranch_vccnz .LBB0_399
	s_nop 0
	v_mul_f32_e32 v1, 0x3c800000, v72
	v_cndmask_b32_e64 v1, v72, v1, s[62:63]
	v_mul_f32_e32 v2, 0x3c800000, v77
	v_mul_f32_e32 v3, 0x3c800000, v73
	v_mul_f32_e32 v1, 0xbfb8aa3b, v1
	v_cndmask_b32_e64 v2, v77, v2, s[62:63]
	v_cndmask_b32_e64 v3, v73, v3, s[62:63]
	v_exp_f32_e32 v1, v1
	v_mul_f32_e32 v2, 0xbfb8aa3b, v2
	v_mul_f32_e32 v3, 0xbfb8aa3b, v3
	v_exp_f32_e32 v2, v2
	v_exp_f32_e32 v3, v3
	v_add_f32_e32 v1, 1.0, v1
	v_rcp_f32_e32 v4, v1
	v_add_f32_e32 v1, 1.0, v2
	v_add_f32_e32 v2, 1.0, v3
	v_mul_f32_e32 v3, 0x3c800000, v78
	v_mul_f32_e32 v5, 0x3c800000, v74
	v_cndmask_b32_e64 v3, v78, v3, s[62:63]
	v_cndmask_b32_e64 v5, v74, v5, s[62:63]
	v_mul_f32_e32 v3, 0xbfb8aa3b, v3
	v_mul_f32_e32 v5, 0xbfb8aa3b, v5
	v_exp_f32_e32 v3, v3
	v_exp_f32_e32 v6, v5
	v_rcp_f32_e32 v5, v2
	v_mul_f32_e32 v0, 0x3c800000, v76
	v_add_f32_e32 v2, 1.0, v3
	v_add_f32_e32 v3, 1.0, v6
	v_mul_f32_e32 v6, 0x3c800000, v79
	v_mul_f32_e32 v7, 0x3c800000, v75
	v_cndmask_b32_e64 v6, v79, v6, s[62:63]
	v_cndmask_b32_e64 v0, v76, v0, s[62:63]
	v_cndmask_b32_e64 v7, v75, v7, s[62:63]
	v_mul_f32_e32 v6, 0xbfb8aa3b, v6
	v_mul_f32_e32 v0, 0xbfb8aa3b, v0
	v_exp_f32_e32 v8, v6
	v_mul_f32_e32 v6, 0xbfb8aa3b, v7
	v_exp_f32_e32 v0, v0
	v_exp_f32_e32 v7, v6
	v_rcp_f32_e32 v6, v3
	v_add_f32_e32 v3, 1.0, v8
	v_add_f32_e32 v0, 1.0, v0
	v_add_f32_e32 v7, 1.0, v7
	v_rcp_f32_e32 v0, v0
	v_rcp_f32_e32 v1, v1
	v_rcp_f32_e32 v2, v2
	v_rcp_f32_e32 v3, v3
	v_rcp_f32_e32 v7, v7
	s_mov_b64 s[66:67], 0

.LBB0_401:
	v_cvt_pk_bf16_f32 v0, v0, v1
	v_cvt_pk_bf16_f32 v1, v2, v3
	s_nop 0
	v_cvt_pk_bf16_f32 v2, v4, v5
	v_cvt_pk_bf16_f32 v3, v6, v7
	v_lshl_add_u64 v[4:5], v[12:13], 1, v[24:25]
	s_and_b64 vcc, exec, s[0:1]
	s_mov_b64 s[66:67], -1
	global_store_dwordx4 v[4:5], v[0:3], off sc1
	s_cbranch_vccnz .LBB0_403
	s_nop 0
	v_mul_f32_e32 v1, 0x3c800000, v64
	v_cndmask_b32_e64 v1, v64, v1, s[62:63]
	v_mul_f32_e32 v2, 0x3c800000, v69
	v_mul_f32_e32 v3, 0x3c800000, v65
	v_mul_f32_e32 v1, 0xbfb8aa3b, v1
	v_cndmask_b32_e64 v2, v69, v2, s[62:63]
	v_cndmask_b32_e64 v3, v65, v3, s[62:63]
	v_exp_f32_e32 v1, v1
	v_mul_f32_e32 v2, 0xbfb8aa3b, v2
	v_mul_f32_e32 v3, 0xbfb8aa3b, v3
	v_exp_f32_e32 v2, v2
	v_exp_f32_e32 v3, v3
	v_add_f32_e32 v1, 1.0, v1
	v_rcp_f32_e32 v4, v1
	v_add_f32_e32 v1, 1.0, v2
	v_add_f32_e32 v2, 1.0, v3
	v_mul_f32_e32 v3, 0x3c800000, v70
	v_mul_f32_e32 v5, 0x3c800000, v66
	v_cndmask_b32_e64 v3, v70, v3, s[62:63]
	v_cndmask_b32_e64 v5, v66, v5, s[62:63]
	v_mul_f32_e32 v3, 0xbfb8aa3b, v3
	v_mul_f32_e32 v5, 0xbfb8aa3b, v5
	v_exp_f32_e32 v3, v3
	v_exp_f32_e32 v6, v5
	v_rcp_f32_e32 v5, v2
	v_mul_f32_e32 v0, 0x3c800000, v68
	v_add_f32_e32 v2, 1.0, v3
	v_add_f32_e32 v3, 1.0, v6
	v_mul_f32_e32 v6, 0x3c800000, v71
	v_mul_f32_e32 v7, 0x3c800000, v67
	v_cndmask_b32_e64 v6, v71, v6, s[62:63]
	v_cndmask_b32_e64 v0, v68, v0, s[62:63]
	v_cndmask_b32_e64 v7, v67, v7, s[62:63]
	v_mul_f32_e32 v6, 0xbfb8aa3b, v6
	v_mul_f32_e32 v0, 0xbfb8aa3b, v0
	v_exp_f32_e32 v8, v6
	v_mul_f32_e32 v6, 0xbfb8aa3b, v7
	v_exp_f32_e32 v0, v0
	v_exp_f32_e32 v7, v6
	v_rcp_f32_e32 v6, v3
	v_add_f32_e32 v3, 1.0, v8
	v_add_f32_e32 v0, 1.0, v0
	v_add_f32_e32 v7, 1.0, v7
	v_rcp_f32_e32 v0, v0
	v_rcp_f32_e32 v1, v1
	v_rcp_f32_e32 v2, v2
	v_rcp_f32_e32 v3, v3
	v_rcp_f32_e32 v7, v7
	s_mov_b64 s[66:67], 0

.LBB0_405:
	v_cvt_pk_bf16_f32 v0, v0, v1
	v_cvt_pk_bf16_f32 v1, v2, v3
	s_nop 0
	v_cvt_pk_bf16_f32 v2, v4, v5
	v_cvt_pk_bf16_f32 v3, v6, v7
	v_lshl_add_u64 v[4:5], v[14:15], 1, v[24:25]
	s_and_b64 vcc, exec, s[0:1]
	s_mov_b64 s[66:67], -1
	global_store_dwordx4 v[4:5], v[0:3], off sc1
	s_cbranch_vccnz .LBB0_407
	s_nop 0
	v_mul_f32_e32 v1, 0x3c800000, v56
	v_cndmask_b32_e64 v1, v56, v1, s[62:63]
	v_mul_f32_e32 v2, 0x3c800000, v61
	v_mul_f32_e32 v3, 0x3c800000, v57
	v_mul_f32_e32 v1, 0xbfb8aa3b, v1
	v_cndmask_b32_e64 v2, v61, v2, s[62:63]
	v_cndmask_b32_e64 v3, v57, v3, s[62:63]
	v_exp_f32_e32 v1, v1
	v_mul_f32_e32 v2, 0xbfb8aa3b, v2
	v_mul_f32_e32 v3, 0xbfb8aa3b, v3
	v_exp_f32_e32 v2, v2
	v_exp_f32_e32 v3, v3
	v_add_f32_e32 v1, 1.0, v1
	v_rcp_f32_e32 v4, v1
	v_add_f32_e32 v1, 1.0, v2
	v_add_f32_e32 v2, 1.0, v3
	v_mul_f32_e32 v3, 0x3c800000, v62
	v_mul_f32_e32 v5, 0x3c800000, v58
	v_cndmask_b32_e64 v3, v62, v3, s[62:63]
	v_cndmask_b32_e64 v5, v58, v5, s[62:63]
	v_mul_f32_e32 v3, 0xbfb8aa3b, v3
	v_mul_f32_e32 v5, 0xbfb8aa3b, v5
	v_exp_f32_e32 v3, v3
	v_exp_f32_e32 v6, v5
	v_rcp_f32_e32 v5, v2
	v_mul_f32_e32 v0, 0x3c800000, v60
	v_add_f32_e32 v2, 1.0, v3
	v_add_f32_e32 v3, 1.0, v6
	v_mul_f32_e32 v6, 0x3c800000, v63
	v_mul_f32_e32 v7, 0x3c800000, v59
	v_cndmask_b32_e64 v6, v63, v6, s[62:63]
	v_cndmask_b32_e64 v0, v60, v0, s[62:63]
	v_cndmask_b32_e64 v7, v59, v7, s[62:63]
	v_mul_f32_e32 v6, 0xbfb8aa3b, v6
	v_mul_f32_e32 v0, 0xbfb8aa3b, v0
	v_exp_f32_e32 v8, v6
	v_mul_f32_e32 v6, 0xbfb8aa3b, v7
	v_exp_f32_e32 v0, v0
	v_exp_f32_e32 v7, v6
	v_rcp_f32_e32 v6, v3
	v_add_f32_e32 v3, 1.0, v8
	v_add_f32_e32 v0, 1.0, v0
	v_add_f32_e32 v7, 1.0, v7
	v_rcp_f32_e32 v0, v0
	v_rcp_f32_e32 v1, v1
	v_rcp_f32_e32 v2, v2
	v_rcp_f32_e32 v3, v3
	v_rcp_f32_e32 v7, v7
	s_mov_b64 s[66:67], 0

.LBB0_409:
	v_cvt_pk_bf16_f32 v0, v0, v1
	v_cvt_pk_bf16_f32 v1, v2, v3
	s_nop 0
	v_cvt_pk_bf16_f32 v2, v4, v5
	v_cvt_pk_bf16_f32 v3, v6, v7
	v_lshl_add_u64 v[4:5], v[16:17], 1, v[24:25]
	s_and_b64 vcc, exec, s[0:1]
	s_mov_b64 s[66:67], -1
	global_store_dwordx4 v[4:5], v[0:3], off sc1
	s_cbranch_vccnz .LBB0_411
	s_nop 0
	v_mul_f32_e32 v1, 0x3c800000, v48
	v_cndmask_b32_e64 v1, v48, v1, s[62:63]
	v_mul_f32_e32 v2, 0x3c800000, v53
	v_mul_f32_e32 v3, 0x3c800000, v49
	v_mul_f32_e32 v1, 0xbfb8aa3b, v1
	v_cndmask_b32_e64 v2, v53, v2, s[62:63]
	v_cndmask_b32_e64 v3, v49, v3, s[62:63]
	v_exp_f32_e32 v1, v1
	v_mul_f32_e32 v2, 0xbfb8aa3b, v2
	v_mul_f32_e32 v3, 0xbfb8aa3b, v3
	v_exp_f32_e32 v2, v2
	v_exp_f32_e32 v3, v3
	v_add_f32_e32 v1, 1.0, v1
	v_rcp_f32_e32 v4, v1
	v_add_f32_e32 v1, 1.0, v2
	v_add_f32_e32 v2, 1.0, v3
	v_mul_f32_e32 v3, 0x3c800000, v54
	v_mul_f32_e32 v5, 0x3c800000, v50
	v_cndmask_b32_e64 v3, v54, v3, s[62:63]
	v_cndmask_b32_e64 v5, v50, v5, s[62:63]
	v_mul_f32_e32 v3, 0xbfb8aa3b, v3
	v_mul_f32_e32 v5, 0xbfb8aa3b, v5
	v_exp_f32_e32 v3, v3
	v_exp_f32_e32 v6, v5
	v_rcp_f32_e32 v5, v2
	v_mul_f32_e32 v0, 0x3c800000, v52
	v_add_f32_e32 v2, 1.0, v3
	v_add_f32_e32 v3, 1.0, v6
	v_mul_f32_e32 v6, 0x3c800000, v55
	v_mul_f32_e32 v7, 0x3c800000, v51
	v_cndmask_b32_e64 v6, v55, v6, s[62:63]
	v_cndmask_b32_e64 v0, v52, v0, s[62:63]
	v_cndmask_b32_e64 v7, v51, v7, s[62:63]
	v_mul_f32_e32 v6, 0xbfb8aa3b, v6
	v_mul_f32_e32 v0, 0xbfb8aa3b, v0
	v_exp_f32_e32 v8, v6
	v_mul_f32_e32 v6, 0xbfb8aa3b, v7
	v_exp_f32_e32 v0, v0
	v_exp_f32_e32 v7, v6
	v_rcp_f32_e32 v6, v3
	v_add_f32_e32 v3, 1.0, v8
	v_add_f32_e32 v0, 1.0, v0
	v_add_f32_e32 v7, 1.0, v7
	v_rcp_f32_e32 v0, v0
	v_rcp_f32_e32 v1, v1
	v_rcp_f32_e32 v2, v2
	v_rcp_f32_e32 v3, v3
	v_rcp_f32_e32 v7, v7
	s_mov_b64 s[66:67], 0

.LBB0_413:
	v_cvt_pk_bf16_f32 v0, v0, v1
	v_cvt_pk_bf16_f32 v1, v2, v3
	s_nop 0
	v_cvt_pk_bf16_f32 v2, v4, v5
	v_cvt_pk_bf16_f32 v3, v6, v7
	v_lshl_add_u64 v[4:5], v[18:19], 1, v[24:25]
	s_and_b64 vcc, exec, s[0:1]
	s_mov_b64 s[66:67], -1
	global_store_dwordx4 v[4:5], v[0:3], off sc1
	s_cbranch_vccnz .LBB0_415
	s_nop 0
	v_mul_f32_e32 v1, 0x3c800000, v40
	v_cndmask_b32_e64 v1, v40, v1, s[62:63]
	v_mul_f32_e32 v2, 0x3c800000, v45
	v_mul_f32_e32 v3, 0x3c800000, v41
	v_mul_f32_e32 v1, 0xbfb8aa3b, v1
	v_cndmask_b32_e64 v2, v45, v2, s[62:63]
	v_cndmask_b32_e64 v3, v41, v3, s[62:63]
	v_exp_f32_e32 v1, v1
	v_mul_f32_e32 v2, 0xbfb8aa3b, v2
	v_mul_f32_e32 v3, 0xbfb8aa3b, v3
	v_exp_f32_e32 v2, v2
	v_exp_f32_e32 v3, v3
	v_add_f32_e32 v1, 1.0, v1
	v_rcp_f32_e32 v4, v1
	v_add_f32_e32 v1, 1.0, v2
	v_add_f32_e32 v2, 1.0, v3
	v_mul_f32_e32 v3, 0x3c800000, v46
	v_mul_f32_e32 v5, 0x3c800000, v42
	v_cndmask_b32_e64 v3, v46, v3, s[62:63]
	v_cndmask_b32_e64 v5, v42, v5, s[62:63]
	v_mul_f32_e32 v3, 0xbfb8aa3b, v3
	v_mul_f32_e32 v5, 0xbfb8aa3b, v5
	v_exp_f32_e32 v3, v3
	v_exp_f32_e32 v6, v5
	v_rcp_f32_e32 v5, v2
	v_mul_f32_e32 v0, 0x3c800000, v44
	v_add_f32_e32 v2, 1.0, v3
	v_add_f32_e32 v3, 1.0, v6
	v_mul_f32_e32 v6, 0x3c800000, v47
	v_mul_f32_e32 v7, 0x3c800000, v43
	v_cndmask_b32_e64 v6, v47, v6, s[62:63]
	v_cndmask_b32_e64 v0, v44, v0, s[62:63]
	v_cndmask_b32_e64 v7, v43, v7, s[62:63]
	v_mul_f32_e32 v6, 0xbfb8aa3b, v6
	v_mul_f32_e32 v0, 0xbfb8aa3b, v0
	v_exp_f32_e32 v8, v6
	v_mul_f32_e32 v6, 0xbfb8aa3b, v7
	v_exp_f32_e32 v0, v0
	v_exp_f32_e32 v7, v6
	v_rcp_f32_e32 v6, v3
	v_add_f32_e32 v3, 1.0, v8
	v_add_f32_e32 v0, 1.0, v0
	v_add_f32_e32 v7, 1.0, v7
	v_rcp_f32_e32 v0, v0
	v_rcp_f32_e32 v1, v1
	v_rcp_f32_e32 v2, v2
	v_rcp_f32_e32 v3, v3
	v_rcp_f32_e32 v7, v7
	s_mov_b64 s[66:67], 0

.LBB0_417:
	v_cvt_pk_bf16_f32 v0, v0, v1
	v_cvt_pk_bf16_f32 v1, v2, v3
	s_nop 0
	v_cvt_pk_bf16_f32 v2, v4, v5
	v_cvt_pk_bf16_f32 v3, v6, v7
	v_lshl_add_u64 v[4:5], v[20:21], 1, v[24:25]
	s_and_b64 vcc, exec, s[0:1]
	s_mov_b64 s[0:1], -1
	global_store_dwordx4 v[4:5], v[0:3], off sc1
	s_cbranch_vccnz .LBB0_419
	s_nop 0
	v_mul_f32_e32 v1, 0x3c800000, v32
	v_cndmask_b32_e64 v1, v32, v1, s[62:63]
	v_mul_f32_e32 v2, 0x3c800000, v37
	v_mul_f32_e32 v3, 0x3c800000, v33
	v_mul_f32_e32 v1, 0xbfb8aa3b, v1
	v_cndmask_b32_e64 v2, v37, v2, s[62:63]
	v_cndmask_b32_e64 v3, v33, v3, s[62:63]
	v_exp_f32_e32 v1, v1
	v_mul_f32_e32 v2, 0xbfb8aa3b, v2
	v_mul_f32_e32 v3, 0xbfb8aa3b, v3
	v_exp_f32_e32 v2, v2
	v_exp_f32_e32 v3, v3
	v_add_f32_e32 v1, 1.0, v1
	v_rcp_f32_e32 v4, v1
	v_add_f32_e32 v1, 1.0, v2
	v_add_f32_e32 v2, 1.0, v3
	v_mul_f32_e32 v3, 0x3c800000, v38
	v_mul_f32_e32 v5, 0x3c800000, v34
	v_cndmask_b32_e64 v3, v38, v3, s[62:63]
	v_cndmask_b32_e64 v5, v34, v5, s[62:63]
	v_mul_f32_e32 v3, 0xbfb8aa3b, v3
	v_mul_f32_e32 v5, 0xbfb8aa3b, v5
	v_exp_f32_e32 v3, v3
	v_exp_f32_e32 v6, v5
	v_rcp_f32_e32 v5, v2
	v_mul_f32_e32 v0, 0x3c800000, v36
	v_add_f32_e32 v2, 1.0, v3
	v_add_f32_e32 v3, 1.0, v6
	v_mul_f32_e32 v6, 0x3c800000, v39
	v_mul_f32_e32 v7, 0x3c800000, v35
	v_cndmask_b32_e64 v6, v39, v6, s[62:63]
	v_cndmask_b32_e64 v0, v36, v0, s[62:63]
	v_cndmask_b32_e64 v7, v35, v7, s[62:63]
	v_mul_f32_e32 v6, 0xbfb8aa3b, v6
	v_mul_f32_e32 v0, 0xbfb8aa3b, v0
	v_exp_f32_e32 v8, v6
	v_mul_f32_e32 v6, 0xbfb8aa3b, v7
	v_exp_f32_e32 v0, v0
	v_exp_f32_e32 v7, v6
	v_rcp_f32_e32 v6, v3
	v_add_f32_e32 v3, 1.0, v8
	v_add_f32_e32 v0, 1.0, v0
	v_add_f32_e32 v7, 1.0, v7
	v_rcp_f32_e32 v0, v0
	v_rcp_f32_e32 v1, v1
	v_rcp_f32_e32 v2, v2
	v_rcp_f32_e32 v3, v3
	v_rcp_f32_e32 v7, v7
	s_mov_b64 s[0:1], 0

.LBB0_421:
	v_cvt_pk_bf16_f32 v0, v0, v1
	v_cvt_pk_bf16_f32 v1, v2, v3
	s_nop 0
	v_cvt_pk_bf16_f32 v2, v4, v5
	v_lshl_add_u64 v[4:5], v[22:23], 1, v[24:25]
	s_andn2_b64 vcc, exec, s[42:43]
	s_mov_b64 s[0:1], -1
	v_cvt_pk_bf16_f32 v3, v6, v7
	global_store_dwordx4 v[4:5], v[0:3], off sc1
	s_cbranch_vccnz .LBB0_335
	s_andn2_b64 vcc, exec, s[10:11]
	s_cbranch_vccnz .LBB0_334
	s_barrier
	s_branch .LBB0_334

.LBB0_467:
	s_or_b64 exec, exec, s[10:11]
	ds_write2_b32 v84, v60, v61 offset1:1
	ds_write2_b32 v84, v62, v63 offset0:2 offset1:3
	v_add_u32_e32 v60, 0x420, v84
	ds_write2_b32 v60, v52, v53 offset1:1
	v_add_u32_e32 v52, 0x428, v84
	ds_write2_b32 v52, v54, v55 offset1:1
	v_add_u32_e32 v52, 0x840, v84
	ds_write2_b32 v52, v56, v57 offset1:1
	v_add_u32_e32 v52, 0x848, v84
	ds_write2_b32 v52, v58, v59 offset1:1
	v_add_u32_e32 v52, 0xc60, v84
	ds_write2_b32 v52, v44, v45 offset1:1
	v_add_u32_e32 v44, 0xc68, v84
	ds_write2_b32 v44, v46, v47 offset1:1
	v_add_u32_e32 v44, 0x1080, v84
	ds_write2_b32 v44, v48, v49 offset1:1
	v_add_u32_e32 v44, 0x1088, v84
	ds_write2_b32 v44, v50, v51 offset1:1
	v_add_u32_e32 v44, 0x14a0, v84
	ds_write2_b32 v44, v36, v37 offset1:1
	v_add_u32_e32 v36, 0x14a8, v84
	ds_write2_b32 v36, v38, v39 offset1:1
	v_add_u32_e32 v36, 0x18c0, v84
	ds_write2_b32 v36, v40, v41 offset1:1
	v_add_u32_e32 v36, 0x18c8, v84
	ds_write2_b32 v36, v42, v43 offset1:1
	v_add_u32_e32 v36, 0x1ce0, v84
	ds_write2_b32 v36, v32, v33 offset1:1
	v_add_u32_e32 v32, 0x1ce8, v84
	ds_write2_b32 v32, v34, v35 offset1:1
	s_waitcnt lgkmcnt(0)
	v_add_u32_e32 v34, v72, v78
	v_cmp_ne_u32_e32 vcc, 0, v65
	v_ashrrev_i32_e32 v65, 31, v64
	v_ashrrev_i32_e32 v33, 31, v34
	s_and_saveexec_b64 s[10:11], vcc
	s_xor_b64 s[10:11], exec, s[10:11]
	s_cbranch_execz .LBB0_469
	ds_read2_b32 v[36:37], v82 offset1:33
	ds_read2_b32 v[40:41], v82 offset0:66 offset1:99
	ds_read2_b32 v[42:43], v82 offset0:132 offset1:165
	v_mov_b32_e32 v38, v69
	v_mov_b32_e32 v39, v69
	s_waitcnt lgkmcnt(2)
	v_mul_f32_e32 v32, 0x42800000, v36
	v_mul_f32_e32 v35, 0x42800000, v37
	ds_read2_b32 v[36:37], v82 offset0:198 offset1:231
	v_cvt_pk_fp8_f32 v38, v32, v35
	s_waitcnt lgkmcnt(2)
	v_mul_f32_e32 v32, 0x42800000, v40
	v_mul_f32_e32 v35, 0x42800000, v41
	s_waitcnt lgkmcnt(1)
	v_mul_f32_e32 v40, 0x42800000, v42
	v_mul_f32_e32 v41, 0x42800000, v43
	v_cvt_pk_fp8_f32 v39, v40, v41
	v_cvt_pk_fp8_f32 v38, v32, v35 op_sel:[0,0,1]
	s_waitcnt lgkmcnt(0)
	v_mul_f32_e32 v32, 0x42800000, v36
	v_mul_f32_e32 v35, 0x42800000, v37
	v_cvt_pk_fp8_f32 v39, v32, v35 op_sel:[0,0,1]
	v_mad_u64_u32 v[34:35], s[12:13], v34, v73, v[66:67]
	v_mov_b32_e32 v32, v35
	v_mad_u64_u32 v[32:33], s[12:13], v33, v73, v[32:33]
	v_mov_b32_e32 v35, v32
	v_lshl_add_u64 v[32:33], v[34:35], 0, v[64:65]
	v_lshl_add_u64 v[32:33], v[32:33], 0, v[70:71]
	global_store_dwordx2 v[32:33], v[38:39], off sc1
.LBB0_469:
	s_or_saveexec_b64 s[10:11], s[10:11]
	v_lshlrev_b32_e32 v32, 1, v70
	s_xor_b64 exec, exec, s[10:11]
	s_cbranch_execz .LBB0_471
	ds_read2_b32 v[36:37], v82 offset1:33
	ds_read2_b32 v[38:39], v82 offset0:66 offset1:99
	ds_read2_b32 v[42:43], v82 offset0:198 offset1:231
	s_waitcnt lgkmcnt(2)
	v_bfe_u32 v35, v36, 16, 1
	v_bfe_u32 v40, v37, 16, 1
	v_add3_u32 v35, v36, v35, s46
	s_waitcnt lgkmcnt(1)
	v_bfe_u32 v41, v38, 16, 1
	v_add3_u32 v36, v37, v40, s46
	v_lshrrev_b32_e32 v35, 16, v35
	v_and_or_b32 v36, v36, s47, v35
	v_add3_u32 v35, v38, v41, s46
	ds_read2_b32 v[40:41], v82 offset0:132 offset1:165
	v_bfe_u32 v37, v39, 16, 1
	v_lshrrev_b32_e32 v35, 16, v35
	v_add3_u32 v37, v39, v37, s46
	v_and_or_b32 v37, v37, s47, v35
	s_waitcnt lgkmcnt(0)
	v_bfe_u32 v35, v40, 16, 1
	v_add3_u32 v35, v40, v35, s46
	v_bfe_u32 v38, v41, 16, 1
	v_lshrrev_b32_e32 v35, 16, v35
	v_add3_u32 v38, v41, v38, s46
	v_and_or_b32 v38, v38, s47, v35
	v_bfe_u32 v35, v42, 16, 1
	v_add3_u32 v35, v42, v35, s46
	v_bfe_u32 v39, v43, 16, 1
	v_lshrrev_b32_e32 v35, 16, v35
	v_add3_u32 v39, v43, v39, s46
	v_and_or_b32 v39, v39, s47, v35
	v_mad_u64_u32 v[34:35], s[12:13], v34, v73, 0
	v_mov_b32_e32 v40, v35
	v_mad_u64_u32 v[40:41], s[12:13], v33, v73, v[40:41]
	v_mov_b32_e32 v35, v40
	v_lshl_add_u64 v[34:35], v[34:35], 1, v[66:67]
	v_lshl_add_u64 v[34:35], v[64:65], 1, v[34:35]
	v_mov_b32_e32 v33, v69
	v_lshl_add_u64 v[34:35], v[34:35], 0, v[32:33]
	global_store_dwordx4 v[34:35], v[36:39], off sc1
.LBB0_471:
	s_or_b64 exec, exec, s[10:11]
	v_add_u32_e32 v34, v72, v79
	v_ashrrev_i32_e32 v33, 31, v34
	s_and_saveexec_b64 s[10:11], vcc
	s_xor_b64 s[10:11], exec, s[10:11]
	s_cbranch_execz .LBB0_473
	ds_read2_b32 v[36:37], v82 offset0:8 offset1:41
	ds_read2_b32 v[40:41], v82 offset0:74 offset1:107
	ds_read2_b32 v[42:43], v82 offset0:140 offset1:173
	v_mov_b32_e32 v38, v69
	v_mov_b32_e32 v39, v69
	s_waitcnt lgkmcnt(2)
	v_mul_f32_e32 v35, 0x42800000, v36
	v_mul_f32_e32 v36, 0x42800000, v37
	v_cvt_pk_fp8_f32 v38, v35, v36
	ds_read2_b32 v[36:37], v82 offset0:206 offset1:239
	s_waitcnt lgkmcnt(2)
	v_mul_f32_e32 v35, 0x42800000, v40
	v_mul_f32_e32 v40, 0x42800000, v41
	s_waitcnt lgkmcnt(1)
	v_mul_f32_e32 v41, 0x42800000, v42
	v_mul_f32_e32 v42, 0x42800000, v43
	v_cvt_pk_fp8_f32 v39, v41, v42
	v_cvt_pk_fp8_f32 v38, v35, v40 op_sel:[0,0,1]
	s_waitcnt lgkmcnt(0)
	v_mul_f32_e32 v35, 0x42800000, v36
	v_mul_f32_e32 v36, 0x42800000, v37
	v_cvt_pk_fp8_f32 v39, v35, v36 op_sel:[0,0,1]
	v_mad_u64_u32 v[34:35], s[12:13], v34, v73, v[66:67]
	v_mov_b32_e32 v36, v35
	v_mad_u64_u32 v[36:37], s[12:13], v33, v73, v[36:37]
	v_mov_b32_e32 v35, v36
	v_lshl_add_u64 v[34:35], v[34:35], 0, v[64:65]
	v_lshl_add_u64 v[34:35], v[34:35], 0, v[70:71]
	global_store_dwordx2 v[34:35], v[38:39], off sc1
.LBB0_473:
	s_andn2_saveexec_b64 s[10:11], s[10:11]
	s_cbranch_execz .LBB0_475
	ds_read2_b32 v[36:37], v82 offset0:8 offset1:41
	ds_read2_b32 v[38:39], v82 offset0:74 offset1:107
	ds_read2_b32 v[42:43], v82 offset0:206 offset1:239
	s_waitcnt lgkmcnt(2)
	v_bfe_u32 v35, v36, 16, 1
	v_bfe_u32 v40, v37, 16, 1
	v_add3_u32 v35, v36, v35, s46
	s_waitcnt lgkmcnt(1)
	v_bfe_u32 v41, v38, 16, 1
	v_add3_u32 v36, v37, v40, s46
	v_lshrrev_b32_e32 v35, 16, v35
	v_and_or_b32 v36, v36, s47, v35
	v_add3_u32 v35, v38, v41, s46
	ds_read2_b32 v[40:41], v82 offset0:140 offset1:173
	v_bfe_u32 v37, v39, 16, 1
	v_lshrrev_b32_e32 v35, 16, v35
	v_add3_u32 v37, v39, v37, s46
	v_and_or_b32 v37, v37, s47, v35
	s_waitcnt lgkmcnt(0)
	v_bfe_u32 v35, v40, 16, 1
	v_add3_u32 v35, v40, v35, s46
	v_bfe_u32 v38, v41, 16, 1
	v_lshrrev_b32_e32 v35, 16, v35
	v_add3_u32 v38, v41, v38, s46
	v_and_or_b32 v38, v38, s47, v35
	v_bfe_u32 v35, v42, 16, 1
	v_add3_u32 v35, v42, v35, s46
	v_bfe_u32 v39, v43, 16, 1
	v_lshrrev_b32_e32 v35, 16, v35
	v_add3_u32 v39, v43, v39, s46
	v_and_or_b32 v39, v39, s47, v35
	v_mad_u64_u32 v[34:35], s[12:13], v34, v73, 0
	v_mov_b32_e32 v40, v35
	v_mad_u64_u32 v[40:41], s[12:13], v33, v73, v[40:41]
	v_mov_b32_e32 v35, v40
	v_lshl_add_u64 v[34:35], v[34:35], 1, v[66:67]
	v_lshl_add_u64 v[34:35], v[64:65], 1, v[34:35]
	v_mov_b32_e32 v33, v69
	v_lshl_add_u64 v[34:35], v[34:35], 0, v[32:33]
	global_store_dwordx4 v[34:35], v[36:39], off sc1
.LBB0_475:
	s_or_b64 exec, exec, s[10:11]
	v_add_u32_e32 v34, v72, v80
	v_ashrrev_i32_e32 v33, 31, v34
	s_and_saveexec_b64 s[10:11], vcc
	s_xor_b64 s[10:11], exec, s[10:11]
	s_cbranch_execz .LBB0_477
	ds_read2_b32 v[36:37], v82 offset0:16 offset1:49
	ds_read2_b32 v[40:41], v82 offset0:82 offset1:115
	ds_read2_b32 v[42:43], v82 offset0:148 offset1:181
	v_mov_b32_e32 v38, v69
	v_mov_b32_e32 v39, v69
	s_waitcnt lgkmcnt(2)
	v_mul_f32_e32 v35, 0x42800000, v36
	v_mul_f32_e32 v36, 0x42800000, v37
	v_cvt_pk_fp8_f32 v38, v35, v36
	ds_read2_b32 v[36:37], v82 offset0:214 offset1:247
	s_waitcnt lgkmcnt(2)
	v_mul_f32_e32 v35, 0x42800000, v40
	v_mul_f32_e32 v40, 0x42800000, v41
	s_waitcnt lgkmcnt(1)
	v_mul_f32_e32 v41, 0x42800000, v42
	v_mul_f32_e32 v42, 0x42800000, v43
	v_cvt_pk_fp8_f32 v39, v41, v42
	v_cvt_pk_fp8_f32 v38, v35, v40 op_sel:[0,0,1]
	s_waitcnt lgkmcnt(0)
	v_mul_f32_e32 v35, 0x42800000, v36
	v_mul_f32_e32 v36, 0x42800000, v37
	v_cvt_pk_fp8_f32 v39, v35, v36 op_sel:[0,0,1]
	v_mad_u64_u32 v[34:35], s[12:13], v34, v73, v[66:67]
	v_mov_b32_e32 v36, v35
	v_mad_u64_u32 v[36:37], s[12:13], v33, v73, v[36:37]
	v_mov_b32_e32 v35, v36
	v_lshl_add_u64 v[34:35], v[34:35], 0, v[64:65]
	v_lshl_add_u64 v[34:35], v[34:35], 0, v[70:71]
	global_store_dwordx2 v[34:35], v[38:39], off sc1
.LBB0_477:
	s_andn2_saveexec_b64 s[10:11], s[10:11]
	s_cbranch_execz .LBB0_479
	ds_read2_b32 v[36:37], v82 offset0:16 offset1:49
	ds_read2_b32 v[38:39], v82 offset0:82 offset1:115
	ds_read2_b32 v[42:43], v82 offset0:214 offset1:247
	s_waitcnt lgkmcnt(2)
	v_bfe_u32 v35, v36, 16, 1
	v_bfe_u32 v40, v37, 16, 1
	v_add3_u32 v35, v36, v35, s46
	s_waitcnt lgkmcnt(1)
	v_bfe_u32 v41, v38, 16, 1
	v_add3_u32 v36, v37, v40, s46
	v_lshrrev_b32_e32 v35, 16, v35
	v_and_or_b32 v36, v36, s47, v35
	v_add3_u32 v35, v38, v41, s46
	ds_read2_b32 v[40:41], v82 offset0:148 offset1:181
	v_bfe_u32 v37, v39, 16, 1
	v_lshrrev_b32_e32 v35, 16, v35
	v_add3_u32 v37, v39, v37, s46
	v_and_or_b32 v37, v37, s47, v35
	s_waitcnt lgkmcnt(0)
	v_bfe_u32 v35, v40, 16, 1
	v_add3_u32 v35, v40, v35, s46
	v_bfe_u32 v38, v41, 16, 1
	v_lshrrev_b32_e32 v35, 16, v35
	v_add3_u32 v38, v41, v38, s46
	v_and_or_b32 v38, v38, s47, v35
	v_bfe_u32 v35, v42, 16, 1
	v_add3_u32 v35, v42, v35, s46
	v_bfe_u32 v39, v43, 16, 1
	v_lshrrev_b32_e32 v35, 16, v35
	v_add3_u32 v39, v43, v39, s46
	v_and_or_b32 v39, v39, s47, v35
	v_mad_u64_u32 v[34:35], s[12:13], v34, v73, 0
	v_mov_b32_e32 v40, v35
	v_mad_u64_u32 v[40:41], s[12:13], v33, v73, v[40:41]
	v_mov_b32_e32 v35, v40
	v_lshl_add_u64 v[34:35], v[34:35], 1, v[66:67]
	v_lshl_add_u64 v[34:35], v[64:65], 1, v[34:35]
	v_mov_b32_e32 v33, v69
	v_lshl_add_u64 v[34:35], v[34:35], 0, v[32:33]
	global_store_dwordx4 v[34:35], v[36:39], off sc1
.LBB0_479:
	s_or_b64 exec, exec, s[10:11]
	v_add_u32_e32 v34, v72, v81
	v_ashrrev_i32_e32 v33, 31, v34
	s_and_saveexec_b64 s[10:11], vcc
	s_xor_b64 s[10:11], exec, s[10:11]
	s_cbranch_execz .LBB0_481
	ds_read2_b32 v[36:37], v82 offset0:24 offset1:57
	ds_read2_b32 v[40:41], v82 offset0:90 offset1:123
	ds_read2_b32 v[42:43], v82 offset0:156 offset1:189
	v_mov_b32_e32 v38, v69
	v_mov_b32_e32 v39, v69
	s_waitcnt lgkmcnt(2)
	v_mul_f32_e32 v32, 0x42800000, v36
	v_mul_f32_e32 v35, 0x42800000, v37
	ds_read2_b32 v[36:37], v82 offset0:222 offset1:255
	v_cvt_pk_fp8_f32 v38, v32, v35
	s_waitcnt lgkmcnt(2)
	v_mul_f32_e32 v32, 0x42800000, v40
	v_mul_f32_e32 v35, 0x42800000, v41
	s_waitcnt lgkmcnt(1)
	v_mul_f32_e32 v40, 0x42800000, v42
	v_mul_f32_e32 v41, 0x42800000, v43
	v_cvt_pk_fp8_f32 v39, v40, v41
	v_cvt_pk_fp8_f32 v38, v32, v35 op_sel:[0,0,1]
	s_waitcnt lgkmcnt(0)
	v_mul_f32_e32 v32, 0x42800000, v36
	v_mul_f32_e32 v35, 0x42800000, v37
	v_cvt_pk_fp8_f32 v39, v32, v35 op_sel:[0,0,1]
	v_mad_u64_u32 v[34:35], s[12:13], v34, v73, v[66:67]
	v_mov_b32_e32 v32, v35
	v_mad_u64_u32 v[32:33], s[12:13], v33, v73, v[32:33]
	v_mov_b32_e32 v35, v32
	v_lshl_add_u64 v[32:33], v[34:35], 0, v[64:65]
	v_lshl_add_u64 v[32:33], v[32:33], 0, v[70:71]
	global_store_dwordx2 v[32:33], v[38:39], off sc1
.LBB0_481:
	s_andn2_saveexec_b64 s[10:11], s[10:11]
	s_cbranch_execz .LBB0_448
	ds_read2_b32 v[36:37], v82 offset0:24 offset1:57
	ds_read2_b32 v[38:39], v82 offset0:90 offset1:123
	ds_read2_b32 v[42:43], v82 offset0:222 offset1:255
	s_waitcnt lgkmcnt(2)
	v_bfe_u32 v35, v36, 16, 1
	v_bfe_u32 v40, v37, 16, 1
	v_add3_u32 v35, v36, v35, s46
	s_waitcnt lgkmcnt(1)
	v_bfe_u32 v41, v38, 16, 1
	v_add3_u32 v36, v37, v40, s46
	v_lshrrev_b32_e32 v35, 16, v35
	v_and_or_b32 v36, v36, s47, v35
	v_add3_u32 v35, v38, v41, s46
	ds_read2_b32 v[40:41], v82 offset0:156 offset1:189
	v_bfe_u32 v37, v39, 16, 1
	v_lshrrev_b32_e32 v35, 16, v35
	v_add3_u32 v37, v39, v37, s46
	v_and_or_b32 v37, v37, s47, v35
	s_waitcnt lgkmcnt(0)
	v_bfe_u32 v35, v40, 16, 1
	v_add3_u32 v35, v40, v35, s46
	v_bfe_u32 v38, v41, 16, 1
	v_lshrrev_b32_e32 v35, 16, v35
	v_add3_u32 v38, v41, v38, s46
	v_and_or_b32 v38, v38, s47, v35
	v_bfe_u32 v35, v42, 16, 1
	v_add3_u32 v35, v42, v35, s46
	v_bfe_u32 v39, v43, 16, 1
	v_lshrrev_b32_e32 v35, 16, v35
	v_add3_u32 v39, v43, v39, s46
	v_and_or_b32 v39, v39, s47, v35
	v_mad_u64_u32 v[34:35], s[12:13], v34, v73, 0
	v_mov_b32_e32 v40, v35
	v_mad_u64_u32 v[40:41], s[12:13], v33, v73, v[40:41]
	v_mov_b32_e32 v35, v40
	v_lshl_add_u64 v[34:35], v[34:35], 1, v[66:67]
	v_lshl_add_u64 v[34:35], v[64:65], 1, v[34:35]
	v_mov_b32_e32 v33, v69
	v_lshl_add_u64 v[32:33], v[34:35], 0, v[32:33]
	global_store_dwordx4 v[32:33], v[36:39], off sc1
	s_branch .LBB0_448

.Lfx_body:
	s_cmp_lt_u32 s62, 0x4000005e
	s_cselect_b64 s[78:79], -1, 0
	s_andn2_b64 vcc, exec, s[78:79]
	s_cbranch_vccnz .Lfx_h1_done
	s_andn2_b64 vcc, exec, s[80:81]
	s_cbranch_vccnz .Lfx_h1_qonly
	s_lshl_b32 s64, s41, 7
	s_mov_b32 s66, s64
	s_ashr_i32 s67, s64, 31
	s_lshl_b64 s[30:31], s[66:67], 8
	s_add_u32 s30, s23, s30
	s_addc_u32 s31, s24, s31
	s_add_i32 s66, s64, 0xffffff80
	s_ashr_i32 s67, s66, 31
	s_lshl_b64 s[28:29], s[66:67], 8
	s_add_u32 s28, s27, s28
	s_addc_u32 s29, s38, s29
	s_lshl_b64 s[68:69], s[66:67], 2
	s_add_u32 s68, s70, s68
	s_addc_u32 s69, s71, s69
	s_cmp_gt_u32 s63, 0
	s_cselect_b32 s82, 1, 0
	s_cmp_gt_i32 s41, 0
	s_cselect_b32 s84, s82, 0
	s_cmp_eq_u32 s40, 0
	s_cselect_b32 s86, s84, 0
	s_add_i32 s64, s77, s51
	v_add_u32_e32 v10, s64, v183
	v_add_u32_e32 v11, s64, v184
	v_add_u32_e32 v12, s64, v185
	v_add_u32_e32 v13, s64, v186
	s_add_i32 s65, s76, s51
	v_add_u32_e32 v14, s65, v174
	s_lshl_b32 s66, s50, 2
	s_add_i32 s66, s66, s76
	v_lshl_add_u32 v0, v144, 2, s66
	v_add_u32_e32 v0, 0x10000, v0
	s_waitcnt lgkmcnt(6)
	v_mfma_f32_32x32x16_bf16 v[64:79], v[2:5], v[196:199], v[64:79]
	ds_read_b64_tr_b16 v[220:221], v11 offset:32768
	ds_read_b64_tr_b16 v[222:223], v11 offset:34816
	ds_read_b128 v[96:99], v0
	s_waitcnt lgkmcnt(7)
	v_mfma_f32_32x32x16_bf16 v[64:79], v[6:9], v[204:207], v[64:79]
	ds_read_b64_tr_b16 v[224:225], v11 offset:36864
	ds_read_b64_tr_b16 v[226:227], v11 offset:38912
	s_cmp_eq_u32 s84, 0
	s_cbranch_scc1 .Lfx_dm1_pq
	s_add_i32 s33, s73, s77
	s_mov_b32 m0, s33
	s_nop 0
	global_load_lds_dwordx4 v163, s[28:29]
.Lfx_dm1_pq:
	ds_read_b128 v[100:103], v0 offset:32
	s_waitcnt lgkmcnt(8)
	v_mfma_f32_32x32x16_bf16 v[64:79], v[212:215], v[200:203], v[64:79]
	ds_read_b64_tr_b16 v[228:229], v11 offset:40960
	ds_read_b64_tr_b16 v[230:231], v11 offset:43008
	ds_read_b128 v[80:83], v0 offset:128
	s_waitcnt lgkmcnt(9)
	v_mfma_f32_32x32x16_bf16 v[64:79], v[216:219], v[208:211], v[64:79]
	ds_read_b64_tr_b16 v[232:233], v11 offset:45056
	ds_read_b64_tr_b16 v[234:235], v11 offset:47104
	ds_read_b128 v[84:87], v0 offset:160
	s_waitcnt lgkmcnt(10)
	v_mfma_f32_32x32x16_bf16 v[48:63], v[220:223], v[196:199], v[48:63]
	ds_read_b64_tr_b16 v[2:3], v12 offset:32768
	ds_read_b64_tr_b16 v[4:5], v12 offset:34816
	s_cmp_eq_u32 s84, 0
	s_cbranch_scc1 .Lfx_dm2_pq
	s_add_i32 m0, s33, 0x400
	s_nop 0
	global_load_lds_dwordx4 v189, s[28:29]
.Lfx_dm2_pq:
	ds_read_b128 v[104:107], v0 offset:64
	s_waitcnt lgkmcnt(10)
	v_mfma_f32_32x32x16_bf16 v[48:63], v[224:227], v[204:207], v[48:63]
	ds_read_b64_tr_b16 v[6:7], v12 offset:36864
	ds_read_b64_tr_b16 v[8:9], v12 offset:38912
	ds_read_b128 v[108:111], v0 offset:96
	s_waitcnt lgkmcnt(10)
	v_mfma_f32_32x32x16_bf16 v[48:63], v[228:231], v[200:203], v[48:63]
	ds_read_b64_tr_b16 v[212:213], v12 offset:40960
	ds_read_b64_tr_b16 v[214:215], v12 offset:43008
	ds_read_b128 v[88:91], v0 offset:192
	s_waitcnt lgkmcnt(10)
	v_mfma_f32_32x32x16_bf16 v[48:63], v[232:235], v[208:211], v[48:63]
	ds_read_b64_tr_b16 v[216:217], v12 offset:45056
	ds_read_b64_tr_b16 v[218:219], v12 offset:47104
	s_cmp_eq_u32 s84, 0
	s_cbranch_scc1 .Lfx_dm3_pq
	s_add_i32 m0, s33, 0x800
	s_nop 0
	global_load_lds_dwordx4 v190, s[28:29]
.Lfx_dm3_pq:
	ds_read_b128 v[92:95], v0 offset:224
	s_waitcnt lgkmcnt(10)
	v_mfma_f32_32x32x16_bf16 v[32:47], v[2:5], v[196:199], v[32:47]
	ds_read_b64_tr_b16 v[220:221], v13 offset:32768
	ds_read_b64_tr_b16 v[222:223], v13 offset:34816
	s_waitcnt lgkmcnt(9)
	v_mfma_f32_32x32x16_bf16 v[32:47], v[6:9], v[204:207], v[32:47]
	ds_read_b64_tr_b16 v[224:225], v13 offset:36864
	ds_read_b64_tr_b16 v[226:227], v13 offset:38912
	s_waitcnt lgkmcnt(8)
	v_mfma_f32_32x32x16_bf16 v[32:47], v[212:215], v[200:203], v[32:47]
	ds_read_b64_tr_b16 v[228:229], v13 offset:40960
	ds_read_b64_tr_b16 v[230:231], v13 offset:43008
	s_cmp_eq_u32 s84, 0
	s_cbranch_scc1 .Lfx_dm4_pq
	s_add_i32 m0, s33, 0xc00
	s_nop 0
	global_load_lds_dwordx4 v191, s[28:29]
.Lfx_dm4_pq:
	s_waitcnt lgkmcnt(7)
	v_mfma_f32_32x32x16_bf16 v[32:47], v[216:219], v[208:211], v[32:47]
	ds_read_b64_tr_b16 v[232:233], v13 offset:45056
	ds_read_b64_tr_b16 v[234:235], v13 offset:47104
	s_waitcnt lgkmcnt(6)
	v_mfma_f32_32x32x16_bf16 v[16:31], v[220:223], v[196:199], v[16:31]
	v_add_u32_e32 v15, v14, v175
	ds_read_b128 v[2:5], v15
	s_waitcnt lgkmcnt(5)
	v_mfma_f32_32x32x16_bf16 v[16:31], v[224:227], v[204:207], v[16:31]
	ds_read_b128 v[6:9], v15 offset:8192
	s_cmp_eq_u32 s86, 0
	s_cbranch_scc1 .Lfx_dm5_pq
	s_add_i32 m0, s72, s77
	s_nop 0
	global_load_lds_dword v172, s[68:69]
.Lfx_dm5_pq:
	s_waitcnt lgkmcnt(4)
	v_mfma_f32_32x32x16_bf16 v[16:31], v[228:231], v[200:203], v[16:31]
	v_add_u32_e32 v15, v14, v176
	ds_read_b128 v[212:215], v15
	s_waitcnt lgkmcnt(3)
	v_mfma_f32_32x32x16_bf16 v[16:31], v[232:235], v[208:211], v[16:31]
	ds_read_b128 v[216:219], v15 offset:8192
	s_waitcnt lgkmcnt(3)
	v_mfma_f32_32x32x16_bf16 v[96:111], v[2:5], v[112:115], v[96:111]
	v_add_u32_e32 v15, v14, v177
	ds_read_b128 v[220:223], v15
	s_waitcnt lgkmcnt(3)
	v_mfma_f32_32x32x16_bf16 v[80:95], v[6:9], v[112:115], v[80:95]
	ds_read_b128 v[224:227], v15 offset:8192
	s_waitcnt lgkmcnt(3)
	v_mfma_f32_32x32x16_bf16 v[96:111], v[212:215], v[116:119], v[96:111]
	v_add_u32_e32 v15, v14, v178
	ds_read_b128 v[228:231], v15
	s_waitcnt lgkmcnt(3)
	v_mfma_f32_32x32x16_bf16 v[80:95], v[216:219], v[116:119], v[80:95]
	ds_read_b128 v[232:235], v15 offset:8192
	s_waitcnt lgkmcnt(3)
	v_mfma_f32_32x32x16_bf16 v[96:111], v[220:223], v[120:123], v[96:111]
	v_add_u32_e32 v15, v14, v179
	ds_read_b128 v[2:5], v15
	s_waitcnt lgkmcnt(3)
	v_mfma_f32_32x32x16_bf16 v[80:95], v[224:227], v[120:123], v[80:95]
	ds_read_b128 v[6:9], v15 offset:8192
	s_waitcnt lgkmcnt(3)
	v_mfma_f32_32x32x16_bf16 v[96:111], v[228:231], v[124:127], v[96:111]
	v_add_u32_e32 v15, v14, v180
	ds_read_b128 v[212:215], v15
	s_waitcnt lgkmcnt(3)
	v_mfma_f32_32x32x16_bf16 v[80:95], v[232:235], v[124:127], v[80:95]
	ds_read_b128 v[216:219], v15 offset:8192
	s_waitcnt lgkmcnt(3)
	v_mfma_f32_32x32x16_bf16 v[96:111], v[2:5], v[128:131], v[96:111]
	v_add_u32_e32 v15, v14, v181
	ds_read_b128 v[220:223], v15
	s_waitcnt lgkmcnt(3)
	v_mfma_f32_32x32x16_bf16 v[80:95], v[6:9], v[128:131], v[80:95]
	ds_read_b128 v[224:227], v15 offset:8192
	s_waitcnt lgkmcnt(3)
	v_mfma_f32_32x32x16_bf16 v[96:111], v[212:215], v[132:135], v[96:111]
	v_add_u32_e32 v15, v14, v182
	ds_read_b128 v[228:231], v15
	s_waitcnt lgkmcnt(3)
	v_mfma_f32_32x32x16_bf16 v[80:95], v[216:219], v[132:135], v[80:95]
	ds_read_b128 v[232:235], v15 offset:8192
	s_waitcnt lgkmcnt(3)
	v_mfma_f32_32x32x16_bf16 v[96:111], v[220:223], v[136:139], v[96:111]
	s_waitcnt lgkmcnt(2)
	v_mfma_f32_32x32x16_bf16 v[80:95], v[224:227], v[136:139], v[80:95]
	s_waitcnt lgkmcnt(1)
	v_mfma_f32_32x32x16_bf16 v[96:111], v[228:231], v[140:143], v[96:111]
	s_waitcnt lgkmcnt(0)
	v_mfma_f32_32x32x16_bf16 v[80:95], v[232:235], v[140:143], v[80:95]
	s_cmp_eq_u32 s84, 0
	s_cbranch_scc1 .Lfx_hw0_pq
	s_waitcnt vmcnt(4)
	s_branch .Lfx_hw1_pq

.Lfx_hw1_pq:
	s_nop 7
	s_branch .Lfx_h1_done
.Lfx_h1_qonly:
	s_lshl_b32 s64, s41, 7
	s_mov_b32 s66, s64
	s_ashr_i32 s67, s64, 31
	s_lshl_b64 s[30:31], s[66:67], 8
	s_add_u32 s30, s23, s30
	s_addc_u32 s31, s24, s31
	s_add_i32 s66, s64, 0xffffff80
	s_ashr_i32 s67, s66, 31
	s_lshl_b64 s[28:29], s[66:67], 8
	s_add_u32 s28, s27, s28
	s_addc_u32 s29, s38, s29
	s_lshl_b64 s[68:69], s[66:67], 2
	s_add_u32 s68, s70, s68
	s_addc_u32 s69, s71, s69
	s_cmp_gt_u32 s63, 0
	s_cselect_b32 s82, 1, 0
	s_cmp_gt_i32 s41, 0
	s_cselect_b32 s84, s82, 0
	s_cmp_eq_u32 s40, 0
	s_cselect_b32 s86, s84, 0
	s_add_i32 s65, s76, s51
	v_add_u32_e32 v14, s65, v174
	s_lshl_b32 s66, s50, 2
	s_add_i32 s66, s66, s76
	v_lshl_add_u32 v0, v144, 2, s66
	v_add_u32_e32 v0, 0x10000, v0
	ds_read_b128 v[96:99], v0
	ds_read_b128 v[100:103], v0 offset:32
	ds_read_b128 v[80:83], v0 offset:128
	ds_read_b128 v[84:87], v0 offset:160
	ds_read_b128 v[104:107], v0 offset:64
	ds_read_b128 v[108:111], v0 offset:96
	ds_read_b128 v[88:91], v0 offset:192
	ds_read_b128 v[92:95], v0 offset:224
	v_add_u32_e32 v15, v14, v175
	ds_read_b128 v[2:5], v15
	ds_read_b128 v[6:9], v15 offset:8192
	v_add_u32_e32 v15, v14, v176
	ds_read_b128 v[212:215], v15
	ds_read_b128 v[216:219], v15 offset:8192
	s_waitcnt lgkmcnt(3)
	v_mfma_f32_32x32x16_bf16 v[96:111], v[2:5], v[112:115], v[96:111]
	v_add_u32_e32 v15, v14, v177
	ds_read_b128 v[220:223], v15
	s_waitcnt lgkmcnt(3)
	v_mfma_f32_32x32x16_bf16 v[80:95], v[6:9], v[112:115], v[80:95]
	ds_read_b128 v[224:227], v15 offset:8192
	s_cmp_eq_u32 s84, 0
	s_cbranch_scc1 .Lfx_dm6_q
	s_add_i32 s33, s73, s77
	s_mov_b32 m0, s33
	s_nop 0
	global_load_lds_dwordx4 v163, s[28:29]
.Lfx_dm6_q:
	s_waitcnt lgkmcnt(3)
	v_mfma_f32_32x32x16_bf16 v[96:111], v[212:215], v[116:119], v[96:111]
	v_add_u32_e32 v15, v14, v178
	ds_read_b128 v[228:231], v15
	s_waitcnt lgkmcnt(3)
	v_mfma_f32_32x32x16_bf16 v[80:95], v[216:219], v[116:119], v[80:95]
	ds_read_b128 v[232:235], v15 offset:8192
	s_waitcnt lgkmcnt(3)
	v_mfma_f32_32x32x16_bf16 v[96:111], v[220:223], v[120:123], v[96:111]
	v_add_u32_e32 v15, v14, v179
	ds_read_b128 v[2:5], v15
	s_cmp_eq_u32 s84, 0
	s_cbranch_scc1 .Lfx_dm7_q
	s_add_i32 m0, s33, 0x400
	s_nop 0
	global_load_lds_dwordx4 v189, s[28:29]
.Lfx_dm7_q:
	s_waitcnt lgkmcnt(3)
	v_mfma_f32_32x32x16_bf16 v[80:95], v[224:227], v[120:123], v[80:95]
	ds_read_b128 v[6:9], v15 offset:8192
	s_waitcnt lgkmcnt(3)
	v_mfma_f32_32x32x16_bf16 v[96:111], v[228:231], v[124:127], v[96:111]
	v_add_u32_e32 v15, v14, v180
	ds_read_b128 v[212:215], v15
	s_waitcnt lgkmcnt(3)
	v_mfma_f32_32x32x16_bf16 v[80:95], v[232:235], v[124:127], v[80:95]
	ds_read_b128 v[216:219], v15 offset:8192
	s_cmp_eq_u32 s84, 0
	s_cbranch_scc1 .Lfx_dm8_q
	s_add_i32 m0, s33, 0x800
	s_nop 0
	global_load_lds_dwordx4 v190, s[28:29]
.Lfx_dm8_q:
	s_waitcnt lgkmcnt(3)
	v_mfma_f32_32x32x16_bf16 v[96:111], v[2:5], v[128:131], v[96:111]
	v_add_u32_e32 v15, v14, v181
	ds_read_b128 v[220:223], v15
	s_waitcnt lgkmcnt(3)
	v_mfma_f32_32x32x16_bf16 v[80:95], v[6:9], v[128:131], v[80:95]
	ds_read_b128 v[224:227], v15 offset:8192
	s_waitcnt lgkmcnt(3)
	v_mfma_f32_32x32x16_bf16 v[96:111], v[212:215], v[132:135], v[96:111]
	v_add_u32_e32 v15, v14, v182
	ds_read_b128 v[228:231], v15
	s_cmp_eq_u32 s84, 0
	s_cbranch_scc1 .Lfx_dm9_q
	s_add_i32 m0, s33, 0xc00
	s_nop 0
	global_load_lds_dwordx4 v191, s[28:29]
.Lfx_dm9_q:
	s_waitcnt lgkmcnt(3)
	v_mfma_f32_32x32x16_bf16 v[80:95], v[216:219], v[132:135], v[80:95]
	ds_read_b128 v[232:235], v15 offset:8192
	s_waitcnt lgkmcnt(3)
	v_mfma_f32_32x32x16_bf16 v[96:111], v[220:223], v[136:139], v[96:111]
	s_waitcnt lgkmcnt(2)
	v_mfma_f32_32x32x16_bf16 v[80:95], v[224:227], v[136:139], v[80:95]
	s_cmp_eq_u32 s86, 0
	s_cbranch_scc1 .Lfx_dm10_q
	s_add_i32 m0, s72, s77
	s_nop 0
	global_load_lds_dword v172, s[68:69]
.Lfx_dm10_q:
	s_waitcnt lgkmcnt(1)
	v_mfma_f32_32x32x16_bf16 v[96:111], v[228:231], v[140:143], v[96:111]
	s_waitcnt lgkmcnt(0)
	v_mfma_f32_32x32x16_bf16 v[80:95], v[232:235], v[140:143], v[80:95]
	s_cmp_eq_u32 s84, 0
	s_cbranch_scc1 .Lfx_hw0_q
	s_waitcnt vmcnt(4)
	s_branch .Lfx_hw1_q
.Lfx_hw0_q:
	s_waitcnt vmcnt(0)
.Lfx_hw1_q:
	s_add_i32 s29, s62, 0xc0000001
	s_cmp_gt_u32 s29, 0xc000005d
	s_cbranch_scc1 .Lfx_nomask_q
	s_nop 11
	v_add_u32_e32 v0, s62, v147
	v_subrev_u32_e32 v2, 30, v0
	v_cmp_gt_u32_e32 vcc, 2.0, v2
	v_add_u32_e32 v2, 0xbfffffc2, v0
	s_nop 3
	v_cndmask_b32_e32 v96, v187, v96, vcc
	v_cmp_lt_u32_e32 vcc, s17, v2
	v_subrev_u32_e32 v2, 31, v0
	s_nop 0
	v_cndmask_b32_e32 v80, v187, v80, vcc
	v_cmp_gt_u32_e32 vcc, 2.0, v2
	v_add_u32_e32 v2, 0xbfffffc1, v0
	s_nop 0
	v_cndmask_b32_e32 v97, v187, v97, vcc
	v_cmp_lt_u32_e32 vcc, s17, v2
	v_subrev_u32_e32 v2, 32, v0
	s_nop 0
	v_cndmask_b32_e32 v81, v187, v81, vcc
	v_cmp_gt_u32_e32 vcc, 2.0, v2
	v_add_u32_e32 v2, 0xbfffffc0, v0
	s_nop 0
	v_cndmask_b32_e32 v98, v187, v98, vcc
	v_cmp_lt_u32_e32 vcc, s17, v2
	v_subrev_u32_e32 v2, 33, v0
	s_nop 0
	v_cndmask_b32_e32 v82, v187, v82, vcc
	v_cmp_gt_u32_e32 vcc, 2.0, v2
	v_add_u32_e32 v2, 0xbfffffbf, v0
	s_nop 0
	v_cndmask_b32_e32 v99, v187, v99, vcc
	v_cmp_lt_u32_e32 vcc, s17, v2
	v_subrev_u32_e32 v2, 38, v0
	s_nop 0
	v_cndmask_b32_e32 v83, v187, v83, vcc
	v_cmp_gt_u32_e32 vcc, 2.0, v2
	v_add_u32_e32 v2, 0xbfffffba, v0
	s_nop 0
	v_cndmask_b32_e32 v100, v187, v100, vcc
	v_cmp_lt_u32_e32 vcc, s17, v2
	v_subrev_u32_e32 v2, 39, v0
	s_nop 0
	v_cndmask_b32_e32 v84, v187, v84, vcc
	v_cmp_gt_u32_e32 vcc, 2.0, v2
	v_add_u32_e32 v2, 0xbfffffb9, v0
	s_nop 0
	v_cndmask_b32_e32 v101, v187, v101, vcc
	v_cmp_lt_u32_e32 vcc, s17, v2
	v_subrev_u32_e32 v2, 40, v0
	s_nop 0
	v_cndmask_b32_e32 v85, v187, v85, vcc
	v_cmp_gt_u32_e32 vcc, 2.0, v2
	v_add_u32_e32 v2, 0xbfffffb8, v0
	s_nop 0
	v_cndmask_b32_e32 v102, v187, v102, vcc
	v_cmp_lt_u32_e32 vcc, s17, v2
	v_subrev_u32_e32 v2, 41, v0
	s_nop 0
	v_cndmask_b32_e32 v86, v187, v86, vcc
	v_cmp_gt_u32_e32 vcc, 2.0, v2
	v_add_u32_e32 v2, 0xbfffffb7, v0
	s_nop 0
	v_cndmask_b32_e32 v103, v187, v103, vcc
	v_cmp_lt_u32_e32 vcc, s17, v2
	v_subrev_u32_e32 v2, 46, v0
	s_nop 0
	v_cndmask_b32_e32 v87, v187, v87, vcc
	v_cmp_gt_u32_e32 vcc, 2.0, v2
	v_add_u32_e32 v2, 0xbfffffb2, v0
	s_nop 0
	v_cndmask_b32_e32 v104, v187, v104, vcc
	v_cmp_lt_u32_e32 vcc, s17, v2
	v_subrev_u32_e32 v2, 47, v0
	s_nop 0
	v_cndmask_b32_e32 v88, v187, v88, vcc
	v_cmp_gt_u32_e32 vcc, 2.0, v2
	v_add_u32_e32 v2, 0xbfffffb1, v0
	s_nop 0
	v_cndmask_b32_e32 v105, v187, v105, vcc
	v_cmp_lt_u32_e32 vcc, s17, v2
	v_subrev_u32_e32 v2, 48, v0
	s_nop 0
	v_cndmask_b32_e32 v89, v187, v89, vcc
	v_cmp_gt_u32_e32 vcc, 2.0, v2
	v_add_u32_e32 v2, 0xbfffffb0, v0
	s_nop 0
	v_cndmask_b32_e32 v106, v187, v106, vcc
	v_cmp_lt_u32_e32 vcc, s17, v2
	v_subrev_u32_e32 v2, 49, v0
	s_nop 0
	v_cndmask_b32_e32 v90, v187, v90, vcc
	v_cmp_gt_u32_e32 vcc, 2.0, v2
	v_add_u32_e32 v2, 0xbfffffaf, v0
	s_nop 0
	v_cndmask_b32_e32 v107, v187, v107, vcc
	v_cmp_lt_u32_e32 vcc, s17, v2
	v_subrev_u32_e32 v2, 54, v0
	s_nop 0
	v_cndmask_b32_e32 v91, v187, v91, vcc
	v_cmp_gt_u32_e32 vcc, 2.0, v2
	v_add_u32_e32 v2, 0xbfffffaa, v0
	s_nop 0
	v_cndmask_b32_e32 v108, v187, v108, vcc
	v_cmp_lt_u32_e32 vcc, s17, v2
	v_subrev_u32_e32 v2, 55, v0
	s_nop 0
	v_cndmask_b32_e32 v92, v187, v92, vcc
	v_cmp_gt_u32_e32 vcc, 2.0, v2
	v_add_u32_e32 v2, 0xbfffffa9, v0
	s_nop 0
	v_cndmask_b32_e32 v109, v187, v109, vcc
	v_cmp_lt_u32_e32 vcc, s17, v2
	v_subrev_u32_e32 v2, 56, v0
	s_nop 0
	v_cndmask_b32_e32 v93, v187, v93, vcc
	v_cmp_gt_u32_e32 vcc, 2.0, v2
	v_add_u32_e32 v2, 0xbfffffa8, v0
	s_nop 0
	v_cndmask_b32_e32 v110, v187, v110, vcc
	v_cmp_lt_u32_e32 vcc, s17, v2
	v_subrev_u32_e32 v2, 57, v0
	v_add_u32_e32 v0, 0xbfffffa7, v0
	v_cndmask_b32_e32 v94, v187, v94, vcc
	v_cmp_gt_u32_e32 vcc, 2.0, v2
	s_nop 1
	v_cndmask_b32_e32 v111, v187, v111, vcc
	v_cmp_lt_u32_e32 vcc, s17, v0
	s_nop 1
	v_cndmask_b32_e32 v95, v187, v95, vcc

.Lfx_h1_done:
	s_barrier
	s_andn2_b64 vcc, exec, s[78:79]
	s_cbranch_vccnz .Lfx_h2_invis
	s_cmp_lt_i32 s41, 1
	s_cbranch_scc1 .Lfx_nv_v
	s_lshl_b32 s64, s41, 7
	s_add_i32 s66, s64, 0xffffff80
	s_ashr_i32 s67, s66, 31
	s_lshl_b64 s[30:31], s[66:67], 8
	s_add_u32 s30, s23, s30
	s_addc_u32 s31, s24, s31
	s_add_i32 m0, s74, s77
	s_nop 0
	global_load_lds_dwordx4 v188, s[30:31]
.Lfx_nv_v:
	s_nop 3
	v_max3_f32 v0, v96, v97, v80
	v_max3_f32 v2, v98, v99, v81
	v_max3_f32 v0, v0, v82, v83
	v_max3_f32 v2, v2, v102, v103
	v_max3_f32 v0, v0, v100, v101
	v_max3_f32 v2, v2, v86, v87
	v_max3_f32 v0, v0, v84, v85
	v_max3_f32 v2, v2, v106, v107
	v_max3_f32 v0, v0, v104, v105
	v_max3_f32 v2, v2, v90, v91
	v_max3_f32 v0, v0, v88, v89
	v_max3_f32 v2, v2, v110, v111
	v_max3_f32 v0, v0, v108, v109
	v_max3_f32 v2, v2, v94, v95
	v_max3_f32 v0, v0, v92, v93
	v_max_f32_e32 v2, v2, v2
	v_max_f32_e32 v0, v0, v0
	v_max_f32_e32 v0, v0, v2
	v_mov_b32_e32 v2, v0
	s_nop 1
	v_permlane32_swap_b32_e32 v0, v2
	v_max_f32_e32 v2, v2, v2
	v_max_f32_e32 v0, v0, v0
	v_max_f32_e32 v0, v0, v2
	v_add_f32_e32 v2, 0x41000000, v192
	v_cmp_gt_f32_e32 vcc, v0, v2
	s_cbranch_vccz .Lfx_sm_exp_v
	v_max_f32_e32 v0, v0, v0
	v_max_f32_e32 v2, v192, v192
	v_max_f32_e32 v2, v2, v0
	v_sub_f32_e32 v0, v192, v2
	v_exp_f32_e32 v0, v0
	v_mov_b32_e32 v192, v2
	v_mul_f32_e32 v162, v162, v0
	v_pk_mul_f32 v[78:79], v[78:79], v[0:1] op_sel_hi:[1,0]
	v_pk_mul_f32 v[76:77], v[76:77], v[0:1] op_sel_hi:[1,0]
	v_pk_mul_f32 v[74:75], v[74:75], v[0:1] op_sel_hi:[1,0]
	v_pk_mul_f32 v[72:73], v[72:73], v[0:1] op_sel_hi:[1,0]
	v_pk_mul_f32 v[70:71], v[70:71], v[0:1] op_sel_hi:[1,0]
	v_pk_mul_f32 v[68:69], v[68:69], v[0:1] op_sel_hi:[1,0]
	v_pk_mul_f32 v[66:67], v[66:67], v[0:1] op_sel_hi:[1,0]
	v_pk_mul_f32 v[64:65], v[64:65], v[0:1] op_sel_hi:[1,0]
	v_pk_mul_f32 v[62:63], v[62:63], v[0:1] op_sel_hi:[1,0]
	v_pk_mul_f32 v[60:61], v[60:61], v[0:1] op_sel_hi:[1,0]
	v_pk_mul_f32 v[58:59], v[58:59], v[0:1] op_sel_hi:[1,0]
	v_pk_mul_f32 v[56:57], v[56:57], v[0:1] op_sel_hi:[1,0]
	v_pk_mul_f32 v[54:55], v[54:55], v[0:1] op_sel_hi:[1,0]
	v_pk_mul_f32 v[52:53], v[52:53], v[0:1] op_sel_hi:[1,0]
	v_pk_mul_f32 v[50:51], v[50:51], v[0:1] op_sel_hi:[1,0]
	v_pk_mul_f32 v[48:49], v[48:49], v[0:1] op_sel_hi:[1,0]
	v_pk_mul_f32 v[46:47], v[46:47], v[0:1] op_sel_hi:[1,0]
	v_pk_mul_f32 v[44:45], v[44:45], v[0:1] op_sel_hi:[1,0]
	v_pk_mul_f32 v[42:43], v[42:43], v[0:1] op_sel_hi:[1,0]
	v_pk_mul_f32 v[40:41], v[40:41], v[0:1] op_sel_hi:[1,0]
	v_pk_mul_f32 v[38:39], v[38:39], v[0:1] op_sel_hi:[1,0]
	v_pk_mul_f32 v[36:37], v[36:37], v[0:1] op_sel_hi:[1,0]
	v_pk_mul_f32 v[34:35], v[34:35], v[0:1] op_sel_hi:[1,0]
	v_pk_mul_f32 v[32:33], v[32:33], v[0:1] op_sel_hi:[1,0]
	v_pk_mul_f32 v[30:31], v[30:31], v[0:1] op_sel_hi:[1,0]
	v_pk_mul_f32 v[28:29], v[28:29], v[0:1] op_sel_hi:[1,0]
	v_pk_mul_f32 v[26:27], v[26:27], v[0:1] op_sel_hi:[1,0]
	v_pk_mul_f32 v[24:25], v[24:25], v[0:1] op_sel_hi:[1,0]
	v_pk_mul_f32 v[22:23], v[22:23], v[0:1] op_sel_hi:[1,0]
	v_pk_mul_f32 v[20:21], v[20:21], v[0:1] op_sel_hi:[1,0]
	v_pk_mul_f32 v[18:19], v[18:19], v[0:1] op_sel_hi:[1,0]
	v_pk_mul_f32 v[16:17], v[16:17], v[0:1] op_sel_hi:[1,0]
.Lfx_sm_exp_v:
	v_sub_f32_e32 v0, v96, v192
	v_exp_f32_e32 v193, v0
	v_sub_f32_e32 v0, v80, v192
	v_exp_f32_e32 v194, v0
	v_sub_f32_e32 v0, v97, v192
	s_cmp_lt_i32 s41, 1
	s_cbranch_scc1 .Lfx_nv0_v
	global_load_lds_dwordx4 v188, s[30:31] offset:1024
.Lfx_nv0_v:
	v_exp_f32_e32 v2, v0
	v_sub_f32_e32 v0, v81, v192
	v_exp_f32_e32 v0, v0
	v_add_f32_e32 v3, v193, v194
	v_add_f32_e32 v4, v2, v0
	v_add_f32_e32 v5, v3, v1
	s_nop 0
	v_add_f32_e32 v8, v4, v4
	v_add_f32_e32 v9, v4, v5
	v_sub_f32_e32 v3, v98, v192
	v_sub_f32_e32 v4, v82, v192
	v_exp_f32_e32 v3, v3
	v_exp_f32_e32 v98, v4
	v_sub_f32_e32 v4, v99, v192
	v_sub_f32_e32 v5, v83, v192
	v_exp_f32_e32 v4, v4
	v_exp_f32_e32 v8, v5
	v_add_f32_e32 v5, v3, v98
	v_cvt_pk_bf16_f32 v196, v193, v2
	v_cvt_pk_bf16_f32 v197, v3, v4
	v_add_f32_e32 v6, v4, v8
	v_add_f32_e32 v7, v5, v9
	v_sub_f32_e32 v5, v100, v192
	v_add_f32_e32 v10, v6, v6
	v_add_f32_e32 v11, v6, v7
	v_sub_f32_e32 v6, v84, v192
	v_exp_f32_e32 v5, v5
	v_exp_f32_e32 v9, v6
	v_sub_f32_e32 v6, v101, v192
	v_sub_f32_e32 v7, v85, v192
	s_cmp_lt_i32 s41, 1
	s_cbranch_scc1 .Lfx_nv1_v
	global_load_lds_dwordx4 v188, s[30:31] offset:2048
.Lfx_nv1_v:
	v_exp_f32_e32 v6, v6
	v_exp_f32_e32 v10, v7
	v_add_f32_e32 v7, v5, v9
	v_cvt_pk_bf16_f32 v198, v5, v6
	v_add_f32_e32 v12, v6, v10
	v_add_f32_e32 v13, v7, v11
	v_sub_f32_e32 v7, v102, v192
	v_add_f32_e32 v13, v12, v13
	v_add_f32_e32 v12, v12, v12
	v_sub_f32_e32 v11, v86, v192
	v_sub_f32_e32 v12, v103, v192
	v_exp_f32_e32 v7, v7
	v_exp_f32_e32 v11, v11
	v_exp_f32_e32 v14, v12
	v_sub_f32_e32 v12, v87, v192
	v_exp_f32_e32 v12, v12
	v_add_f32_e32 v15, v7, v11
	v_cvt_pk_bf16_f32 v199, v7, v14
	v_cvt_pk_bf16_f32 v200, v194, v0
	v_add_f32_e32 v80, v14, v12
	v_add_f32_e32 v81, v15, v13
	v_sub_f32_e32 v13, v104, v192
	v_add_f32_e32 v81, v80, v81
	v_add_f32_e32 v80, v80, v80
	v_sub_f32_e32 v15, v88, v192
	v_sub_f32_e32 v80, v105, v192
	v_exp_f32_e32 v13, v13
	v_exp_f32_e32 v15, v15
	v_exp_f32_e32 v82, v80
	v_sub_f32_e32 v80, v89, v192
	s_cmp_lt_i32 s41, 1
	s_cbranch_scc1 .Lfx_nv2_v
	global_load_lds_dwordx4 v188, s[30:31] offset:3072
.Lfx_nv2_v:
	v_exp_f32_e32 v80, v80
	v_add_f32_e32 v83, v13, v15
	v_cvt_pk_bf16_f32 v201, v98, v8
	v_cvt_pk_bf16_f32 v202, v9, v10
	v_add_f32_e32 v84, v82, v80
	v_add_f32_e32 v85, v83, v81
	v_sub_f32_e32 v81, v106, v192
	v_add_f32_e32 v85, v84, v85
	v_add_f32_e32 v84, v84, v84
	v_sub_f32_e32 v83, v90, v192
	v_sub_f32_e32 v84, v107, v192
	v_exp_f32_e32 v81, v81
	v_exp_f32_e32 v83, v83
	v_exp_f32_e32 v86, v84
	v_sub_f32_e32 v84, v91, v192
	v_exp_f32_e32 v84, v84
	v_add_f32_e32 v87, v81, v83
	v_cvt_pk_bf16_f32 v203, v11, v12
	v_cvt_pk_bf16_f32 v204, v13, v82
	v_add_f32_e32 v88, v86, v84
	v_add_f32_e32 v89, v87, v85
	v_sub_f32_e32 v85, v108, v192
	v_add_f32_e32 v89, v88, v89
	v_add_f32_e32 v88, v88, v88
	v_sub_f32_e32 v87, v92, v192
	v_sub_f32_e32 v88, v109, v192
	v_exp_f32_e32 v85, v85
	v_exp_f32_e32 v87, v87
	v_exp_f32_e32 v90, v88
	v_sub_f32_e32 v88, v93, v192
	v_exp_f32_e32 v88, v88
	v_add_f32_e32 v91, v85, v87
	v_cvt_pk_bf16_f32 v205, v81, v86
	v_cvt_pk_bf16_f32 v206, v85, v90
	v_add_f32_e32 v92, v90, v88
	v_add_f32_e32 v93, v91, v89
	v_sub_f32_e32 v89, v110, v192
	v_add_f32_e32 v93, v92, v93
	v_add_f32_e32 v92, v92, v92
	v_sub_f32_e32 v91, v94, v192
	v_sub_f32_e32 v92, v111, v192
	v_exp_f32_e32 v89, v89
	v_exp_f32_e32 v91, v91
	v_exp_f32_e32 v94, v92
	v_sub_f32_e32 v92, v95, v192
	v_exp_f32_e32 v92, v92
	v_add_f32_e32 v95, v89, v91
	v_cvt_pk_bf16_f32 v207, v89, v94
	v_cvt_pk_bf16_f32 v208, v15, v80
	v_add_f32_e32 v96, v94, v92
	v_add_f32_e32 v97, v95, v93
	v_cvt_pk_bf16_f32 v209, v83, v84
	v_add_f32_e32 v93, v96, v97
	v_add_f32_e32 v162, v162, v93
	v_cvt_pk_bf16_f32 v210, v87, v88
	v_cvt_pk_bf16_f32 v211, v91, v92
	s_cmp_lt_i32 s41, 1
	s_cbranch_scc1 .Lfx_w0_v
	s_waitcnt vmcnt(4)
	s_branch .Lfx_w1_v

.Lfx_w1_v:
	s_add_i32 s64, s76, s51
	v_add_u32_e32 v10, s64, v183
	ds_read_b64_tr_b16 v[2:3], v10 offset:32768
	ds_read_b64_tr_b16 v[4:5], v10 offset:34816
	ds_read_b64_tr_b16 v[6:7], v10 offset:36864
	ds_read_b64_tr_b16 v[8:9], v10 offset:38912
	ds_read_b64_tr_b16 v[212:213], v10 offset:40960
	ds_read_b64_tr_b16 v[214:215], v10 offset:43008
	ds_read_b64_tr_b16 v[216:217], v10 offset:45056
	ds_read_b64_tr_b16 v[218:219], v10 offset:47104
	s_branch .Lfx_h2_done
.Lfx_h2_invis:
	s_cmp_lt_i32 s41, 1
	s_cbranch_scc1 .Lfx_nv_i
	s_lshl_b32 s64, s41, 7
	s_add_i32 s66, s64, 0xffffff80
	s_ashr_i32 s67, s66, 31
	s_lshl_b64 s[30:31], s[66:67], 8
	s_add_u32 s30, s23, s30
	s_addc_u32 s31, s24, s31
	s_add_i32 m0, s74, s77
	s_nop 0
	global_load_lds_dwordx4 v188, s[30:31]
.Lfx_nv_i:
	s_cmp_lt_i32 s41, 1
	s_cbranch_scc1 .Lfx_nv0_i
	global_load_lds_dwordx4 v188, s[30:31] offset:1024
.Lfx_nv0_i:
	s_cmp_lt_i32 s41, 1
	s_cbranch_scc1 .Lfx_nv1_i
	global_load_lds_dwordx4 v188, s[30:31] offset:2048
.Lfx_nv1_i:
	s_cmp_lt_i32 s41, 1
	s_cbranch_scc1 .Lfx_nv2_i
	global_load_lds_dwordx4 v188, s[30:31] offset:3072
.Lfx_nv2_i:
	s_cmp_lt_i32 s41, 1
	s_cbranch_scc1 .Lfx_w0_i
	s_waitcnt vmcnt(4)
	s_branch .Lfx_w1_i

.Lfx_w1_i:
.Lfx_h2_done:
	s_barrier
	s_add_i32 s63, s63, 1
	s_add_i32 s41, s41, -1
	s_addk_i32 s62, 0x80
	s_xor_b32 s76, s76, 0x10200
	s_xor_b32 s77, s77, 0x10200
	s_mov_b64 s[80:81], s[78:79]
	s_cmp_eq_u32 s41, -1
	s_cbranch_scc0 .Lfx_body
	s_andn2_b64 vcc, exec, s[80:81]
	s_cbranch_vccnz .Lfx_tail_done
	s_add_i32 s64, s77, s51
	v_add_u32_e32 v10, s64, v183
	v_add_u32_e32 v11, s64, v184
	v_add_u32_e32 v12, s64, v185
	v_add_u32_e32 v13, s64, v186
	s_waitcnt lgkmcnt(6)
	v_mfma_f32_32x32x16_bf16 v[64:79], v[2:5], v[196:199], v[64:79]
	ds_read_b64_tr_b16 v[220:221], v11 offset:32768
	ds_read_b64_tr_b16 v[222:223], v11 offset:34816
	s_waitcnt lgkmcnt(6)
	v_mfma_f32_32x32x16_bf16 v[64:79], v[6:9], v[204:207], v[64:79]
	ds_read_b64_tr_b16 v[224:225], v11 offset:36864
	ds_read_b64_tr_b16 v[226:227], v11 offset:38912
	s_waitcnt lgkmcnt(6)
	v_mfma_f32_32x32x16_bf16 v[64:79], v[212:215], v[200:203], v[64:79]
	ds_read_b64_tr_b16 v[228:229], v11 offset:40960
	ds_read_b64_tr_b16 v[230:231], v11 offset:43008
	s_waitcnt lgkmcnt(6)
	v_mfma_f32_32x32x16_bf16 v[64:79], v[216:219], v[208:211], v[64:79]
	ds_read_b64_tr_b16 v[232:233], v11 offset:45056
	ds_read_b64_tr_b16 v[234:235], v11 offset:47104
	s_waitcnt lgkmcnt(6)
	v_mfma_f32_32x32x16_bf16 v[48:63], v[220:223], v[196:199], v[48:63]
	ds_read_b64_tr_b16 v[2:3], v12 offset:32768
	ds_read_b64_tr_b16 v[4:5], v12 offset:34816
	s_waitcnt lgkmcnt(6)
	v_mfma_f32_32x32x16_bf16 v[48:63], v[224:227], v[204:207], v[48:63]
	ds_read_b64_tr_b16 v[6:7], v12 offset:36864
	ds_read_b64_tr_b16 v[8:9], v12 offset:38912
	s_waitcnt lgkmcnt(6)
	v_mfma_f32_32x32x16_bf16 v[48:63], v[228:231], v[200:203], v[48:63]
	ds_read_b64_tr_b16 v[212:213], v12 offset:40960
	ds_read_b64_tr_b16 v[214:215], v12 offset:43008
	s_waitcnt lgkmcnt(6)
	v_mfma_f32_32x32x16_bf16 v[48:63], v[232:235], v[208:211], v[48:63]
	ds_read_b64_tr_b16 v[216:217], v12 offset:45056
	ds_read_b64_tr_b16 v[218:219], v12 offset:47104
	s_waitcnt lgkmcnt(6)
	v_mfma_f32_32x32x16_bf16 v[32:47], v[2:5], v[196:199], v[32:47]
	ds_read_b64_tr_b16 v[220:221], v13 offset:32768
	ds_read_b64_tr_b16 v[222:223], v13 offset:34816
	s_waitcnt lgkmcnt(6)
	v_mfma_f32_32x32x16_bf16 v[32:47], v[6:9], v[204:207], v[32:47]
	ds_read_b64_tr_b16 v[224:225], v13 offset:36864
	ds_read_b64_tr_b16 v[226:227], v13 offset:38912
	s_waitcnt lgkmcnt(6)
	v_mfma_f32_32x32x16_bf16 v[32:47], v[212:215], v[200:203], v[32:47]
	ds_read_b64_tr_b16 v[228:229], v13 offset:40960
	ds_read_b64_tr_b16 v[230:231], v13 offset:43008
	s_waitcnt lgkmcnt(6)
	v_mfma_f32_32x32x16_bf16 v[32:47], v[216:219], v[208:211], v[32:47]
	ds_read_b64_tr_b16 v[232:233], v13 offset:45056
	ds_read_b64_tr_b16 v[234:235], v13 offset:47104
	s_waitcnt lgkmcnt(6)
	v_mfma_f32_32x32x16_bf16 v[16:31], v[220:223], v[196:199], v[16:31]
	s_waitcnt lgkmcnt(4)
	v_mfma_f32_32x32x16_bf16 v[16:31], v[224:227], v[204:207], v[16:31]
	s_waitcnt lgkmcnt(2)
	v_mfma_f32_32x32x16_bf16 v[16:31], v[228:231], v[200:203], v[16:31]
	s_waitcnt lgkmcnt(0)
	v_mfma_f32_32x32x16_bf16 v[16:31], v[232:235], v[208:211], v[16:31]
	s_waitcnt vmcnt(0)
